# A+Q+P2+S + residual epilogues touch the x lines of later 16-row groups two groups ahead (one-dword loads, L2 prefetch) in 5 EpiResidNorm instances
# baseline (speedup 1.0000x reference)
; #define LAS __attribute__((address_space(3)))
;     __device__ __forceinline__ void operator()(const f32x4 (&acc)[2][2][4][2], const Unit& u, int wr, int wc, int fr, int fq) const {
;         const int s = u.pm >> 5, lane = fq * 16 + fr, rr = lane >> 3, pc = lane & 7;
;         const float* __restrict__ xi = xin + (size_t)u.pm * BM * DM; float* __restrict__ xo = xout + (size_t)u.pm * BM * DM; bf16_t* __restrict__ ho = Hn + (size_t)u.pm * BM * DM;
;         LAS unsigned char* st = lds_epi + (wr * 4 + wc) * 2304;
;         LAS float* sst = (LAS float*)(lds_epi + 18432 + (wr * 4 + wc) * 512);
;         const int colr = u.pn * BM + wc * 64 + 4 * pc;
;         const unsigned eb = (unsigned)((wr * 64 + rr) * DM + colr);
;         f32x4 gv[2], gsn[2];
; #pragma unroll
;         for (int bj = 0; bj < 2; ++bj) { gv[bj] = *(const f32x4*)(gate + (size_t)s * MODW + colr + bj * 32) * (0.5f * GS2);
;             if (!PLAIN) gsn[bj] = *(const f32x4*)(gnext + colr + bj * 32) * (*(const f32x4*)(scnext + (size_t)s * MODW + colr + bj * 32) + 1.0f); else gsn[bj] = gv[bj]; }
;         const unsigned wr_off = (unsigned)(fr * 144 + 16 * fq), rd_off = (unsigned)(rr * 144 + pc * 16);
;         const bool odd = (rr & 1) != 0;
;         f32x4 xb[2][2][2];
;     ...
;         ERN_LOADX(0);
; #pragma unroll
;         for (int g = 0; g < 8; ++g) { const int ai = g >> 2, m = g & 3;
;             if (g + 1 < 8) ERN_LOADX(g + 1);
;             float sq0 = 0.f, sq1 = 0.f; u32x2 hw[2][2];
; #pragma unroll
;             for (int bj = 0; bj < 2; ++bj) {
;                 *(LAS f32x4*)(st + wr_off) = acc[ai][bj][m][0]; *(LAS f32x4*)(st + wr_off + 64) = acc[ai][bj][m][1];
;                 const f32x4 a0 = *(const LAS f32x4*)(st + rd_off), a1 = *(const LAS f32x4*)(st + rd_off + 8 * 144);
;                 { const f32x4 xv = xb[g & 1][bj][0] + gv[bj] * a0; __builtin_nontemporal_store(xv, (f32x4*)((char*)xo + 4u * ERN_EOFF(g, bj, 0)));
;                   sq0 += (xv.x * xv.x + xv.y * xv.y) + (xv.z * xv.z + xv.w * xv.w);
;                   const f32x4 hv = xv * gsn[bj]; hw[bj][0].x = cvt_pk_bf16(hv.x, hv.y); hw[bj][0].y = cvt_pk_bf16(hv.z, hv.w); }
;                 { const f32x4 xv = xb[g & 1][bj][1] + gv[bj] * a1; __builtin_nontemporal_store(xv, (f32x4*)((char*)xo + 4u * ERN_EOFF(g, bj, 1)));
;                   sq1 += (xv.x * xv.x + xv.y * xv.y) + (xv.z * xv.z + xv.w * xv.w);
.LBB0_320:
	s_ashr_i32 s12, s4, 5
	s_ashr_i32 s5, s4, 31
	v_lshl_or_b32 v130, s0, 8, v192
	s_mul_i32 s14, s12, 0x12000
	s_mul_hi_i32 s0, s12, 0x12000
	s_add_u32 s12, s35, s14
	v_ashrrev_i32_e32 v131, 31, v130
	s_addc_u32 s13, s36, s0
	v_lshlrev_b64 v[132:133], 2, v[130:131]
	v_lshl_add_u64 v[134:135], s[12:13], 0, v[132:133]
	s_add_u32 s12, s37, s14
	s_addc_u32 s13, s60, s0
	v_lshl_add_u64 v[136:137], s[46:47], 0, v[132:133]
	v_lshl_add_u64 v[132:133], s[12:13], 0, v[132:133]
	s_lshl_b64 s[54:55], s[4:5], 21
	v_readlane_b32 s12, v253, 2
	v_readlane_b32 s13, v253, 3
	s_add_u32 s58, s12, s54
	v_add_u32_e32 v202, v130, v193
	s_addc_u32 s59, s13, s55
	v_lshlrev_b32_e32 v207, 2, v202
	global_load_dwordx4 v[170:173], v[136:137], off
	global_load_dwordx4 v[166:169], v[134:135], off
	global_load_dwordx4 v[174:177], v[134:135], off offset:128
	global_load_dwordx4 v[186:189], v[132:133], off
	global_load_dwordx4 v[208:211], v[132:133], off offset:128
	global_load_dwordx4 v[212:215], v207, s[58:59]
	v_add_u32_e32 v130, 0x10000, v207
	global_load_dwordx4 v[216:219], v130, s[58:59]
	global_load_dwordx4 v[220:223], v[136:137], off offset:128
	global_load_dwordx4 v[224:227], v207, s[58:59] offset:128
	v_add_u32_e32 v206, 0x10080, v207
	v_add_u32_e32 v130, 0x20000, v207
	global_load_dwordx4 v[228:231], v206, s[58:59]
	v_add_u32_e32 v154, 0x30000, v207
	v_add_u32_e32 v184, 0x20080, v207
	v_add_u32_e32 v182, 0x30080, v207
	global_load_dwordx4 v[142:145], v130, s[58:59]
	global_load_dwordx4 v[138:141], v154, s[58:59]
	global_load_dwordx4 v[134:137], v184, s[58:59]
	s_nop 0
	global_load_dwordx4 v[130:133], v182, s[58:59]
	ds_write_b128 v200, v[126:129]
	ds_write_b128 v200, v[122:125] offset:64
	v_and_b32_e32 v127, 64, v199
	ds_read_b128 v[122:125], v201
	ds_read_b128 v[232:235], v201 offset:1152
	v_xor_b32_e32 v126, 8, v199
	v_add_u32_e32 v183, 64, v127
	v_cmp_lt_i32_e32 vcc, v126, v183
	v_add_u32_e32 v185, 0x4000, v202
	s_add_u32 s56, s90, s54
	v_cndmask_b32_e32 v126, v199, v126, vcc
	v_lshlrev_b32_e32 v203, 2, v126
	v_lshlrev_b32_e32 v236, 2, v185
	s_addc_u32 s57, s91, s55
	s_lshl_b64 s[12:13], s[4:5], 20
	s_add_u32 s54, s93, s12
	v_readlane_b32 s16, v253, 6
	v_readlane_b32 s17, v253, 7
	s_addc_u32 s55, s92, s13
	v_readlane_b32 s14, v253, 4
	v_readlane_b32 s15, v253, 5
	v_readlane_b32 s18, v253, 8
	v_readlane_b32 s19, v253, 9
	v_readlane_b32 s20, v253, 10
	v_readlane_b32 s21, v253, 11
	v_readlane_b32 s22, v253, 12
	v_readlane_b32 s23, v253, 13
	v_readlane_b32 s24, v253, 14
	v_readlane_b32 s25, v253, 15
	v_readlane_b32 s26, v253, 16
	v_readlane_b32 s27, v253, 17
	v_mbcnt_lo_u32_b32 v250, -1, 0
	v_mbcnt_hi_u32_b32 v250, -1, v250
	v_and_b32_e32 v249, 15, v250
	v_lshrrev_b32_e32 v251, 3, v250
	v_sub_u32_e32 v249, v249, v251
	v_lshlrev_b32_e32 v249, 13, v249
	v_bfe_u32 v251, v250, 4, 1
	v_lshl_add_u32 v249, v251, 7, v249
	v_and_b32_e32 v251, 7, v250
	v_lshlrev_b32_e32 v251, 4, v251
	v_sub_u32_e32 v249, v249, v251
	v_add_u32_e32 v249, v249, v207
	v_add_u32_e32 v250, 0x40000, v249
	global_load_dword v251, v250, s[58:59]
	v_add_u32_e32 v250, 0x60000, v249
	global_load_dword v251, v250, s[58:59]
	s_waitcnt vmcnt(2)
	v_pk_mul_f32 v[180:181], v[166:167], 0.5 op_sel_hi:[1,0]
	v_pk_mul_f32 v[178:179], v[168:169], 0.5 op_sel_hi:[1,0]
	v_pk_add_f32 v[126:127], v[188:189], 1.0 op_sel_hi:[1,0]
	v_pk_add_f32 v[128:129], v[186:187], 1.0 op_sel_hi:[1,0]
	v_pk_mul_f32 v[166:167], v[176:177], 0.5 op_sel_hi:[1,0]
	v_pk_mul_f32 v[168:169], v[174:175], 0.5 op_sel_hi:[1,0]
	v_pk_mul_f32 v[174:175], v[172:173], v[126:127]
	v_pk_mul_f32 v[176:177], v[170:171], v[128:129]
	s_waitcnt lgkmcnt(1)
	v_pk_fma_f32 v[126:127], v[180:181], v[122:123], v[212:213]
	s_waitcnt lgkmcnt(0)
	v_pk_fma_f32 v[122:123], v[180:181], v[232:233], v[216:217]
	v_pk_fma_f32 v[128:129], v[178:179], v[124:125], v[214:215]
	v_pk_fma_f32 v[124:125], v[178:179], v[234:235], v[218:219]
	v_pk_mul_f32 v[186:187], v[176:177], v[122:123]
	global_store_dwordx4 v207, v[126:129], s[56:57] nt
	v_pk_mul_f32 v[170:171], v[174:175], v[128:129]
	v_pk_mul_f32 v[172:173], v[176:177], v[126:127]
	v_pk_mul_f32 v[204:205], v[174:175], v[124:125]
	v_cvt_pk_bf16_f32 v188, v172, v173
	v_cvt_pk_bf16_f32 v189, v170, v171
	global_store_dwordx4 v236, v[122:125], s[56:57] nt
	v_cvt_pk_bf16_f32 v186, v186, v187
	v_cvt_pk_bf16_f32 v187, v204, v205
	ds_write_b128 v200, v[118:121]
	ds_write_b128 v200, v[114:117] offset:64
	ds_read_b128 v[114:117], v201
	v_pk_add_f32 v[190:191], v[210:211], 1.0 op_sel_hi:[1,0]
	v_pk_add_f32 v[118:119], v[208:209], 1.0 op_sel_hi:[1,0]
	ds_read_b128 v[208:211], v201 offset:1152
	v_pk_mul_f32 v[170:171], v[222:223], v[190:191]
	v_pk_mul_f32 v[172:173], v[220:221], v[118:119]
	s_waitcnt lgkmcnt(1)
	v_pk_fma_f32 v[120:121], v[166:167], v[116:117], v[226:227]
	v_pk_fma_f32 v[118:119], v[168:169], v[114:115], v[224:225]
	v_pk_mul_f32 v[190:191], v[170:171], v[120:121]
	v_pk_mul_f32 v[204:205], v[172:173], v[118:119]
	global_store_dwordx4 v207, v[118:121], s[56:57] offset:128 nt
	v_cvt_pk_bf16_f32 v204, v204, v205
	v_cvt_pk_bf16_f32 v191, v190, v191
	ds_bpermute_b32 v190, v203, v204
	ds_bpermute_b32 v191, v203, v191
	s_waitcnt lgkmcnt(2)
	v_pk_fma_f32 v[116:117], v[166:167], v[210:211], v[230:231]
	v_pk_fma_f32 v[114:115], v[168:169], v[208:209], v[228:229]
	global_store_dwordx4 v206, v[114:117], s[56:57] nt
	v_pk_mul_f32 v[204:205], v[172:173], v[114:115]
	v_lshlrev_b32_e32 v206, 1, v202
	v_pk_mul_f32 v[208:209], v[170:171], v[116:117]
	v_cvt_pk_bf16_f32 v204, v204, v205
	s_nop 0
	v_cvt_pk_bf16_f32 v205, v208, v209
	s_and_saveexec_b64 s[12:13], s[40:41]
	s_xor_b64 s[16:17], exec, s[12:13]
	s_cbranch_execz .LBB0_322
	v_lshlrev_b32_e32 v206, 1, v202
	v_add_u32_e32 v208, 0xfffff040, v206
	s_waitcnt lgkmcnt(0)
	global_store_dwordx2 v208, v[190:191], s[54:55]

; #define LAS __attribute__((address_space(3)))
; __device__ __forceinline__ unsigned cvt_pk_bf16(float lo, float hi) { unsigned r; asm volatile("v_cvt_pk_bf16_f32 %0, %1, %2" : "=v"(r) : "v"(lo), "v"(hi)); return r; }
; #define ERN_EOFF(q, m) (eb + (unsigned)((((q) & 1) * HALF + (m) * 16) * DM + ERN_COL((q) >> 1)))
; #define ERN_LOADX(q) do { _Pragma("unroll") for (int m = 0; m < 4; ++m) xb[(q) & 1][m] = *(const f32x4*)((const char*)xi + 4u * ERN_EOFF(q, m)); } while (0)
;     __device__ __forceinline__ void operator()(const f32x4 (&acc)[2][2][4][2], const Unit& u, int wr, int wc, int fr, int fq) const {
;     ...
;         for (int g = 0; g < 8; ++g) { const int ai = g >> 2, m = g & 3;
;             if (g + 1 < 8) ERN_LOADX(g + 1);
;             float sq0 = 0.f, sq1 = 0.f; u32x2 hw[2][2];
; #pragma unroll
;             for (int bj = 0; bj < 2; ++bj) {
;                 *(LAS f32x4*)(st + wr_off) = acc[ai][bj][m][0]; *(LAS f32x4*)(st + wr_off + 64) = acc[ai][bj][m][1];
;                 const f32x4 a0 = *(const LAS f32x4*)(st + rd_off), a1 = *(const LAS f32x4*)(st + rd_off + 8 * 144);
;                 { const f32x4 xv = xb[g & 1][bj][0] + gv[bj] * a0; __builtin_nontemporal_store(xv, (f32x4*)((char*)xo + 4u * ERN_EOFF(g, bj, 0)));
;                   sq0 += (xv.x * xv.x + xv.y * xv.y) + (xv.z * xv.z + xv.w * xv.w);
;                   const f32x4 hv = xv * gsn[bj]; hw[bj][0].x = cvt_pk_bf16(hv.x, hv.y); hw[bj][0].y = cvt_pk_bf16(hv.z, hv.w); }
;                 { const f32x4 xv = xb[g & 1][bj][1] + gv[bj] * a1; __builtin_nontemporal_store(xv, (f32x4*)((char*)xo + 4u * ERN_EOFF(g, bj, 1)));
;                   sq1 += (xv.x * xv.x + xv.y * xv.y) + (xv.z * xv.z + xv.w * xv.w);
;                   const f32x4 hv = xv * gsn[bj]; hw[bj][1].x = cvt_pk_bf16(hv.x, hv.y); hw[bj][1].y = cvt_pk_bf16(hv.z, hv.w); }
;             }
;             if (!NOH && !PLAIN) {
; #pragma unroll
;                 for (int rh = 0; rh < 2; ++rh) { u32x2 rv; rv.x = __shfl_xor(hw[1][rh].x, 8); rv.y = __shfl_xor(hw[1][rh].y, 8);
;                     const unsigned e0 = ERN_EOFF(g, 0, rh);
;                     const unsigned ee = odd ? (e0 - DM + 32) : e0, eo2 = odd ? e0 : (e0 + DM + 32);
;                     *(u32x2*)((char*)ho + 2u * ee) = odd ? rv : hw[0][rh];
;                     *(u32x2*)((char*)ho + 2u * eo2) = odd ? hw[0][rh] : rv; }
.LBB0_330:
	s_or_b64 exec, exec, s[16:17]
	v_add_u32_e32 v114, 0x40000, v207
	v_add_u32_e32 v190, 0x50000, v207
	v_add_u32_e32 v188, 0x40080, v207
	global_load_dwordx4 v[122:125], v190, s[58:59]
	global_load_dwordx4 v[118:121], v188, s[58:59]
	v_add_u32_e32 v186, 0x50080, v207
	global_load_dwordx4 v[126:129], v114, s[58:59]
	s_waitcnt lgkmcnt(0)
	global_load_dwordx4 v[114:117], v186, s[58:59]
	v_add_u32_e32 v250, 0x100000, v249
	global_load_dword v251, v250, s[58:59]
	ds_write_b128 v200, v[110:113]
	ds_write_b128 v200, v[106:109] offset:64
	ds_read_b128 v[106:109], v201
	ds_read_b128 v[110:113], v201 offset:1152
	v_mov_b32_e32 v185, v155
	v_mov_b32_e32 v183, v155
	s_waitcnt lgkmcnt(1)
	v_pk_fma_f32 v[108:109], v[178:179], v[108:109], v[144:145]
	v_add_u32_e32 v144, 0x8000, v202
	v_pk_fma_f32 v[106:107], v[180:181], v[106:107], v[142:143]
	v_lshlrev_b32_e32 v142, 2, v144
	global_store_dwordx4 v142, v[106:109], s[56:57] nt
	v_pk_mul_f32 v[142:143], v[176:177], v[106:107]
	s_waitcnt lgkmcnt(0)
	v_pk_fma_f32 v[112:113], v[178:179], v[112:113], v[140:141]
	v_pk_fma_f32 v[110:111], v[180:181], v[110:111], v[138:139]
	v_lshl_add_u64 v[138:139], s[56:57], 0, v[154:155]
	v_pk_mul_f32 v[208:209], v[174:175], v[108:109]
	v_cvt_pk_bf16_f32 v142, v142, v143
	v_pk_mul_f32 v[140:141], v[174:175], v[112:113]
	v_cvt_pk_bf16_f32 v143, v208, v209
	global_store_dwordx4 v[138:139], v[110:113], off nt
	v_pk_mul_f32 v[138:139], v[176:177], v[110:111]
	s_nop 0
	v_cvt_pk_bf16_f32 v138, v138, v139
	v_cvt_pk_bf16_f32 v139, v140, v141
	ds_write_b128 v200, v[102:105]
	ds_write_b128 v200, v[98:101] offset:64
	ds_read_b128 v[98:101], v201
	ds_read_b128 v[102:105], v201 offset:1152
	s_waitcnt lgkmcnt(1)
	v_pk_fma_f32 v[98:99], v[168:169], v[98:99], v[134:135]
	v_pk_fma_f32 v[100:101], v[166:167], v[100:101], v[136:137]
	v_lshl_add_u64 v[134:135], s[56:57], 0, v[184:185]
	v_pk_mul_f32 v[136:137], v[172:173], v[98:99]
	s_waitcnt lgkmcnt(0)
	v_pk_fma_f32 v[104:105], v[166:167], v[104:105], v[132:133]
	v_pk_fma_f32 v[102:103], v[168:169], v[102:103], v[130:131]
	v_lshl_add_u64 v[130:131], s[56:57], 0, v[182:183]
	global_store_dwordx4 v[134:135], v[98:101], off nt
	v_pk_mul_f32 v[134:135], v[170:171], v[100:101]
	v_cvt_pk_bf16_f32 v136, v136, v137
	v_pk_mul_f32 v[132:133], v[172:173], v[102:103]
	v_cvt_pk_bf16_f32 v137, v134, v135
	global_store_dwordx4 v[130:131], v[102:105], off nt
	ds_bpermute_b32 v130, v203, v136
	ds_bpermute_b32 v131, v203, v137
	v_pk_mul_f32 v[134:135], v[170:171], v[104:105]
	v_cvt_pk_bf16_f32 v132, v132, v133
	s_nop 0
	v_cvt_pk_bf16_f32 v133, v134, v135
	v_lshlrev_b32_e32 v134, 1, v144
	s_and_saveexec_b64 s[12:13], s[40:41]
	s_xor_b64 s[16:17], exec, s[12:13]
	s_cbranch_execz .LBB0_332
	v_lshlrev_b32_e32 v134, 1, v144
	v_add_u32_e32 v135, 0xfffff040, v134
	s_waitcnt lgkmcnt(0)
	global_store_dwordx2 v135, v[130:131], s[54:55]

; #define LAS __attribute__((address_space(3)))
; __device__ __forceinline__ unsigned cvt_pk_bf16(float lo, float hi) { unsigned r; asm volatile("v_cvt_pk_bf16_f32 %0, %1, %2" : "=v"(r) : "v"(lo), "v"(hi)); return r; }
; #define ERN_EOFF(q, m) (eb + (unsigned)((((q) & 1) * HALF + (m) * 16) * DM + ERN_COL((q) >> 1)))
; #define ERN_LOADX(q) do { _Pragma("unroll") for (int m = 0; m < 4; ++m) xb[(q) & 1][m] = *(const f32x4*)((const char*)xi + 4u * ERN_EOFF(q, m)); } while (0)
;     __device__ __forceinline__ void operator()(const f32x4 (&acc)[2][2][4][2], const Unit& u, int wr, int wc, int fr, int fq) const {
;     ...
;         for (int g = 0; g < 8; ++g) { const int ai = g >> 2, m = g & 3;
;             if (g + 1 < 8) ERN_LOADX(g + 1);
;             float sq0 = 0.f, sq1 = 0.f; u32x2 hw[2][2];
; #pragma unroll
;             for (int bj = 0; bj < 2; ++bj) {
;                 *(LAS f32x4*)(st + wr_off) = acc[ai][bj][m][0]; *(LAS f32x4*)(st + wr_off + 64) = acc[ai][bj][m][1];
;                 const f32x4 a0 = *(const LAS f32x4*)(st + rd_off), a1 = *(const LAS f32x4*)(st + rd_off + 8 * 144);
;                 { const f32x4 xv = xb[g & 1][bj][0] + gv[bj] * a0; __builtin_nontemporal_store(xv, (f32x4*)((char*)xo + 4u * ERN_EOFF(g, bj, 0)));
;                   sq0 += (xv.x * xv.x + xv.y * xv.y) + (xv.z * xv.z + xv.w * xv.w);
;                   const f32x4 hv = xv * gsn[bj]; hw[bj][0].x = cvt_pk_bf16(hv.x, hv.y); hw[bj][0].y = cvt_pk_bf16(hv.z, hv.w); }
;                 { const f32x4 xv = xb[g & 1][bj][1] + gv[bj] * a1; __builtin_nontemporal_store(xv, (f32x4*)((char*)xo + 4u * ERN_EOFF(g, bj, 1)));
;                   sq1 += (xv.x * xv.x + xv.y * xv.y) + (xv.z * xv.z + xv.w * xv.w);
;                   const f32x4 hv = xv * gsn[bj]; hw[bj][1].x = cvt_pk_bf16(hv.x, hv.y); hw[bj][1].y = cvt_pk_bf16(hv.z, hv.w); }
;             }
;             if (!NOH && !PLAIN) {
; #pragma unroll
;                 for (int rh = 0; rh < 2; ++rh) { u32x2 rv; rv.x = __shfl_xor(hw[1][rh].x, 8); rv.y = __shfl_xor(hw[1][rh].y, 8);
;                     const unsigned e0 = ERN_EOFF(g, 0, rh);
;                     const unsigned ee = odd ? (e0 - DM + 32) : e0, eo2 = odd ? e0 : (e0 + DM + 32);
;                     *(u32x2*)((char*)ho + 2u * ee) = odd ? rv : hw[0][rh];
;                     *(u32x2*)((char*)ho + 2u * eo2) = odd ? hw[0][rh] : rv; }
.LBB0_340:
	s_or_b64 exec, exec, s[16:17]
	v_add_u32_e32 v98, 0x60000, v207
	v_add_u32_e32 v154, 0x70000, v207
	v_add_u32_e32 v132, 0x60080, v207
	global_load_dwordx4 v[106:109], v154, s[58:59]
	global_load_dwordx4 v[102:105], v132, s[58:59]
	v_add_u32_e32 v130, 0x70080, v207
	global_load_dwordx4 v[110:113], v98, s[58:59]
	s_waitcnt lgkmcnt(0)
	global_load_dwordx4 v[98:101], v130, s[58:59]
	v_add_u32_e32 v250, 0x120000, v249
	global_load_dword v251, v250, s[58:59]
	ds_write_b128 v200, v[94:97]
	ds_write_b128 v200, v[90:93] offset:64
	ds_read_b128 v[90:93], v201
	ds_read_b128 v[94:97], v201 offset:1152
	v_mov_b32_e32 v191, v155
	v_mov_b32_e32 v189, v155
	v_mov_b32_e32 v187, v155
	s_waitcnt vmcnt(11) lgkmcnt(1)
	v_pk_fma_f32 v[92:93], v[178:179], v[92:93], v[128:129]
	v_add_u32_e32 v128, 0x10000, v202
	v_pk_fma_f32 v[90:91], v[180:181], v[90:91], v[126:127]
	v_lshlrev_b32_e32 v126, 2, v128
	global_store_dwordx4 v126, v[90:93], s[56:57] nt
	v_pk_mul_f32 v[126:127], v[176:177], v[90:91]
	s_waitcnt lgkmcnt(0)
	v_pk_fma_f32 v[96:97], v[178:179], v[96:97], v[124:125]
	v_pk_fma_f32 v[94:95], v[180:181], v[94:95], v[122:123]
	v_lshl_add_u64 v[122:123], s[56:57], 0, v[190:191]
	v_pk_mul_f32 v[134:135], v[174:175], v[92:93]
	v_cvt_pk_bf16_f32 v126, v126, v127
	v_pk_mul_f32 v[124:125], v[174:175], v[96:97]
	v_cvt_pk_bf16_f32 v127, v134, v135
	global_store_dwordx4 v[122:123], v[94:97], off nt
	v_pk_mul_f32 v[122:123], v[176:177], v[94:95]
	s_nop 0
	v_cvt_pk_bf16_f32 v122, v122, v123
	v_cvt_pk_bf16_f32 v123, v124, v125
	ds_write_b128 v200, v[86:89]
	ds_write_b128 v200, v[82:85] offset:64
	ds_read_b128 v[82:85], v201
	ds_read_b128 v[86:89], v201 offset:1152
	s_waitcnt lgkmcnt(1)
	v_pk_fma_f32 v[82:83], v[168:169], v[82:83], v[118:119]
	v_pk_fma_f32 v[84:85], v[166:167], v[84:85], v[120:121]
	v_lshl_add_u64 v[118:119], s[56:57], 0, v[188:189]
	v_pk_mul_f32 v[120:121], v[172:173], v[82:83]
	s_waitcnt vmcnt(12) lgkmcnt(0)
	v_pk_fma_f32 v[88:89], v[166:167], v[88:89], v[116:117]
	v_pk_fma_f32 v[86:87], v[168:169], v[86:87], v[114:115]
	v_lshl_add_u64 v[114:115], s[56:57], 0, v[186:187]
	global_store_dwordx4 v[118:119], v[82:85], off nt
	v_pk_mul_f32 v[118:119], v[170:171], v[84:85]
	v_cvt_pk_bf16_f32 v120, v120, v121
	v_pk_mul_f32 v[116:117], v[172:173], v[86:87]
	v_cvt_pk_bf16_f32 v121, v118, v119
	global_store_dwordx4 v[114:115], v[86:89], off nt
	ds_bpermute_b32 v114, v203, v120
	ds_bpermute_b32 v115, v203, v121
	v_pk_mul_f32 v[118:119], v[170:171], v[88:89]
	v_cvt_pk_bf16_f32 v116, v116, v117
	s_nop 0
	v_cvt_pk_bf16_f32 v117, v118, v119
	v_lshlrev_b32_e32 v118, 1, v128
	s_and_saveexec_b64 s[12:13], s[40:41]
	s_xor_b64 s[16:17], exec, s[12:13]
	s_cbranch_execz .LBB0_342
	v_lshlrev_b32_e32 v118, 1, v128
	v_add_u32_e32 v119, 0xfffff040, v118
	s_waitcnt lgkmcnt(0)
	global_store_dwordx2 v119, v[114:115], s[54:55]

; #define LAS __attribute__((address_space(3)))
; __device__ __forceinline__ unsigned cvt_pk_bf16(float lo, float hi) { unsigned r; asm volatile("v_cvt_pk_bf16_f32 %0, %1, %2" : "=v"(r) : "v"(lo), "v"(hi)); return r; }
; #define ERN_EOFF(q, m) (eb + (unsigned)((((q) & 1) * HALF + (m) * 16) * DM + ERN_COL((q) >> 1)))
; #define ERN_LOADX(q) do { _Pragma("unroll") for (int m = 0; m < 4; ++m) xb[(q) & 1][m] = *(const f32x4*)((const char*)xi + 4u * ERN_EOFF(q, m)); } while (0)
;     __device__ __forceinline__ void operator()(const f32x4 (&acc)[2][2][4][2], const Unit& u, int wr, int wc, int fr, int fq) const {
;     ...
;         for (int g = 0; g < 8; ++g) { const int ai = g >> 2, m = g & 3;
;             if (g + 1 < 8) ERN_LOADX(g + 1);
;             float sq0 = 0.f, sq1 = 0.f; u32x2 hw[2][2];
; #pragma unroll
;             for (int bj = 0; bj < 2; ++bj) {
;                 *(LAS f32x4*)(st + wr_off) = acc[ai][bj][m][0]; *(LAS f32x4*)(st + wr_off + 64) = acc[ai][bj][m][1];
;                 const f32x4 a0 = *(const LAS f32x4*)(st + rd_off), a1 = *(const LAS f32x4*)(st + rd_off + 8 * 144);
;                 { const f32x4 xv = xb[g & 1][bj][0] + gv[bj] * a0; __builtin_nontemporal_store(xv, (f32x4*)((char*)xo + 4u * ERN_EOFF(g, bj, 0)));
;                   sq0 += (xv.x * xv.x + xv.y * xv.y) + (xv.z * xv.z + xv.w * xv.w);
;                   const f32x4 hv = xv * gsn[bj]; hw[bj][0].x = cvt_pk_bf16(hv.x, hv.y); hw[bj][0].y = cvt_pk_bf16(hv.z, hv.w); }
;                 { const f32x4 xv = xb[g & 1][bj][1] + gv[bj] * a1; __builtin_nontemporal_store(xv, (f32x4*)((char*)xo + 4u * ERN_EOFF(g, bj, 1)));
;                   sq1 += (xv.x * xv.x + xv.y * xv.y) + (xv.z * xv.z + xv.w * xv.w);
;                   const f32x4 hv = xv * gsn[bj]; hw[bj][1].x = cvt_pk_bf16(hv.x, hv.y); hw[bj][1].y = cvt_pk_bf16(hv.z, hv.w); }
;             }
;             if (!NOH && !PLAIN) {
; #pragma unroll
;                 for (int rh = 0; rh < 2; ++rh) { u32x2 rv; rv.x = __shfl_xor(hw[1][rh].x, 8); rv.y = __shfl_xor(hw[1][rh].y, 8);
;                     const unsigned e0 = ERN_EOFF(g, 0, rh);
;                     const unsigned ee = odd ? (e0 - DM + 32) : e0, eo2 = odd ? e0 : (e0 + DM + 32);
;                     *(u32x2*)((char*)ho + 2u * ee) = odd ? rv : hw[0][rh];
;                     *(u32x2*)((char*)ho + 2u * eo2) = odd ? hw[0][rh] : rv; }
.LBB0_350:
	s_or_b64 exec, exec, s[16:17]
	v_add_u32_e32 v82, 0x100000, v207
	s_waitcnt lgkmcnt(1)
	v_add_u32_e32 v83, 0x110000, v207
	v_add_u32_e32 v116, 0x100080, v207
	global_load_dwordx4 v[94:97], v82, s[58:59]
	global_load_dwordx4 v[90:93], v83, s[58:59]
	v_add_u32_e32 v114, 0x110080, v207
	global_load_dwordx4 v[86:89], v116, s[58:59]
	s_waitcnt lgkmcnt(0)
	global_load_dwordx4 v[82:85], v114, s[58:59]
	v_add_u32_e32 v250, 0x140000, v249
	global_load_dword v251, v250, s[58:59]
	ds_write_b128 v200, v[78:81]
	ds_write_b128 v200, v[74:77] offset:64
	ds_read_b128 v[74:77], v201
	ds_read_b128 v[78:81], v201 offset:1152
	v_mov_b32_e32 v133, v155
	v_mov_b32_e32 v131, v155
	s_waitcnt vmcnt(11) lgkmcnt(1)
	v_pk_fma_f32 v[76:77], v[178:179], v[76:77], v[112:113]
	v_add_u32_e32 v112, 0x18000, v202
	v_pk_fma_f32 v[74:75], v[180:181], v[74:75], v[110:111]
	v_lshlrev_b32_e32 v110, 2, v112
	global_store_dwordx4 v110, v[74:77], s[56:57] nt
	v_pk_mul_f32 v[110:111], v[176:177], v[74:75]
	s_waitcnt lgkmcnt(0)
	v_pk_fma_f32 v[80:81], v[178:179], v[80:81], v[108:109]
	v_pk_fma_f32 v[78:79], v[180:181], v[78:79], v[106:107]
	v_lshl_add_u64 v[106:107], s[56:57], 0, v[154:155]
	v_pk_mul_f32 v[118:119], v[174:175], v[76:77]
	v_cvt_pk_bf16_f32 v110, v110, v111
	v_pk_mul_f32 v[108:109], v[174:175], v[80:81]
	v_cvt_pk_bf16_f32 v111, v118, v119
	global_store_dwordx4 v[106:107], v[78:81], off nt
	v_pk_mul_f32 v[106:107], v[176:177], v[78:79]
	s_nop 0
	v_cvt_pk_bf16_f32 v106, v106, v107
	v_cvt_pk_bf16_f32 v107, v108, v109
	ds_write_b128 v200, v[70:73]
	ds_write_b128 v200, v[66:69] offset:64
	ds_read_b128 v[66:69], v201
	ds_read_b128 v[70:73], v201 offset:1152
	s_waitcnt lgkmcnt(1)
	v_pk_fma_f32 v[66:67], v[168:169], v[66:67], v[102:103]
	v_pk_fma_f32 v[68:69], v[166:167], v[68:69], v[104:105]
	v_lshl_add_u64 v[102:103], s[56:57], 0, v[132:133]
	v_pk_mul_f32 v[104:105], v[172:173], v[66:67]
	s_waitcnt vmcnt(12) lgkmcnt(0)
	v_pk_fma_f32 v[72:73], v[166:167], v[72:73], v[100:101]
	v_pk_fma_f32 v[70:71], v[168:169], v[70:71], v[98:99]
	v_lshl_add_u64 v[98:99], s[56:57], 0, v[130:131]
	global_store_dwordx4 v[102:103], v[66:69], off nt
	v_pk_mul_f32 v[102:103], v[170:171], v[68:69]
	v_cvt_pk_bf16_f32 v104, v104, v105
	v_pk_mul_f32 v[100:101], v[172:173], v[70:71]
	v_cvt_pk_bf16_f32 v105, v102, v103
	global_store_dwordx4 v[98:99], v[70:73], off nt
	ds_bpermute_b32 v98, v203, v104
	ds_bpermute_b32 v99, v203, v105
	v_pk_mul_f32 v[102:103], v[170:171], v[72:73]
	v_cvt_pk_bf16_f32 v100, v100, v101
	s_nop 0
	v_cvt_pk_bf16_f32 v101, v102, v103
	v_lshlrev_b32_e32 v102, 1, v112
	s_and_saveexec_b64 s[12:13], s[40:41]
	s_xor_b64 s[16:17], exec, s[12:13]
	s_cbranch_execz .LBB0_352
	v_lshlrev_b32_e32 v102, 1, v112
	v_add_u32_e32 v103, 0xfffff040, v102
	s_waitcnt lgkmcnt(0)
	global_store_dwordx2 v103, v[98:99], s[54:55]

; #define LAS __attribute__((address_space(3)))
; __device__ __forceinline__ unsigned cvt_pk_bf16(float lo, float hi) { unsigned r; asm volatile("v_cvt_pk_bf16_f32 %0, %1, %2" : "=v"(r) : "v"(lo), "v"(hi)); return r; }
; #define ERN_EOFF(q, m) (eb + (unsigned)((((q) & 1) * HALF + (m) * 16) * DM + ERN_COL((q) >> 1)))
; #define ERN_LOADX(q) do { _Pragma("unroll") for (int m = 0; m < 4; ++m) xb[(q) & 1][m] = *(const f32x4*)((const char*)xi + 4u * ERN_EOFF(q, m)); } while (0)
;     __device__ __forceinline__ void operator()(const f32x4 (&acc)[2][2][4][2], const Unit& u, int wr, int wc, int fr, int fq) const {
;     ...
;         for (int g = 0; g < 8; ++g) { const int ai = g >> 2, m = g & 3;
;             if (g + 1 < 8) ERN_LOADX(g + 1);
;             float sq0 = 0.f, sq1 = 0.f; u32x2 hw[2][2];
; #pragma unroll
;             for (int bj = 0; bj < 2; ++bj) {
;                 *(LAS f32x4*)(st + wr_off) = acc[ai][bj][m][0]; *(LAS f32x4*)(st + wr_off + 64) = acc[ai][bj][m][1];
;                 const f32x4 a0 = *(const LAS f32x4*)(st + rd_off), a1 = *(const LAS f32x4*)(st + rd_off + 8 * 144);
;                 { const f32x4 xv = xb[g & 1][bj][0] + gv[bj] * a0; __builtin_nontemporal_store(xv, (f32x4*)((char*)xo + 4u * ERN_EOFF(g, bj, 0)));
;                   sq0 += (xv.x * xv.x + xv.y * xv.y) + (xv.z * xv.z + xv.w * xv.w);
;                   const f32x4 hv = xv * gsn[bj]; hw[bj][0].x = cvt_pk_bf16(hv.x, hv.y); hw[bj][0].y = cvt_pk_bf16(hv.z, hv.w); }
;                 { const f32x4 xv = xb[g & 1][bj][1] + gv[bj] * a1; __builtin_nontemporal_store(xv, (f32x4*)((char*)xo + 4u * ERN_EOFF(g, bj, 1)));
;                   sq1 += (xv.x * xv.x + xv.y * xv.y) + (xv.z * xv.z + xv.w * xv.w);
;                   const f32x4 hv = xv * gsn[bj]; hw[bj][1].x = cvt_pk_bf16(hv.x, hv.y); hw[bj][1].y = cvt_pk_bf16(hv.z, hv.w); }
;             }
;             if (!NOH && !PLAIN) {
; #pragma unroll
;                 for (int rh = 0; rh < 2; ++rh) { u32x2 rv; rv.x = __shfl_xor(hw[1][rh].x, 8); rv.y = __shfl_xor(hw[1][rh].y, 8);
;                     const unsigned e0 = ERN_EOFF(g, 0, rh);
;                     const unsigned ee = odd ? (e0 - DM + 32) : e0, eo2 = odd ? e0 : (e0 + DM + 32);
;                     *(u32x2*)((char*)ho + 2u * ee) = odd ? rv : hw[0][rh];
;                     *(u32x2*)((char*)ho + 2u * eo2) = odd ? hw[0][rh] : rv; }
.LBB0_360:
	s_or_b64 exec, exec, s[16:17]
	v_add_u32_e32 v154, 0x120000, v207
	v_add_u32_e32 v100, 0x120080, v207
	v_add_u32_e32 v102, 0x130000, v207
	global_load_dwordx4 v[78:81], v154, s[58:59]
	global_load_dwordx4 v[74:77], v102, s[58:59]
	v_add_u32_e32 v98, 0x130080, v207
	global_load_dwordx4 v[70:73], v100, s[58:59]
	s_waitcnt lgkmcnt(0)
	global_load_dwordx4 v[66:69], v98, s[58:59]
	v_add_u32_e32 v250, 0x160000, v249
	global_load_dword v251, v250, s[58:59]
	ds_write_b128 v200, v[62:65]
	ds_write_b128 v200, v[58:61] offset:64
	ds_read_b128 v[58:61], v201
	ds_read_b128 v[62:65], v201 offset:1152
	v_mov_b32_e32 v117, v155
	v_mov_b32_e32 v115, v155
	s_waitcnt vmcnt(13) lgkmcnt(1)
	v_pk_fma_f32 v[60:61], v[178:179], v[60:61], v[96:97]
	v_add_u32_e32 v96, 0x40000, v202
	v_pk_fma_f32 v[58:59], v[180:181], v[58:59], v[94:95]
	v_lshlrev_b32_e32 v94, 2, v96
	s_waitcnt vmcnt(12) lgkmcnt(0)
	v_pk_fma_f32 v[64:65], v[178:179], v[64:65], v[92:93]
	v_add_u32_e32 v92, 0x44000, v202
	global_store_dwordx4 v94, v[58:61], s[56:57] nt
	v_pk_mul_f32 v[94:95], v[176:177], v[58:59]
	v_pk_fma_f32 v[62:63], v[180:181], v[62:63], v[90:91]
	v_lshlrev_b32_e32 v90, 2, v92
	v_pk_mul_f32 v[104:105], v[174:175], v[60:61]
	v_cvt_pk_bf16_f32 v94, v94, v95
	s_nop 0
	v_cvt_pk_bf16_f32 v95, v104, v105
	global_store_dwordx4 v90, v[62:65], s[56:57] nt
	v_pk_mul_f32 v[90:91], v[176:177], v[62:63]
	v_pk_mul_f32 v[104:105], v[174:175], v[64:65]
	v_cvt_pk_bf16_f32 v90, v90, v91
	s_nop 0
	v_cvt_pk_bf16_f32 v91, v104, v105
	ds_write_b128 v200, v[54:57]
	ds_write_b128 v200, v[50:53] offset:64
	ds_read_b128 v[50:53], v201
	ds_read_b128 v[54:57], v201 offset:1152
	s_waitcnt vmcnt(13) lgkmcnt(1)
	v_pk_fma_f32 v[50:51], v[168:169], v[50:51], v[86:87]
	v_pk_fma_f32 v[52:53], v[166:167], v[52:53], v[88:89]
	v_lshl_add_u64 v[86:87], s[56:57], 0, v[116:117]
	v_pk_mul_f32 v[88:89], v[172:173], v[50:51]
	s_waitcnt vmcnt(12) lgkmcnt(0)
	v_pk_fma_f32 v[56:57], v[166:167], v[56:57], v[84:85]
	v_pk_fma_f32 v[54:55], v[168:169], v[54:55], v[82:83]
	v_lshl_add_u64 v[82:83], s[56:57], 0, v[114:115]
	global_store_dwordx4 v[86:87], v[50:53], off nt
	v_pk_mul_f32 v[86:87], v[170:171], v[52:53]
	v_cvt_pk_bf16_f32 v88, v88, v89
	v_pk_mul_f32 v[84:85], v[172:173], v[54:55]
	v_cvt_pk_bf16_f32 v89, v86, v87
	global_store_dwordx4 v[82:83], v[54:57], off nt
	ds_bpermute_b32 v82, v203, v88
	ds_bpermute_b32 v83, v203, v89
	v_pk_mul_f32 v[86:87], v[170:171], v[56:57]
	v_cvt_pk_bf16_f32 v84, v84, v85
	s_nop 0
	v_cvt_pk_bf16_f32 v85, v86, v87
	v_lshlrev_b32_e32 v86, 1, v96
	s_and_saveexec_b64 s[12:13], s[40:41]
	s_xor_b64 s[16:17], exec, s[12:13]
	s_cbranch_execz .LBB0_362
	v_lshlrev_b32_e32 v86, 1, v96
	v_add_u32_e32 v87, 0xfffff040, v86
	s_waitcnt lgkmcnt(0)
	global_store_dwordx2 v87, v[82:83], s[54:55]

; #define LAS __attribute__((address_space(3)))
;     __device__ __forceinline__ void operator()(const f32x4 (&acc)[2][2][4][2], const Unit& u, int wr, int wc, int fr, int fq) const {
;         const int s = u.pm >> 5, lane = fq * 16 + fr, rr = lane >> 3, pc = lane & 7;
;         const float* __restrict__ xi = xin + (size_t)u.pm * BM * DM; float* __restrict__ xo = xout + (size_t)u.pm * BM * DM; bf16_t* __restrict__ ho = Hn + (size_t)u.pm * BM * DM;
;         LAS unsigned char* st = lds_epi + (wr * 4 + wc) * 2304;
;         LAS float* sst = (LAS float*)(lds_epi + 18432 + (wr * 4 + wc) * 512);
;         const int colr = u.pn * BM + wc * 64 + 4 * pc;
;         const unsigned eb = (unsigned)((wr * 64 + rr) * DM + colr);
;         f32x4 gv[2], gsn[2];
; #pragma unroll
;         for (int bj = 0; bj < 2; ++bj) { gv[bj] = *(const f32x4*)(gate + (size_t)s * MODW + colr + bj * 32) * (0.5f * GS2);
;             if (!PLAIN) gsn[bj] = *(const f32x4*)(gnext + colr + bj * 32) * (*(const f32x4*)(scnext + (size_t)s * MODW + colr + bj * 32) + 1.0f); else gsn[bj] = gv[bj]; }
;         const unsigned wr_off = (unsigned)(fr * 144 + 16 * fq), rd_off = (unsigned)(rr * 144 + pc * 16);
;         const bool odd = (rr & 1) != 0;
;         f32x4 xb[2][2][2];
;     ...
;         ERN_LOADX(0);
; #pragma unroll
;         for (int g = 0; g < 8; ++g) { const int ai = g >> 2, m = g & 3;
;             if (g + 1 < 8) ERN_LOADX(g + 1);
;             float sq0 = 0.f, sq1 = 0.f; u32x2 hw[2][2];
; #pragma unroll
;             for (int bj = 0; bj < 2; ++bj) {
;                 *(LAS f32x4*)(st + wr_off) = acc[ai][bj][m][0]; *(LAS f32x4*)(st + wr_off + 64) = acc[ai][bj][m][1];
;                 const f32x4 a0 = *(const LAS f32x4*)(st + rd_off), a1 = *(const LAS f32x4*)(st + rd_off + 8 * 144);
;                 { const f32x4 xv = xb[g & 1][bj][0] + gv[bj] * a0; __builtin_nontemporal_store(xv, (f32x4*)((char*)xo + 4u * ERN_EOFF(g, bj, 0)));
;                   sq0 += (xv.x * xv.x + xv.y * xv.y) + (xv.z * xv.z + xv.w * xv.w);
;                   const f32x4 hv = xv * gsn[bj]; hw[bj][0].x = cvt_pk_bf16(hv.x, hv.y); hw[bj][0].y = cvt_pk_bf16(hv.z, hv.w); }
;                 { const f32x4 xv = xb[g & 1][bj][1] + gv[bj] * a1; __builtin_nontemporal_store(xv, (f32x4*)((char*)xo + 4u * ERN_EOFF(g, bj, 1)));
;                   sq1 += (xv.x * xv.x + xv.y * xv.y) + (xv.z * xv.z + xv.w * xv.w);
.LBB0_1253:
	s_ashr_i32 s0, s92, 5
	s_ashr_i32 s93, s92, 31
	v_lshl_or_b32 v50, s46, 8, v192
	s_mul_hi_i32 s15, s0, 0x12000
	s_mul_i32 s0, s0, 0x12000
	s_add_u32 s16, s35, s0
	v_ashrrev_i32_e32 v51, 31, v50
	s_addc_u32 s17, s36, s15
	v_lshlrev_b64 v[52:53], 2, v[50:51]
	v_lshl_add_u64 v[138:139], s[16:17], 0, v[52:53]
	s_add_u32 s16, s37, s0
	s_addc_u32 s17, s52, s15
	v_lshl_add_u64 v[140:141], s[8:9], 0, v[52:53]
	v_lshl_add_u64 v[52:53], s[16:17], 0, v[52:53]
	s_lshl_b64 s[16:17], s[92:93], 21
	s_add_u32 s48, s90, s16
	v_add_u32_e32 v202, v50, v193
	s_addc_u32 s49, s91, s17
	v_lshlrev_b32_e32 v205, 2, v202
	global_load_dwordx4 v[54:57], v[138:139], off
	global_load_dwordx4 v[174:177], v[140:141], off
	global_load_dwordx4 v[178:181], v[52:53], off
	global_load_dwordx4 v[206:209], v[52:53], off offset:128
	global_load_dwordx4 v[186:189], v205, s[48:49]
	v_add_u32_e32 v50, 0x10000, v205
	global_load_dwordx4 v[210:213], v50, s[48:49]
	global_load_dwordx4 v[214:217], v[140:141], off offset:128
	s_nop 0
	global_load_dwordx4 v[50:53], v[138:139], off offset:128
	global_load_dwordx4 v[218:221], v205, s[48:49] offset:128
	v_add_u32_e32 v204, 0x10080, v205
	global_load_dwordx4 v[222:225], v204, s[48:49]
	v_add_u32_e32 v138, 0x20000, v205
	v_add_u32_e32 v162, 0x30000, v205
	v_add_u32_e32 v184, 0x20080, v205
	v_add_u32_e32 v182, 0x30080, v205
	global_load_dwordx4 v[150:153], v138, s[48:49]
	global_load_dwordx4 v[146:149], v162, s[48:49]
	global_load_dwordx4 v[142:145], v184, s[48:49]
	s_nop 0
	global_load_dwordx4 v[138:141], v182, s[48:49]
	ds_write_b128 v200, v[134:137]
	ds_write_b128 v200, v[130:133] offset:64
	v_and_b32_e32 v135, 64, v199
	ds_read_b128 v[130:133], v201
	ds_read_b128 v[226:229], v201 offset:1152
	v_xor_b32_e32 v134, 8, v199
	v_add_u32_e32 v183, 64, v135
	v_cmp_lt_i32_e32 vcc, v134, v183
	v_add_u32_e32 v185, 0x4000, v202
	v_lshlrev_b32_e32 v230, 2, v185
	v_cndmask_b32_e32 v134, v199, v134, vcc
	v_lshlrev_b32_e32 v203, 2, v134
	s_lshl_b64 s[16:17], s[92:93], 20
	v_readlane_b32 s0, v252, 41
	s_add_u32 s46, s0, s16
	v_readlane_b32 s0, v252, 42
	s_addc_u32 s47, s0, s17
	v_mbcnt_lo_u32_b32 v250, -1, 0
	v_mbcnt_hi_u32_b32 v250, -1, v250
	v_and_b32_e32 v249, 15, v250
	v_lshrrev_b32_e32 v251, 3, v250
	v_sub_u32_e32 v249, v249, v251
	v_lshlrev_b32_e32 v249, 13, v249
	v_bfe_u32 v251, v250, 4, 1
	v_lshl_add_u32 v249, v251, 7, v249
	v_and_b32_e32 v251, 7, v250
	v_lshlrev_b32_e32 v251, 4, v251
	v_sub_u32_e32 v249, v249, v251
	v_add_u32_e32 v249, v249, v205
	v_add_u32_e32 v250, 0x40000, v249
	global_load_dword v251, v250, s[48:49]
	v_add_u32_e32 v250, 0x60000, v249
	global_load_dword v251, v250, s[48:49]
	s_waitcnt vmcnt(2)
	v_pk_add_f32 v[134:135], v[180:181], 1.0 op_sel_hi:[1,0]
	v_pk_add_f32 v[136:137], v[178:179], 1.0 op_sel_hi:[1,0]
	v_pk_mul_f32 v[178:179], v[176:177], v[134:135]
	v_pk_mul_f32 v[180:181], v[174:175], v[136:137]
	s_waitcnt lgkmcnt(1)
	v_pk_fma_f32 v[134:135], v[54:55], v[130:131], v[186:187]
	s_waitcnt lgkmcnt(0)
	v_pk_fma_f32 v[130:131], v[54:55], v[226:227], v[210:211]
	v_pk_fma_f32 v[136:137], v[56:57], v[132:133], v[188:189]
	v_pk_fma_f32 v[132:133], v[56:57], v[228:229], v[212:213]
	v_pk_mul_f32 v[186:187], v[180:181], v[130:131]
	v_pk_add_f32 v[190:191], v[208:209], 1.0 op_sel_hi:[1,0]
	global_store_dwordx4 v205, v[134:137], s[48:49] nt
	v_pk_mul_f32 v[174:175], v[178:179], v[136:137]
	v_pk_mul_f32 v[176:177], v[180:181], v[134:135]
	v_pk_mul_f32 v[208:209], v[178:179], v[132:133]
	v_cvt_pk_bf16_f32 v188, v176, v177
	v_cvt_pk_bf16_f32 v189, v174, v175
	global_store_dwordx4 v230, v[130:133], s[48:49] nt
	v_cvt_pk_bf16_f32 v186, v186, v187
	v_cvt_pk_bf16_f32 v187, v208, v209
	ds_write_b128 v200, v[126:129]
	ds_write_b128 v200, v[122:125] offset:64
	ds_read_b128 v[122:125], v201
	v_pk_add_f32 v[126:127], v[206:207], 1.0 op_sel_hi:[1,0]
	ds_read_b128 v[206:209], v201 offset:1152
	v_pk_mul_f32 v[174:175], v[216:217], v[190:191]
	v_pk_mul_f32 v[176:177], v[214:215], v[126:127]
	s_waitcnt lgkmcnt(1)
	v_pk_fma_f32 v[128:129], v[52:53], v[124:125], v[220:221]
	v_pk_fma_f32 v[126:127], v[50:51], v[122:123], v[218:219]
	s_waitcnt lgkmcnt(0)
	v_pk_fma_f32 v[122:123], v[50:51], v[206:207], v[222:223]
	v_pk_mul_f32 v[190:191], v[174:175], v[128:129]
	v_pk_mul_f32 v[206:207], v[176:177], v[126:127]
	global_store_dwordx4 v205, v[126:129], s[48:49] offset:128 nt
	v_cvt_pk_bf16_f32 v206, v206, v207
	v_cvt_pk_bf16_f32 v191, v190, v191
	ds_bpermute_b32 v190, v203, v206
	ds_bpermute_b32 v191, v203, v191
	v_pk_fma_f32 v[124:125], v[52:53], v[208:209], v[224:225]
	v_pk_mul_f32 v[206:207], v[176:177], v[122:123]
	global_store_dwordx4 v204, v[122:125], s[48:49] nt
	v_cvt_pk_bf16_f32 v204, v206, v207
	v_lshlrev_b32_e32 v207, 1, v202
	v_pk_mul_f32 v[208:209], v[174:175], v[124:125]
	s_nop 0
	v_cvt_pk_bf16_f32 v206, v208, v209
	s_and_saveexec_b64 s[16:17], s[40:41]
	s_xor_b64 s[16:17], exec, s[16:17]
	s_cbranch_execz .LBB0_1255
	v_lshlrev_b32_e32 v207, 1, v202
	v_add_u32_e32 v208, 0xfffff040, v207
	s_waitcnt lgkmcnt(0)
	global_store_dwordx2 v208, v[190:191], s[46:47]

; #define LAS __attribute__((address_space(3)))
; __device__ __forceinline__ unsigned cvt_pk_bf16(float lo, float hi) { unsigned r; asm volatile("v_cvt_pk_bf16_f32 %0, %1, %2" : "=v"(r) : "v"(lo), "v"(hi)); return r; }
; #define ERN_EOFF(q, m) (eb + (unsigned)((((q) & 1) * HALF + (m) * 16) * DM + ERN_COL((q) >> 1)))
; #define ERN_LOADX(q) do { _Pragma("unroll") for (int m = 0; m < 4; ++m) xb[(q) & 1][m] = *(const f32x4*)((const char*)xi + 4u * ERN_EOFF(q, m)); } while (0)
;     __device__ __forceinline__ void operator()(const f32x4 (&acc)[2][2][4][2], const Unit& u, int wr, int wc, int fr, int fq) const {
;     ...
;         for (int g = 0; g < 8; ++g) { const int ai = g >> 2, m = g & 3;
;             if (g + 1 < 8) ERN_LOADX(g + 1);
;             float sq0 = 0.f, sq1 = 0.f; u32x2 hw[2][2];
; #pragma unroll
;             for (int bj = 0; bj < 2; ++bj) {
;                 *(LAS f32x4*)(st + wr_off) = acc[ai][bj][m][0]; *(LAS f32x4*)(st + wr_off + 64) = acc[ai][bj][m][1];
;                 const f32x4 a0 = *(const LAS f32x4*)(st + rd_off), a1 = *(const LAS f32x4*)(st + rd_off + 8 * 144);
;                 { const f32x4 xv = xb[g & 1][bj][0] + gv[bj] * a0; __builtin_nontemporal_store(xv, (f32x4*)((char*)xo + 4u * ERN_EOFF(g, bj, 0)));
;                   sq0 += (xv.x * xv.x + xv.y * xv.y) + (xv.z * xv.z + xv.w * xv.w);
;                   const f32x4 hv = xv * gsn[bj]; hw[bj][0].x = cvt_pk_bf16(hv.x, hv.y); hw[bj][0].y = cvt_pk_bf16(hv.z, hv.w); }
;                 { const f32x4 xv = xb[g & 1][bj][1] + gv[bj] * a1; __builtin_nontemporal_store(xv, (f32x4*)((char*)xo + 4u * ERN_EOFF(g, bj, 1)));
;                   sq1 += (xv.x * xv.x + xv.y * xv.y) + (xv.z * xv.z + xv.w * xv.w);
;                   const f32x4 hv = xv * gsn[bj]; hw[bj][1].x = cvt_pk_bf16(hv.x, hv.y); hw[bj][1].y = cvt_pk_bf16(hv.z, hv.w); }
;             }
;             if (!NOH && !PLAIN) {
; #pragma unroll
;                 for (int rh = 0; rh < 2; ++rh) { u32x2 rv; rv.x = __shfl_xor(hw[1][rh].x, 8); rv.y = __shfl_xor(hw[1][rh].y, 8);
;                     const unsigned e0 = ERN_EOFF(g, 0, rh);
;                     const unsigned ee = odd ? (e0 - DM + 32) : e0, eo2 = odd ? e0 : (e0 + DM + 32);
;                     *(u32x2*)((char*)ho + 2u * ee) = odd ? rv : hw[0][rh];
;                     *(u32x2*)((char*)ho + 2u * eo2) = odd ? hw[0][rh] : rv; }
.LBB0_1263:
	s_or_b64 exec, exec, s[16:17]
	v_lshl_add_u64 v[206:207], s[48:49], 0, v[162:163]
	v_add_u32_e32 v122, 0x40000, v205
	v_add_u32_e32 v162, 0x50000, v205
	v_add_u32_e32 v186, 0x40080, v205
	global_load_dwordx4 v[130:133], v162, s[48:49]
	global_load_dwordx4 v[126:129], v186, s[48:49]
	v_add_u32_e32 v188, 0x50080, v205
	global_load_dwordx4 v[134:137], v122, s[48:49]
	s_waitcnt lgkmcnt(0)
	global_load_dwordx4 v[122:125], v188, s[48:49]
	v_add_u32_e32 v250, 0x100000, v249
	global_load_dword v251, v250, s[48:49]
	ds_write_b128 v200, v[118:121]
	ds_write_b128 v200, v[114:117] offset:64
	ds_read_b128 v[114:117], v201
	ds_read_b128 v[118:121], v201 offset:1152
	v_mov_b32_e32 v185, v163
	v_mov_b32_e32 v183, v163
	v_lshl_add_u64 v[182:183], s[48:49], 0, v[182:183]
	s_waitcnt lgkmcnt(1)
	v_pk_fma_f32 v[116:117], v[56:57], v[116:117], v[152:153]
	v_add_u32_e32 v152, 0x8000, v202
	v_pk_fma_f32 v[114:115], v[54:55], v[114:115], v[150:151]
	v_lshlrev_b32_e32 v150, 2, v152
	s_waitcnt lgkmcnt(0)
	v_pk_fma_f32 v[118:119], v[54:55], v[118:119], v[146:147]
	global_store_dwordx4 v150, v[114:117], s[48:49] nt
	v_pk_mul_f32 v[150:151], v[180:181], v[114:115]
	v_pk_fma_f32 v[120:121], v[56:57], v[120:121], v[148:149]
	v_pk_mul_f32 v[146:147], v[180:181], v[118:119]
	v_pk_mul_f32 v[208:209], v[178:179], v[116:117]
	v_cvt_pk_bf16_f32 v150, v150, v151
	v_pk_mul_f32 v[148:149], v[178:179], v[120:121]
	v_cvt_pk_bf16_f32 v151, v208, v209
	global_store_dwordx4 v[206:207], v[118:121], off nt
	v_cvt_pk_bf16_f32 v146, v146, v147
	v_cvt_pk_bf16_f32 v147, v148, v149
	ds_write_b128 v200, v[110:113]
	ds_write_b128 v200, v[106:109] offset:64
	ds_read_b128 v[106:109], v201
	ds_read_b128 v[110:113], v201 offset:1152
	v_lshl_add_u64 v[148:149], s[48:49], 0, v[184:185]
	s_waitcnt lgkmcnt(1)
	v_pk_fma_f32 v[106:107], v[50:51], v[106:107], v[142:143]
	v_pk_fma_f32 v[108:109], v[52:53], v[108:109], v[144:145]
	v_pk_mul_f32 v[144:145], v[176:177], v[106:107]
	global_store_dwordx4 v[148:149], v[106:109], off nt
	v_pk_mul_f32 v[142:143], v[174:175], v[108:109]
	v_cvt_pk_bf16_f32 v144, v144, v145
	s_waitcnt lgkmcnt(0)
	v_pk_fma_f32 v[110:111], v[50:51], v[110:111], v[138:139]
	v_cvt_pk_bf16_f32 v145, v142, v143
	ds_bpermute_b32 v138, v203, v144
	ds_bpermute_b32 v139, v203, v145
	v_pk_fma_f32 v[112:113], v[52:53], v[112:113], v[140:141]
	v_pk_mul_f32 v[140:141], v[176:177], v[110:111]
	v_pk_mul_f32 v[142:143], v[174:175], v[112:113]
	global_store_dwordx4 v[182:183], v[110:113], off nt
	v_cvt_pk_bf16_f32 v140, v140, v141
	v_cvt_pk_bf16_f32 v141, v142, v143
	v_lshlrev_b32_e32 v142, 1, v152
	s_and_saveexec_b64 s[16:17], s[40:41]
	s_xor_b64 s[16:17], exec, s[16:17]
	s_cbranch_execz .LBB0_1265
	v_lshlrev_b32_e32 v142, 1, v152
	v_add_u32_e32 v143, 0xfffff040, v142
	s_waitcnt lgkmcnt(0)
	global_store_dwordx2 v143, v[138:139], s[46:47]

; #define LAS __attribute__((address_space(3)))
; __device__ __forceinline__ unsigned cvt_pk_bf16(float lo, float hi) { unsigned r; asm volatile("v_cvt_pk_bf16_f32 %0, %1, %2" : "=v"(r) : "v"(lo), "v"(hi)); return r; }
; #define ERN_EOFF(q, m) (eb + (unsigned)((((q) & 1) * HALF + (m) * 16) * DM + ERN_COL((q) >> 1)))
; #define ERN_LOADX(q) do { _Pragma("unroll") for (int m = 0; m < 4; ++m) xb[(q) & 1][m] = *(const f32x4*)((const char*)xi + 4u * ERN_EOFF(q, m)); } while (0)
;     __device__ __forceinline__ void operator()(const f32x4 (&acc)[2][2][4][2], const Unit& u, int wr, int wc, int fr, int fq) const {
;     ...
;         for (int g = 0; g < 8; ++g) { const int ai = g >> 2, m = g & 3;
;             if (g + 1 < 8) ERN_LOADX(g + 1);
;             float sq0 = 0.f, sq1 = 0.f; u32x2 hw[2][2];
; #pragma unroll
;             for (int bj = 0; bj < 2; ++bj) {
;                 *(LAS f32x4*)(st + wr_off) = acc[ai][bj][m][0]; *(LAS f32x4*)(st + wr_off + 64) = acc[ai][bj][m][1];
;                 const f32x4 a0 = *(const LAS f32x4*)(st + rd_off), a1 = *(const LAS f32x4*)(st + rd_off + 8 * 144);
;                 { const f32x4 xv = xb[g & 1][bj][0] + gv[bj] * a0; __builtin_nontemporal_store(xv, (f32x4*)((char*)xo + 4u * ERN_EOFF(g, bj, 0)));
;                   sq0 += (xv.x * xv.x + xv.y * xv.y) + (xv.z * xv.z + xv.w * xv.w);
;                   const f32x4 hv = xv * gsn[bj]; hw[bj][0].x = cvt_pk_bf16(hv.x, hv.y); hw[bj][0].y = cvt_pk_bf16(hv.z, hv.w); }
;                 { const f32x4 xv = xb[g & 1][bj][1] + gv[bj] * a1; __builtin_nontemporal_store(xv, (f32x4*)((char*)xo + 4u * ERN_EOFF(g, bj, 1)));
;                   sq1 += (xv.x * xv.x + xv.y * xv.y) + (xv.z * xv.z + xv.w * xv.w);
;                   const f32x4 hv = xv * gsn[bj]; hw[bj][1].x = cvt_pk_bf16(hv.x, hv.y); hw[bj][1].y = cvt_pk_bf16(hv.z, hv.w); }
;             }
;             if (!NOH && !PLAIN) {
; #pragma unroll
;                 for (int rh = 0; rh < 2; ++rh) { u32x2 rv; rv.x = __shfl_xor(hw[1][rh].x, 8); rv.y = __shfl_xor(hw[1][rh].y, 8);
;                     const unsigned e0 = ERN_EOFF(g, 0, rh);
;                     const unsigned ee = odd ? (e0 - DM + 32) : e0, eo2 = odd ? e0 : (e0 + DM + 32);
;                     *(u32x2*)((char*)ho + 2u * ee) = odd ? rv : hw[0][rh];
;                     *(u32x2*)((char*)ho + 2u * eo2) = odd ? hw[0][rh] : rv; }
.LBB0_1273:
	s_or_b64 exec, exec, s[16:17]
	v_lshl_add_u64 v[142:143], s[48:49], 0, v[162:163]
	v_add_u32_e32 v106, 0x60000, v205
	v_add_u32_e32 v162, 0x70000, v205
	v_add_u32_e32 v138, 0x60080, v205
	global_load_dwordx4 v[114:117], v162, s[48:49]
	global_load_dwordx4 v[110:113], v138, s[48:49]
	v_add_u32_e32 v140, 0x70080, v205
	global_load_dwordx4 v[118:121], v106, s[48:49]
	s_waitcnt lgkmcnt(0)
	global_load_dwordx4 v[106:109], v140, s[48:49]
	v_add_u32_e32 v250, 0x120000, v249
	global_load_dword v251, v250, s[48:49]
	ds_write_b128 v200, v[102:105]
	ds_write_b128 v200, v[98:101] offset:64
	ds_read_b128 v[98:101], v201
	ds_read_b128 v[102:105], v201 offset:1152
	v_mov_b32_e32 v187, v163
	v_mov_b32_e32 v189, v163
	s_waitcnt vmcnt(11) lgkmcnt(1)
	v_pk_fma_f32 v[100:101], v[56:57], v[100:101], v[136:137]
	v_add_u32_e32 v136, 0x10000, v202
	v_pk_fma_f32 v[98:99], v[54:55], v[98:99], v[134:135]
	v_lshlrev_b32_e32 v134, 2, v136
	s_waitcnt lgkmcnt(0)
	v_pk_fma_f32 v[102:103], v[54:55], v[102:103], v[130:131]
	global_store_dwordx4 v134, v[98:101], s[48:49] nt
	v_pk_mul_f32 v[134:135], v[180:181], v[98:99]
	v_pk_fma_f32 v[104:105], v[56:57], v[104:105], v[132:133]
	v_pk_mul_f32 v[130:131], v[180:181], v[102:103]
	v_pk_mul_f32 v[144:145], v[178:179], v[100:101]
	v_cvt_pk_bf16_f32 v134, v134, v135
	v_pk_mul_f32 v[132:133], v[178:179], v[104:105]
	v_cvt_pk_bf16_f32 v135, v144, v145
	global_store_dwordx4 v[142:143], v[102:105], off nt
	v_cvt_pk_bf16_f32 v130, v130, v131
	v_cvt_pk_bf16_f32 v131, v132, v133
	ds_write_b128 v200, v[94:97]
	ds_write_b128 v200, v[90:93] offset:64
	ds_read_b128 v[90:93], v201
	ds_read_b128 v[94:97], v201 offset:1152
	v_lshl_add_u64 v[132:133], s[48:49], 0, v[186:187]
	v_lshl_add_u64 v[142:143], s[48:49], 0, v[188:189]
	s_waitcnt lgkmcnt(1)
	v_pk_fma_f32 v[90:91], v[50:51], v[90:91], v[126:127]
	v_pk_fma_f32 v[92:93], v[52:53], v[92:93], v[128:129]
	v_pk_mul_f32 v[128:129], v[176:177], v[90:91]
	global_store_dwordx4 v[132:133], v[90:93], off nt
	v_pk_mul_f32 v[126:127], v[174:175], v[92:93]
	v_cvt_pk_bf16_f32 v128, v128, v129
	s_waitcnt vmcnt(13) lgkmcnt(0)
	v_pk_fma_f32 v[94:95], v[50:51], v[94:95], v[122:123]
	v_cvt_pk_bf16_f32 v129, v126, v127
	ds_bpermute_b32 v122, v203, v128
	ds_bpermute_b32 v123, v203, v129
	v_pk_fma_f32 v[96:97], v[52:53], v[96:97], v[124:125]
	v_pk_mul_f32 v[124:125], v[176:177], v[94:95]
	v_pk_mul_f32 v[126:127], v[174:175], v[96:97]
	global_store_dwordx4 v[142:143], v[94:97], off nt
	v_cvt_pk_bf16_f32 v124, v124, v125
	v_cvt_pk_bf16_f32 v125, v126, v127
	v_lshlrev_b32_e32 v126, 1, v136
	s_and_saveexec_b64 s[16:17], s[40:41]
	s_xor_b64 s[16:17], exec, s[16:17]
	s_cbranch_execz .LBB0_1275
	v_lshlrev_b32_e32 v126, 1, v136
	v_add_u32_e32 v127, 0xfffff040, v126
	s_waitcnt lgkmcnt(0)
	global_store_dwordx2 v127, v[122:123], s[46:47]

; #define LAS __attribute__((address_space(3)))
; __device__ __forceinline__ unsigned cvt_pk_bf16(float lo, float hi) { unsigned r; asm volatile("v_cvt_pk_bf16_f32 %0, %1, %2" : "=v"(r) : "v"(lo), "v"(hi)); return r; }
; #define ERN_EOFF(q, m) (eb + (unsigned)((((q) & 1) * HALF + (m) * 16) * DM + ERN_COL((q) >> 1)))
; #define ERN_LOADX(q) do { _Pragma("unroll") for (int m = 0; m < 4; ++m) xb[(q) & 1][m] = *(const f32x4*)((const char*)xi + 4u * ERN_EOFF(q, m)); } while (0)
;     __device__ __forceinline__ void operator()(const f32x4 (&acc)[2][2][4][2], const Unit& u, int wr, int wc, int fr, int fq) const {
;     ...
;         for (int g = 0; g < 8; ++g) { const int ai = g >> 2, m = g & 3;
;             if (g + 1 < 8) ERN_LOADX(g + 1);
;             float sq0 = 0.f, sq1 = 0.f; u32x2 hw[2][2];
; #pragma unroll
;             for (int bj = 0; bj < 2; ++bj) {
;                 *(LAS f32x4*)(st + wr_off) = acc[ai][bj][m][0]; *(LAS f32x4*)(st + wr_off + 64) = acc[ai][bj][m][1];
;                 const f32x4 a0 = *(const LAS f32x4*)(st + rd_off), a1 = *(const LAS f32x4*)(st + rd_off + 8 * 144);
;                 { const f32x4 xv = xb[g & 1][bj][0] + gv[bj] * a0; __builtin_nontemporal_store(xv, (f32x4*)((char*)xo + 4u * ERN_EOFF(g, bj, 0)));
;                   sq0 += (xv.x * xv.x + xv.y * xv.y) + (xv.z * xv.z + xv.w * xv.w);
;                   const f32x4 hv = xv * gsn[bj]; hw[bj][0].x = cvt_pk_bf16(hv.x, hv.y); hw[bj][0].y = cvt_pk_bf16(hv.z, hv.w); }
;                 { const f32x4 xv = xb[g & 1][bj][1] + gv[bj] * a1; __builtin_nontemporal_store(xv, (f32x4*)((char*)xo + 4u * ERN_EOFF(g, bj, 1)));
;                   sq1 += (xv.x * xv.x + xv.y * xv.y) + (xv.z * xv.z + xv.w * xv.w);
;                   const f32x4 hv = xv * gsn[bj]; hw[bj][1].x = cvt_pk_bf16(hv.x, hv.y); hw[bj][1].y = cvt_pk_bf16(hv.z, hv.w); }
;             }
;             if (!NOH && !PLAIN) {
; #pragma unroll
;                 for (int rh = 0; rh < 2; ++rh) { u32x2 rv; rv.x = __shfl_xor(hw[1][rh].x, 8); rv.y = __shfl_xor(hw[1][rh].y, 8);
;                     const unsigned e0 = ERN_EOFF(g, 0, rh);
;                     const unsigned ee = odd ? (e0 - DM + 32) : e0, eo2 = odd ? e0 : (e0 + DM + 32);
;                     *(u32x2*)((char*)ho + 2u * ee) = odd ? rv : hw[0][rh];
;                     *(u32x2*)((char*)ho + 2u * eo2) = odd ? hw[0][rh] : rv; }
.LBB0_1283:
	s_or_b64 exec, exec, s[16:17]
	v_lshl_add_u64 v[124:125], s[48:49], 0, v[162:163]
	v_add_u32_e32 v90, 0x100000, v205
	s_waitcnt lgkmcnt(1)
	v_add_u32_e32 v91, 0x110000, v205
	v_add_u32_e32 v162, 0x100080, v205
	global_load_dwordx4 v[102:105], v90, s[48:49]
	global_load_dwordx4 v[98:101], v91, s[48:49]
	v_add_u32_e32 v122, 0x110080, v205
	global_load_dwordx4 v[94:97], v162, s[48:49]
	s_waitcnt lgkmcnt(0)
	global_load_dwordx4 v[90:93], v122, s[48:49]
	v_add_u32_e32 v250, 0x140000, v249
	global_load_dword v251, v250, s[48:49]
	ds_write_b128 v200, v[86:89]
	ds_write_b128 v200, v[82:85] offset:64
	ds_read_b128 v[82:85], v201
	ds_read_b128 v[86:89], v201 offset:1152
	v_mov_b32_e32 v139, v163
	v_mov_b32_e32 v141, v163
	s_waitcnt vmcnt(11) lgkmcnt(1)
	v_pk_fma_f32 v[84:85], v[56:57], v[84:85], v[120:121]
	v_add_u32_e32 v120, 0x18000, v202
	v_pk_fma_f32 v[82:83], v[54:55], v[82:83], v[118:119]
	v_lshlrev_b32_e32 v118, 2, v120
	s_waitcnt lgkmcnt(0)
	v_pk_fma_f32 v[86:87], v[54:55], v[86:87], v[114:115]
	global_store_dwordx4 v118, v[82:85], s[48:49] nt
	v_pk_mul_f32 v[118:119], v[180:181], v[82:83]
	v_pk_fma_f32 v[88:89], v[56:57], v[88:89], v[116:117]
	v_pk_mul_f32 v[114:115], v[180:181], v[86:87]
	v_pk_mul_f32 v[126:127], v[178:179], v[84:85]
	v_cvt_pk_bf16_f32 v118, v118, v119
	v_pk_mul_f32 v[116:117], v[178:179], v[88:89]
	v_cvt_pk_bf16_f32 v119, v126, v127
	global_store_dwordx4 v[124:125], v[86:89], off nt
	v_cvt_pk_bf16_f32 v114, v114, v115
	v_cvt_pk_bf16_f32 v115, v116, v117
	ds_write_b128 v200, v[78:81]
	ds_write_b128 v200, v[74:77] offset:64
	ds_read_b128 v[74:77], v201
	ds_read_b128 v[78:81], v201 offset:1152
	v_lshl_add_u64 v[116:117], s[48:49], 0, v[138:139]
	v_lshl_add_u64 v[124:125], s[48:49], 0, v[140:141]
	s_waitcnt lgkmcnt(1)
	v_pk_fma_f32 v[74:75], v[50:51], v[74:75], v[110:111]
	v_pk_fma_f32 v[76:77], v[52:53], v[76:77], v[112:113]
	v_pk_mul_f32 v[112:113], v[176:177], v[74:75]
	global_store_dwordx4 v[116:117], v[74:77], off nt
	v_pk_mul_f32 v[110:111], v[174:175], v[76:77]
	v_cvt_pk_bf16_f32 v112, v112, v113
	s_waitcnt vmcnt(13) lgkmcnt(0)
	v_pk_fma_f32 v[78:79], v[50:51], v[78:79], v[106:107]
	v_cvt_pk_bf16_f32 v113, v110, v111
	ds_bpermute_b32 v106, v203, v112
	ds_bpermute_b32 v107, v203, v113
	v_pk_fma_f32 v[80:81], v[52:53], v[80:81], v[108:109]
	v_pk_mul_f32 v[108:109], v[176:177], v[78:79]
	v_pk_mul_f32 v[110:111], v[174:175], v[80:81]
	global_store_dwordx4 v[124:125], v[78:81], off nt
	v_cvt_pk_bf16_f32 v108, v108, v109
	v_cvt_pk_bf16_f32 v109, v110, v111
	v_lshlrev_b32_e32 v110, 1, v120
	s_and_saveexec_b64 s[16:17], s[40:41]
	s_xor_b64 s[16:17], exec, s[16:17]
	s_cbranch_execz .LBB0_1285
	v_lshlrev_b32_e32 v110, 1, v120
	v_add_u32_e32 v111, 0xfffff040, v110
	s_waitcnt lgkmcnt(0)
	global_store_dwordx2 v111, v[106:107], s[46:47]

; #define LAS __attribute__((address_space(3)))
; __device__ __forceinline__ unsigned cvt_pk_bf16(float lo, float hi) { unsigned r; asm volatile("v_cvt_pk_bf16_f32 %0, %1, %2" : "=v"(r) : "v"(lo), "v"(hi)); return r; }
; #define ERN_EOFF(q, m) (eb + (unsigned)((((q) & 1) * HALF + (m) * 16) * DM + ERN_COL((q) >> 1)))
; #define ERN_LOADX(q) do { _Pragma("unroll") for (int m = 0; m < 4; ++m) xb[(q) & 1][m] = *(const f32x4*)((const char*)xi + 4u * ERN_EOFF(q, m)); } while (0)
;     __device__ __forceinline__ void operator()(const f32x4 (&acc)[2][2][4][2], const Unit& u, int wr, int wc, int fr, int fq) const {
;     ...
;         for (int g = 0; g < 8; ++g) { const int ai = g >> 2, m = g & 3;
;             if (g + 1 < 8) ERN_LOADX(g + 1);
;             float sq0 = 0.f, sq1 = 0.f; u32x2 hw[2][2];
; #pragma unroll
;             for (int bj = 0; bj < 2; ++bj) {
;                 *(LAS f32x4*)(st + wr_off) = acc[ai][bj][m][0]; *(LAS f32x4*)(st + wr_off + 64) = acc[ai][bj][m][1];
;                 const f32x4 a0 = *(const LAS f32x4*)(st + rd_off), a1 = *(const LAS f32x4*)(st + rd_off + 8 * 144);
;                 { const f32x4 xv = xb[g & 1][bj][0] + gv[bj] * a0; __builtin_nontemporal_store(xv, (f32x4*)((char*)xo + 4u * ERN_EOFF(g, bj, 0)));
;                   sq0 += (xv.x * xv.x + xv.y * xv.y) + (xv.z * xv.z + xv.w * xv.w);
;                   const f32x4 hv = xv * gsn[bj]; hw[bj][0].x = cvt_pk_bf16(hv.x, hv.y); hw[bj][0].y = cvt_pk_bf16(hv.z, hv.w); }
;                 { const f32x4 xv = xb[g & 1][bj][1] + gv[bj] * a1; __builtin_nontemporal_store(xv, (f32x4*)((char*)xo + 4u * ERN_EOFF(g, bj, 1)));
;                   sq1 += (xv.x * xv.x + xv.y * xv.y) + (xv.z * xv.z + xv.w * xv.w);
;                   const f32x4 hv = xv * gsn[bj]; hw[bj][1].x = cvt_pk_bf16(hv.x, hv.y); hw[bj][1].y = cvt_pk_bf16(hv.z, hv.w); }
;             }
;             if (!NOH && !PLAIN) {
; #pragma unroll
;                 for (int rh = 0; rh < 2; ++rh) { u32x2 rv; rv.x = __shfl_xor(hw[1][rh].x, 8); rv.y = __shfl_xor(hw[1][rh].y, 8);
;                     const unsigned e0 = ERN_EOFF(g, 0, rh);
;                     const unsigned ee = odd ? (e0 - DM + 32) : e0, eo2 = odd ? e0 : (e0 + DM + 32);
;                     *(u32x2*)((char*)ho + 2u * ee) = odd ? rv : hw[0][rh];
;                     *(u32x2*)((char*)ho + 2u * eo2) = odd ? hw[0][rh] : rv; }
.LBB0_1293:
	s_or_b64 exec, exec, s[16:17]
	v_lshl_add_u64 v[112:113], s[48:49], 0, v[162:163]
	v_add_u32_e32 v162, 0x120000, v205
	v_add_u32_e32 v108, 0x120080, v205
	v_add_u32_e32 v110, 0x130000, v205
	global_load_dwordx4 v[86:89], v162, s[48:49]
	global_load_dwordx4 v[82:85], v110, s[48:49]
	v_add_u32_e32 v106, 0x130080, v205
	global_load_dwordx4 v[78:81], v108, s[48:49]
	s_waitcnt lgkmcnt(0)
	global_load_dwordx4 v[74:77], v106, s[48:49]
	v_add_u32_e32 v250, 0x160000, v249
	global_load_dword v251, v250, s[48:49]
	ds_write_b128 v200, v[70:73]
	ds_write_b128 v200, v[66:69] offset:64
	ds_read_b128 v[66:69], v201
	ds_read_b128 v[70:73], v201 offset:1152
	v_mov_b32_e32 v123, v163
	s_waitcnt vmcnt(13) lgkmcnt(1)
	v_pk_fma_f32 v[68:69], v[56:57], v[68:69], v[104:105]
	v_add_u32_e32 v104, 0x40000, v202
	v_pk_fma_f32 v[66:67], v[54:55], v[66:67], v[102:103]
	v_lshlrev_b32_e32 v102, 2, v104
	s_waitcnt vmcnt(12) lgkmcnt(0)
	v_pk_fma_f32 v[72:73], v[56:57], v[72:73], v[100:101]
	v_add_u32_e32 v100, 0x44000, v202
	global_store_dwordx4 v102, v[66:69], s[48:49] nt
	v_pk_mul_f32 v[102:103], v[180:181], v[66:67]
	v_pk_fma_f32 v[70:71], v[54:55], v[70:71], v[98:99]
	v_lshlrev_b32_e32 v98, 2, v100
	v_pk_mul_f32 v[114:115], v[178:179], v[68:69]
	v_cvt_pk_bf16_f32 v102, v102, v103
	s_nop 0
	v_cvt_pk_bf16_f32 v103, v114, v115
	global_store_dwordx4 v98, v[70:73], s[48:49] nt
	v_pk_mul_f32 v[98:99], v[180:181], v[70:71]
	v_pk_mul_f32 v[114:115], v[178:179], v[72:73]
	v_cvt_pk_bf16_f32 v98, v98, v99
	s_nop 0
	v_cvt_pk_bf16_f32 v99, v114, v115
	ds_write_b128 v200, v[62:65]
	ds_write_b128 v200, v[58:61] offset:64
	ds_read_b128 v[58:61], v201
	ds_read_b128 v[62:65], v201 offset:1152
	v_lshl_add_u64 v[114:115], s[48:49], 0, v[122:123]
	s_waitcnt vmcnt(13) lgkmcnt(1)
	v_pk_fma_f32 v[58:59], v[50:51], v[58:59], v[94:95]
	v_pk_fma_f32 v[60:61], v[52:53], v[60:61], v[96:97]
	v_pk_mul_f32 v[96:97], v[176:177], v[58:59]
	global_store_dwordx4 v[112:113], v[58:61], off nt
	v_pk_mul_f32 v[94:95], v[174:175], v[60:61]
	v_cvt_pk_bf16_f32 v96, v96, v97
	s_waitcnt vmcnt(13) lgkmcnt(0)
	v_pk_fma_f32 v[62:63], v[50:51], v[62:63], v[90:91]
	v_cvt_pk_bf16_f32 v97, v94, v95
	ds_bpermute_b32 v90, v203, v96
	ds_bpermute_b32 v91, v203, v97
	v_pk_fma_f32 v[64:65], v[52:53], v[64:65], v[92:93]
	v_pk_mul_f32 v[92:93], v[176:177], v[62:63]
	v_pk_mul_f32 v[94:95], v[174:175], v[64:65]
	global_store_dwordx4 v[114:115], v[62:65], off nt
	v_cvt_pk_bf16_f32 v92, v92, v93
	v_cvt_pk_bf16_f32 v93, v94, v95
	v_lshlrev_b32_e32 v94, 1, v104
	s_and_saveexec_b64 s[16:17], s[40:41]
	s_xor_b64 s[16:17], exec, s[16:17]
	s_cbranch_execz .LBB0_1295
	v_lshlrev_b32_e32 v94, 1, v104
	v_add_u32_e32 v95, 0xfffff040, v94
	s_waitcnt lgkmcnt(0)
	global_store_dwordx2 v95, v[90:91], s[46:47]

; #define LAS __attribute__((address_space(3)))
;     __device__ __forceinline__ void operator()(const f32x4 (&acc)[2][2][4][2], const Unit& u, int wr, int wc, int fr, int fq) const {
;         const int s = u.pm >> 5, lane = fq * 16 + fr, rr = lane >> 3, pc = lane & 7;
;         const float* __restrict__ xi = xin + (size_t)u.pm * BM * DM; float* __restrict__ xo = xout + (size_t)u.pm * BM * DM; bf16_t* __restrict__ ho = Hn + (size_t)u.pm * BM * DM;
;         LAS unsigned char* st = lds_epi + (wr * 4 + wc) * 2304;
;         LAS float* sst = (LAS float*)(lds_epi + 18432 + (wr * 4 + wc) * 512);
;         const int colr = u.pn * BM + wc * 64 + 4 * pc;
;         const unsigned eb = (unsigned)((wr * 64 + rr) * DM + colr);
;         f32x4 gv[2], gsn[2];
; #pragma unroll
;         for (int bj = 0; bj < 2; ++bj) { gv[bj] = *(const f32x4*)(gate + (size_t)s * MODW + colr + bj * 32) * (0.5f * GS2);
;             if (!PLAIN) gsn[bj] = *(const f32x4*)(gnext + colr + bj * 32) * (*(const f32x4*)(scnext + (size_t)s * MODW + colr + bj * 32) + 1.0f); else gsn[bj] = gv[bj]; }
;         const unsigned wr_off = (unsigned)(fr * 144 + 16 * fq), rd_off = (unsigned)(rr * 144 + pc * 16);
;         const bool odd = (rr & 1) != 0;
;         f32x4 xb[2][2][2];
;     ...
;         ERN_LOADX(0);
; #pragma unroll
;         for (int g = 0; g < 8; ++g) { const int ai = g >> 2, m = g & 3;
;             if (g + 1 < 8) ERN_LOADX(g + 1);
;             float sq0 = 0.f, sq1 = 0.f; u32x2 hw[2][2];
; #pragma unroll
;             for (int bj = 0; bj < 2; ++bj) {
;                 *(LAS f32x4*)(st + wr_off) = acc[ai][bj][m][0]; *(LAS f32x4*)(st + wr_off + 64) = acc[ai][bj][m][1];
;                 const f32x4 a0 = *(const LAS f32x4*)(st + rd_off), a1 = *(const LAS f32x4*)(st + rd_off + 8 * 144);
;                 { const f32x4 xv = xb[g & 1][bj][0] + gv[bj] * a0; __builtin_nontemporal_store(xv, (f32x4*)((char*)xo + 4u * ERN_EOFF(g, bj, 0)));
;                   sq0 += (xv.x * xv.x + xv.y * xv.y) + (xv.z * xv.z + xv.w * xv.w);
;                   const f32x4 hv = xv * gsn[bj]; hw[bj][0].x = cvt_pk_bf16(hv.x, hv.y); hw[bj][0].y = cvt_pk_bf16(hv.z, hv.w); }
;                 { const f32x4 xv = xb[g & 1][bj][1] + gv[bj] * a1; __builtin_nontemporal_store(xv, (f32x4*)((char*)xo + 4u * ERN_EOFF(g, bj, 1)));
;                   sq1 += (xv.x * xv.x + xv.y * xv.y) + (xv.z * xv.z + xv.w * xv.w);
.LBB0_1598:
	s_ashr_i32 s16, s8, 5
	s_ashr_i32 s9, s8, 31
	v_lshl_or_b32 v130, s0, 8, v192
	s_mul_i32 s20, s16, 0x12000
	s_mul_hi_i32 s0, s16, 0x12000
	s_add_u32 s16, s37, s20
	v_ashrrev_i32_e32 v131, 31, v130
	s_addc_u32 s17, s48, s0
	v_lshlrev_b64 v[132:133], 2, v[130:131]
	v_lshl_add_u64 v[134:135], s[16:17], 0, v[132:133]
	s_add_u32 s16, s26, s20
	s_addc_u32 s17, s27, s0
	v_lshl_add_u64 v[136:137], s[4:5], 0, v[132:133]
	v_lshl_add_u64 v[132:133], s[16:17], 0, v[132:133]
	s_lshl_b64 s[16:17], s[8:9], 21
	s_add_u32 s22, s90, s16
	v_add_u32_e32 v202, v130, v193
	s_addc_u32 s23, s91, s17
	v_lshlrev_b32_e32 v205, 2, v202
	global_load_dwordx4 v[170:173], v[136:137], off
	global_load_dwordx4 v[166:169], v[134:135], off
	global_load_dwordx4 v[186:189], v[134:135], off offset:128
	global_load_dwordx4 v[206:209], v[132:133], off
	global_load_dwordx4 v[210:213], v[132:133], off offset:128
	global_load_dwordx4 v[214:217], v205, s[22:23]
	v_add_u32_e32 v130, 0x10000, v205
	global_load_dwordx4 v[218:221], v130, s[22:23]
	global_load_dwordx4 v[222:225], v[136:137], off offset:128
	global_load_dwordx4 v[226:229], v205, s[22:23] offset:128
	v_add_u32_e32 v204, 0x10080, v205
	global_load_dwordx4 v[230:233], v204, s[22:23]
	v_add_u32_e32 v130, 0x20000, v205
	v_add_u32_e32 v154, 0x30000, v205
	v_add_u32_e32 v184, 0x20080, v205
	v_add_u32_e32 v182, 0x30080, v205
	global_load_dwordx4 v[142:145], v130, s[22:23]
	global_load_dwordx4 v[138:141], v154, s[22:23]
	global_load_dwordx4 v[134:137], v184, s[22:23]
	s_nop 0
	global_load_dwordx4 v[130:133], v182, s[22:23]
	ds_write_b128 v200, v[126:129]
	ds_write_b128 v200, v[122:125] offset:64
	v_and_b32_e32 v127, 64, v199
	ds_read_b128 v[122:125], v201
	ds_read_b128 v[234:237], v201 offset:1152
	v_xor_b32_e32 v126, 8, v199
	v_add_u32_e32 v183, 64, v127
	v_cmp_lt_i32_e32 vcc, v126, v183
	v_add_u32_e32 v185, 0x4000, v202
	v_lshlrev_b32_e32 v238, 2, v185
	v_cndmask_b32_e32 v126, v199, v126, vcc
	v_lshlrev_b32_e32 v203, 2, v126
	s_lshl_b64 s[16:17], s[8:9], 20
	s_add_u32 s20, s93, s16
	s_addc_u32 s21, s92, s17
	v_mbcnt_lo_u32_b32 v250, -1, 0
	v_mbcnt_hi_u32_b32 v250, -1, v250
	v_and_b32_e32 v249, 15, v250
	v_lshrrev_b32_e32 v251, 3, v250
	v_sub_u32_e32 v249, v249, v251
	v_lshlrev_b32_e32 v249, 13, v249
	v_bfe_u32 v251, v250, 4, 1
	v_lshl_add_u32 v249, v251, 7, v249
	v_and_b32_e32 v251, 7, v250
	v_lshlrev_b32_e32 v251, 4, v251
	v_sub_u32_e32 v249, v249, v251
	v_add_u32_e32 v249, v249, v205
	v_add_u32_e32 v250, 0x40000, v249
	global_load_dword v251, v250, s[22:23]
	v_add_u32_e32 v250, 0x60000, v249
	global_load_dword v251, v250, s[22:23]
	s_waitcnt vmcnt(2)
	v_pk_mul_f32 v[180:181], v[166:167], 0.5 op_sel_hi:[1,0]
	v_pk_mul_f32 v[176:177], v[168:169], 0.5 op_sel_hi:[1,0]
	v_pk_add_f32 v[126:127], v[208:209], 1.0 op_sel_hi:[1,0]
	v_pk_add_f32 v[128:129], v[206:207], 1.0 op_sel_hi:[1,0]
	v_pk_mul_f32 v[174:175], v[172:173], v[126:127]
	v_pk_mul_f32 v[178:179], v[170:171], v[128:129]
	s_waitcnt lgkmcnt(1)
	v_pk_fma_f32 v[126:127], v[180:181], v[122:123], v[214:215]
	s_waitcnt lgkmcnt(0)
	v_pk_fma_f32 v[122:123], v[180:181], v[234:235], v[218:219]
	v_pk_mul_f32 v[168:169], v[186:187], 0.5 op_sel_hi:[1,0]
	v_pk_fma_f32 v[128:129], v[176:177], v[124:125], v[216:217]
	v_pk_fma_f32 v[124:125], v[176:177], v[236:237], v[220:221]
	v_pk_mul_f32 v[186:187], v[178:179], v[122:123]
	v_pk_mul_f32 v[166:167], v[188:189], 0.5 op_sel_hi:[1,0]
	global_store_dwordx4 v205, v[126:129], s[22:23] nt
	v_pk_mul_f32 v[170:171], v[174:175], v[128:129]
	v_pk_mul_f32 v[172:173], v[178:179], v[126:127]
	v_pk_mul_f32 v[206:207], v[174:175], v[124:125]
	v_cvt_pk_bf16_f32 v188, v172, v173
	v_cvt_pk_bf16_f32 v189, v170, v171
	global_store_dwordx4 v238, v[122:125], s[22:23] nt
	v_cvt_pk_bf16_f32 v186, v186, v187
	v_cvt_pk_bf16_f32 v187, v206, v207
	ds_write_b128 v200, v[118:121]
	ds_write_b128 v200, v[114:117] offset:64
	ds_read_b128 v[114:117], v201
	ds_read_b128 v[206:209], v201 offset:1152
	v_pk_add_f32 v[190:191], v[212:213], 1.0 op_sel_hi:[1,0]
	v_pk_add_f32 v[118:119], v[210:211], 1.0 op_sel_hi:[1,0]
	v_pk_mul_f32 v[170:171], v[224:225], v[190:191]
	v_pk_mul_f32 v[172:173], v[222:223], v[118:119]
	s_waitcnt lgkmcnt(1)
	v_pk_fma_f32 v[120:121], v[166:167], v[116:117], v[228:229]
	v_pk_fma_f32 v[118:119], v[168:169], v[114:115], v[226:227]
	s_waitcnt lgkmcnt(0)
	v_pk_fma_f32 v[114:115], v[168:169], v[206:207], v[230:231]
	v_pk_mul_f32 v[190:191], v[170:171], v[120:121]
	v_pk_mul_f32 v[206:207], v[172:173], v[118:119]
	global_store_dwordx4 v205, v[118:121], s[22:23] offset:128 nt
	v_cvt_pk_bf16_f32 v206, v206, v207
	v_cvt_pk_bf16_f32 v191, v190, v191
	ds_bpermute_b32 v190, v203, v206
	ds_bpermute_b32 v191, v203, v191
	v_pk_fma_f32 v[116:117], v[166:167], v[208:209], v[232:233]
	v_pk_mul_f32 v[206:207], v[172:173], v[114:115]
	global_store_dwordx4 v204, v[114:117], s[22:23] nt
	v_cvt_pk_bf16_f32 v204, v206, v207
	v_lshlrev_b32_e32 v207, 1, v202
	v_pk_mul_f32 v[208:209], v[170:171], v[116:117]
	s_nop 0
	v_cvt_pk_bf16_f32 v206, v208, v209
	s_and_saveexec_b64 s[16:17], s[40:41]
	s_xor_b64 s[16:17], exec, s[16:17]
	s_cbranch_execz .LBB0_1600
	v_lshlrev_b32_e32 v207, 1, v202
	v_add_u32_e32 v208, 0xfffff040, v207
	s_waitcnt lgkmcnt(0)
	global_store_dwordx2 v208, v[190:191], s[20:21]

; #define LAS __attribute__((address_space(3)))
; __device__ __forceinline__ unsigned cvt_pk_bf16(float lo, float hi) { unsigned r; asm volatile("v_cvt_pk_bf16_f32 %0, %1, %2" : "=v"(r) : "v"(lo), "v"(hi)); return r; }
; #define ERN_EOFF(q, m) (eb + (unsigned)((((q) & 1) * HALF + (m) * 16) * DM + ERN_COL((q) >> 1)))
; #define ERN_LOADX(q) do { _Pragma("unroll") for (int m = 0; m < 4; ++m) xb[(q) & 1][m] = *(const f32x4*)((const char*)xi + 4u * ERN_EOFF(q, m)); } while (0)
;     __device__ __forceinline__ void operator()(const f32x4 (&acc)[2][2][4][2], const Unit& u, int wr, int wc, int fr, int fq) const {
;     ...
;         for (int g = 0; g < 8; ++g) { const int ai = g >> 2, m = g & 3;
;             if (g + 1 < 8) ERN_LOADX(g + 1);
;             float sq0 = 0.f, sq1 = 0.f; u32x2 hw[2][2];
; #pragma unroll
;             for (int bj = 0; bj < 2; ++bj) {
;                 *(LAS f32x4*)(st + wr_off) = acc[ai][bj][m][0]; *(LAS f32x4*)(st + wr_off + 64) = acc[ai][bj][m][1];
;                 const f32x4 a0 = *(const LAS f32x4*)(st + rd_off), a1 = *(const LAS f32x4*)(st + rd_off + 8 * 144);
;                 { const f32x4 xv = xb[g & 1][bj][0] + gv[bj] * a0; __builtin_nontemporal_store(xv, (f32x4*)((char*)xo + 4u * ERN_EOFF(g, bj, 0)));
;                   sq0 += (xv.x * xv.x + xv.y * xv.y) + (xv.z * xv.z + xv.w * xv.w);
;                   const f32x4 hv = xv * gsn[bj]; hw[bj][0].x = cvt_pk_bf16(hv.x, hv.y); hw[bj][0].y = cvt_pk_bf16(hv.z, hv.w); }
;                 { const f32x4 xv = xb[g & 1][bj][1] + gv[bj] * a1; __builtin_nontemporal_store(xv, (f32x4*)((char*)xo + 4u * ERN_EOFF(g, bj, 1)));
;                   sq1 += (xv.x * xv.x + xv.y * xv.y) + (xv.z * xv.z + xv.w * xv.w);
;                   const f32x4 hv = xv * gsn[bj]; hw[bj][1].x = cvt_pk_bf16(hv.x, hv.y); hw[bj][1].y = cvt_pk_bf16(hv.z, hv.w); }
;             }
;             if (!NOH && !PLAIN) {
; #pragma unroll
;                 for (int rh = 0; rh < 2; ++rh) { u32x2 rv; rv.x = __shfl_xor(hw[1][rh].x, 8); rv.y = __shfl_xor(hw[1][rh].y, 8);
;                     const unsigned e0 = ERN_EOFF(g, 0, rh);
;                     const unsigned ee = odd ? (e0 - DM + 32) : e0, eo2 = odd ? e0 : (e0 + DM + 32);
;                     *(u32x2*)((char*)ho + 2u * ee) = odd ? rv : hw[0][rh];
;                     *(u32x2*)((char*)ho + 2u * eo2) = odd ? hw[0][rh] : rv; }
.LBB0_1608:
	s_or_b64 exec, exec, s[16:17]
	v_lshl_add_u64 v[206:207], s[22:23], 0, v[154:155]
	v_add_u32_e32 v114, 0x40000, v205
	v_add_u32_e32 v154, 0x50000, v205
	v_add_u32_e32 v186, 0x40080, v205
	global_load_dwordx4 v[122:125], v154, s[22:23]
	global_load_dwordx4 v[118:121], v186, s[22:23]
	v_add_u32_e32 v188, 0x50080, v205
	global_load_dwordx4 v[126:129], v114, s[22:23]
	s_waitcnt lgkmcnt(0)
	global_load_dwordx4 v[114:117], v188, s[22:23]
	v_add_u32_e32 v250, 0x100000, v249
	global_load_dword v251, v250, s[22:23]
	ds_write_b128 v200, v[110:113]
	ds_write_b128 v200, v[106:109] offset:64
	ds_read_b128 v[106:109], v201
	ds_read_b128 v[110:113], v201 offset:1152
	v_mov_b32_e32 v185, v155
	v_mov_b32_e32 v183, v155
	v_lshl_add_u64 v[182:183], s[22:23], 0, v[182:183]
	s_waitcnt lgkmcnt(1)
	v_pk_fma_f32 v[108:109], v[176:177], v[108:109], v[144:145]
	v_add_u32_e32 v144, 0x8000, v202
	v_pk_fma_f32 v[106:107], v[180:181], v[106:107], v[142:143]
	v_lshlrev_b32_e32 v142, 2, v144
	s_waitcnt lgkmcnt(0)
	v_pk_fma_f32 v[110:111], v[180:181], v[110:111], v[138:139]
	global_store_dwordx4 v142, v[106:109], s[22:23] nt
	v_pk_mul_f32 v[142:143], v[178:179], v[106:107]
	v_pk_fma_f32 v[112:113], v[176:177], v[112:113], v[140:141]
	v_pk_mul_f32 v[138:139], v[178:179], v[110:111]
	v_pk_mul_f32 v[208:209], v[174:175], v[108:109]
	v_cvt_pk_bf16_f32 v142, v142, v143
	v_pk_mul_f32 v[140:141], v[174:175], v[112:113]
	v_cvt_pk_bf16_f32 v143, v208, v209
	global_store_dwordx4 v[206:207], v[110:113], off nt
	v_cvt_pk_bf16_f32 v138, v138, v139
	v_cvt_pk_bf16_f32 v139, v140, v141
	ds_write_b128 v200, v[102:105]
	ds_write_b128 v200, v[98:101] offset:64
	ds_read_b128 v[98:101], v201
	ds_read_b128 v[102:105], v201 offset:1152
	v_lshl_add_u64 v[140:141], s[22:23], 0, v[184:185]
	s_waitcnt lgkmcnt(1)
	v_pk_fma_f32 v[98:99], v[168:169], v[98:99], v[134:135]
	v_pk_fma_f32 v[100:101], v[166:167], v[100:101], v[136:137]
	v_pk_mul_f32 v[136:137], v[172:173], v[98:99]
	global_store_dwordx4 v[140:141], v[98:101], off nt
	v_pk_mul_f32 v[134:135], v[170:171], v[100:101]
	v_cvt_pk_bf16_f32 v136, v136, v137
	s_waitcnt lgkmcnt(0)
	v_pk_fma_f32 v[102:103], v[168:169], v[102:103], v[130:131]
	v_cvt_pk_bf16_f32 v137, v134, v135
	ds_bpermute_b32 v130, v203, v136
	ds_bpermute_b32 v131, v203, v137
	v_pk_fma_f32 v[104:105], v[166:167], v[104:105], v[132:133]
	v_pk_mul_f32 v[132:133], v[172:173], v[102:103]
	v_pk_mul_f32 v[134:135], v[170:171], v[104:105]
	global_store_dwordx4 v[182:183], v[102:105], off nt
	v_cvt_pk_bf16_f32 v132, v132, v133
	v_cvt_pk_bf16_f32 v133, v134, v135
	v_lshlrev_b32_e32 v134, 1, v144
	s_and_saveexec_b64 s[16:17], s[40:41]
	s_xor_b64 s[16:17], exec, s[16:17]
	s_cbranch_execz .LBB0_1610
	v_lshlrev_b32_e32 v134, 1, v144
	v_add_u32_e32 v135, 0xfffff040, v134
	s_waitcnt lgkmcnt(0)
	global_store_dwordx2 v135, v[130:131], s[20:21]

; #define LAS __attribute__((address_space(3)))
; __device__ __forceinline__ unsigned cvt_pk_bf16(float lo, float hi) { unsigned r; asm volatile("v_cvt_pk_bf16_f32 %0, %1, %2" : "=v"(r) : "v"(lo), "v"(hi)); return r; }
; #define ERN_EOFF(q, m) (eb + (unsigned)((((q) & 1) * HALF + (m) * 16) * DM + ERN_COL((q) >> 1)))
; #define ERN_LOADX(q) do { _Pragma("unroll") for (int m = 0; m < 4; ++m) xb[(q) & 1][m] = *(const f32x4*)((const char*)xi + 4u * ERN_EOFF(q, m)); } while (0)
;     __device__ __forceinline__ void operator()(const f32x4 (&acc)[2][2][4][2], const Unit& u, int wr, int wc, int fr, int fq) const {
;     ...
;         for (int g = 0; g < 8; ++g) { const int ai = g >> 2, m = g & 3;
;             if (g + 1 < 8) ERN_LOADX(g + 1);
;             float sq0 = 0.f, sq1 = 0.f; u32x2 hw[2][2];
; #pragma unroll
;             for (int bj = 0; bj < 2; ++bj) {
;                 *(LAS f32x4*)(st + wr_off) = acc[ai][bj][m][0]; *(LAS f32x4*)(st + wr_off + 64) = acc[ai][bj][m][1];
;                 const f32x4 a0 = *(const LAS f32x4*)(st + rd_off), a1 = *(const LAS f32x4*)(st + rd_off + 8 * 144);
;                 { const f32x4 xv = xb[g & 1][bj][0] + gv[bj] * a0; __builtin_nontemporal_store(xv, (f32x4*)((char*)xo + 4u * ERN_EOFF(g, bj, 0)));
;                   sq0 += (xv.x * xv.x + xv.y * xv.y) + (xv.z * xv.z + xv.w * xv.w);
;                   const f32x4 hv = xv * gsn[bj]; hw[bj][0].x = cvt_pk_bf16(hv.x, hv.y); hw[bj][0].y = cvt_pk_bf16(hv.z, hv.w); }
;                 { const f32x4 xv = xb[g & 1][bj][1] + gv[bj] * a1; __builtin_nontemporal_store(xv, (f32x4*)((char*)xo + 4u * ERN_EOFF(g, bj, 1)));
;                   sq1 += (xv.x * xv.x + xv.y * xv.y) + (xv.z * xv.z + xv.w * xv.w);
;                   const f32x4 hv = xv * gsn[bj]; hw[bj][1].x = cvt_pk_bf16(hv.x, hv.y); hw[bj][1].y = cvt_pk_bf16(hv.z, hv.w); }
;             }
;             if (!NOH && !PLAIN) {
; #pragma unroll
;                 for (int rh = 0; rh < 2; ++rh) { u32x2 rv; rv.x = __shfl_xor(hw[1][rh].x, 8); rv.y = __shfl_xor(hw[1][rh].y, 8);
;                     const unsigned e0 = ERN_EOFF(g, 0, rh);
;                     const unsigned ee = odd ? (e0 - DM + 32) : e0, eo2 = odd ? e0 : (e0 + DM + 32);
;                     *(u32x2*)((char*)ho + 2u * ee) = odd ? rv : hw[0][rh];
;                     *(u32x2*)((char*)ho + 2u * eo2) = odd ? hw[0][rh] : rv; }
.LBB0_1618:
	s_or_b64 exec, exec, s[16:17]
	v_lshl_add_u64 v[134:135], s[22:23], 0, v[154:155]
	v_add_u32_e32 v98, 0x60000, v205
	v_add_u32_e32 v154, 0x70000, v205
	v_add_u32_e32 v130, 0x60080, v205
	global_load_dwordx4 v[106:109], v154, s[22:23]
	global_load_dwordx4 v[102:105], v130, s[22:23]
	v_add_u32_e32 v132, 0x70080, v205
	global_load_dwordx4 v[110:113], v98, s[22:23]
	s_waitcnt lgkmcnt(0)
	global_load_dwordx4 v[98:101], v132, s[22:23]
	v_add_u32_e32 v250, 0x120000, v249
	global_load_dword v251, v250, s[22:23]
	ds_write_b128 v200, v[94:97]
	ds_write_b128 v200, v[90:93] offset:64
	ds_read_b128 v[90:93], v201
	ds_read_b128 v[94:97], v201 offset:1152
	v_mov_b32_e32 v187, v155
	v_mov_b32_e32 v189, v155
	s_waitcnt vmcnt(11) lgkmcnt(1)
	v_pk_fma_f32 v[92:93], v[176:177], v[92:93], v[128:129]
	v_add_u32_e32 v128, 0x10000, v202
	v_pk_fma_f32 v[90:91], v[180:181], v[90:91], v[126:127]
	v_lshlrev_b32_e32 v126, 2, v128
	s_waitcnt lgkmcnt(0)
	v_pk_fma_f32 v[94:95], v[180:181], v[94:95], v[122:123]
	global_store_dwordx4 v126, v[90:93], s[22:23] nt
	v_pk_mul_f32 v[126:127], v[178:179], v[90:91]
	v_pk_fma_f32 v[96:97], v[176:177], v[96:97], v[124:125]
	v_pk_mul_f32 v[122:123], v[178:179], v[94:95]
	v_pk_mul_f32 v[136:137], v[174:175], v[92:93]
	v_cvt_pk_bf16_f32 v126, v126, v127
	v_pk_mul_f32 v[124:125], v[174:175], v[96:97]
	v_cvt_pk_bf16_f32 v127, v136, v137
	global_store_dwordx4 v[134:135], v[94:97], off nt
	v_cvt_pk_bf16_f32 v122, v122, v123
	v_cvt_pk_bf16_f32 v123, v124, v125
	ds_write_b128 v200, v[86:89]
	ds_write_b128 v200, v[82:85] offset:64
	ds_read_b128 v[82:85], v201
	ds_read_b128 v[86:89], v201 offset:1152
	v_lshl_add_u64 v[124:125], s[22:23], 0, v[186:187]
	v_lshl_add_u64 v[134:135], s[22:23], 0, v[188:189]
	s_waitcnt lgkmcnt(1)
	v_pk_fma_f32 v[82:83], v[168:169], v[82:83], v[118:119]
	v_pk_fma_f32 v[84:85], v[166:167], v[84:85], v[120:121]
	v_pk_mul_f32 v[120:121], v[172:173], v[82:83]
	global_store_dwordx4 v[124:125], v[82:85], off nt
	v_pk_mul_f32 v[118:119], v[170:171], v[84:85]
	v_cvt_pk_bf16_f32 v120, v120, v121
	s_waitcnt vmcnt(13) lgkmcnt(0)
	v_pk_fma_f32 v[86:87], v[168:169], v[86:87], v[114:115]
	v_cvt_pk_bf16_f32 v121, v118, v119
	ds_bpermute_b32 v114, v203, v120
	ds_bpermute_b32 v115, v203, v121
	v_pk_fma_f32 v[88:89], v[166:167], v[88:89], v[116:117]
	v_pk_mul_f32 v[116:117], v[172:173], v[86:87]
	v_pk_mul_f32 v[118:119], v[170:171], v[88:89]
	global_store_dwordx4 v[134:135], v[86:89], off nt
	v_cvt_pk_bf16_f32 v116, v116, v117
	v_cvt_pk_bf16_f32 v117, v118, v119
	v_lshlrev_b32_e32 v118, 1, v128
	s_and_saveexec_b64 s[16:17], s[40:41]
	s_xor_b64 s[16:17], exec, s[16:17]
	s_cbranch_execz .LBB0_1620
	v_lshlrev_b32_e32 v118, 1, v128
	v_add_u32_e32 v119, 0xfffff040, v118
	s_waitcnt lgkmcnt(0)
	global_store_dwordx2 v119, v[114:115], s[20:21]

; #define LAS __attribute__((address_space(3)))
; __device__ __forceinline__ unsigned cvt_pk_bf16(float lo, float hi) { unsigned r; asm volatile("v_cvt_pk_bf16_f32 %0, %1, %2" : "=v"(r) : "v"(lo), "v"(hi)); return r; }
; #define ERN_EOFF(q, m) (eb + (unsigned)((((q) & 1) * HALF + (m) * 16) * DM + ERN_COL((q) >> 1)))
; #define ERN_LOADX(q) do { _Pragma("unroll") for (int m = 0; m < 4; ++m) xb[(q) & 1][m] = *(const f32x4*)((const char*)xi + 4u * ERN_EOFF(q, m)); } while (0)
;     __device__ __forceinline__ void operator()(const f32x4 (&acc)[2][2][4][2], const Unit& u, int wr, int wc, int fr, int fq) const {
;     ...
;         for (int g = 0; g < 8; ++g) { const int ai = g >> 2, m = g & 3;
;             if (g + 1 < 8) ERN_LOADX(g + 1);
;             float sq0 = 0.f, sq1 = 0.f; u32x2 hw[2][2];
; #pragma unroll
;             for (int bj = 0; bj < 2; ++bj) {
;                 *(LAS f32x4*)(st + wr_off) = acc[ai][bj][m][0]; *(LAS f32x4*)(st + wr_off + 64) = acc[ai][bj][m][1];
;                 const f32x4 a0 = *(const LAS f32x4*)(st + rd_off), a1 = *(const LAS f32x4*)(st + rd_off + 8 * 144);
;                 { const f32x4 xv = xb[g & 1][bj][0] + gv[bj] * a0; __builtin_nontemporal_store(xv, (f32x4*)((char*)xo + 4u * ERN_EOFF(g, bj, 0)));
;                   sq0 += (xv.x * xv.x + xv.y * xv.y) + (xv.z * xv.z + xv.w * xv.w);
;                   const f32x4 hv = xv * gsn[bj]; hw[bj][0].x = cvt_pk_bf16(hv.x, hv.y); hw[bj][0].y = cvt_pk_bf16(hv.z, hv.w); }
;                 { const f32x4 xv = xb[g & 1][bj][1] + gv[bj] * a1; __builtin_nontemporal_store(xv, (f32x4*)((char*)xo + 4u * ERN_EOFF(g, bj, 1)));
;                   sq1 += (xv.x * xv.x + xv.y * xv.y) + (xv.z * xv.z + xv.w * xv.w);
;                   const f32x4 hv = xv * gsn[bj]; hw[bj][1].x = cvt_pk_bf16(hv.x, hv.y); hw[bj][1].y = cvt_pk_bf16(hv.z, hv.w); }
;             }
;             if (!NOH && !PLAIN) {
; #pragma unroll
;                 for (int rh = 0; rh < 2; ++rh) { u32x2 rv; rv.x = __shfl_xor(hw[1][rh].x, 8); rv.y = __shfl_xor(hw[1][rh].y, 8);
;                     const unsigned e0 = ERN_EOFF(g, 0, rh);
;                     const unsigned ee = odd ? (e0 - DM + 32) : e0, eo2 = odd ? e0 : (e0 + DM + 32);
;                     *(u32x2*)((char*)ho + 2u * ee) = odd ? rv : hw[0][rh];
;                     *(u32x2*)((char*)ho + 2u * eo2) = odd ? hw[0][rh] : rv; }
.LBB0_1628:
	s_or_b64 exec, exec, s[16:17]
	v_lshl_add_u64 v[116:117], s[22:23], 0, v[154:155]
	v_add_u32_e32 v82, 0x100000, v205
	s_waitcnt lgkmcnt(1)
	v_add_u32_e32 v83, 0x110000, v205
	v_add_u32_e32 v154, 0x100080, v205
	global_load_dwordx4 v[94:97], v82, s[22:23]
	global_load_dwordx4 v[90:93], v83, s[22:23]
	v_add_u32_e32 v114, 0x110080, v205
	global_load_dwordx4 v[86:89], v154, s[22:23]
	s_waitcnt lgkmcnt(0)
	global_load_dwordx4 v[82:85], v114, s[22:23]
	v_add_u32_e32 v250, 0x140000, v249
	global_load_dword v251, v250, s[22:23]
	ds_write_b128 v200, v[78:81]
	ds_write_b128 v200, v[74:77] offset:64
	ds_read_b128 v[74:77], v201
	ds_read_b128 v[78:81], v201 offset:1152
	v_mov_b32_e32 v131, v155
	v_mov_b32_e32 v133, v155
	s_waitcnt vmcnt(11) lgkmcnt(1)
	v_pk_fma_f32 v[76:77], v[176:177], v[76:77], v[112:113]
	v_add_u32_e32 v112, 0x18000, v202
	v_pk_fma_f32 v[74:75], v[180:181], v[74:75], v[110:111]
	v_lshlrev_b32_e32 v110, 2, v112
	s_waitcnt lgkmcnt(0)
	v_pk_fma_f32 v[78:79], v[180:181], v[78:79], v[106:107]
	global_store_dwordx4 v110, v[74:77], s[22:23] nt
	v_pk_mul_f32 v[110:111], v[178:179], v[74:75]
	v_pk_fma_f32 v[80:81], v[176:177], v[80:81], v[108:109]
	v_pk_mul_f32 v[106:107], v[178:179], v[78:79]
	v_pk_mul_f32 v[118:119], v[174:175], v[76:77]
	v_cvt_pk_bf16_f32 v110, v110, v111
	v_pk_mul_f32 v[108:109], v[174:175], v[80:81]
	v_cvt_pk_bf16_f32 v111, v118, v119
	global_store_dwordx4 v[116:117], v[78:81], off nt
	v_cvt_pk_bf16_f32 v106, v106, v107
	v_cvt_pk_bf16_f32 v107, v108, v109
	ds_write_b128 v200, v[70:73]
	ds_write_b128 v200, v[66:69] offset:64
	ds_read_b128 v[66:69], v201
	ds_read_b128 v[70:73], v201 offset:1152
	v_lshl_add_u64 v[108:109], s[22:23], 0, v[130:131]
	v_lshl_add_u64 v[116:117], s[22:23], 0, v[132:133]
	s_waitcnt lgkmcnt(1)
	v_pk_fma_f32 v[66:67], v[168:169], v[66:67], v[102:103]
	v_pk_fma_f32 v[68:69], v[166:167], v[68:69], v[104:105]
	v_pk_mul_f32 v[104:105], v[172:173], v[66:67]
	global_store_dwordx4 v[108:109], v[66:69], off nt
	v_pk_mul_f32 v[102:103], v[170:171], v[68:69]
	v_cvt_pk_bf16_f32 v104, v104, v105
	s_waitcnt vmcnt(13) lgkmcnt(0)
	v_pk_fma_f32 v[70:71], v[168:169], v[70:71], v[98:99]
	v_cvt_pk_bf16_f32 v105, v102, v103
	ds_bpermute_b32 v98, v203, v104
	ds_bpermute_b32 v99, v203, v105
	v_pk_fma_f32 v[72:73], v[166:167], v[72:73], v[100:101]
	v_pk_mul_f32 v[100:101], v[172:173], v[70:71]
	v_pk_mul_f32 v[102:103], v[170:171], v[72:73]
	global_store_dwordx4 v[116:117], v[70:73], off nt
	v_cvt_pk_bf16_f32 v100, v100, v101
	v_cvt_pk_bf16_f32 v101, v102, v103
	v_lshlrev_b32_e32 v102, 1, v112
	s_and_saveexec_b64 s[16:17], s[40:41]
	s_xor_b64 s[16:17], exec, s[16:17]
	s_cbranch_execz .LBB0_1630
	v_lshlrev_b32_e32 v102, 1, v112
	v_add_u32_e32 v103, 0xfffff040, v102
	s_waitcnt lgkmcnt(0)
	global_store_dwordx2 v103, v[98:99], s[20:21]

; #define LAS __attribute__((address_space(3)))
; __device__ __forceinline__ unsigned cvt_pk_bf16(float lo, float hi) { unsigned r; asm volatile("v_cvt_pk_bf16_f32 %0, %1, %2" : "=v"(r) : "v"(lo), "v"(hi)); return r; }
; #define ERN_EOFF(q, m) (eb + (unsigned)((((q) & 1) * HALF + (m) * 16) * DM + ERN_COL((q) >> 1)))
; #define ERN_LOADX(q) do { _Pragma("unroll") for (int m = 0; m < 4; ++m) xb[(q) & 1][m] = *(const f32x4*)((const char*)xi + 4u * ERN_EOFF(q, m)); } while (0)
;     __device__ __forceinline__ void operator()(const f32x4 (&acc)[2][2][4][2], const Unit& u, int wr, int wc, int fr, int fq) const {
;     ...
;         for (int g = 0; g < 8; ++g) { const int ai = g >> 2, m = g & 3;
;             if (g + 1 < 8) ERN_LOADX(g + 1);
;             float sq0 = 0.f, sq1 = 0.f; u32x2 hw[2][2];
; #pragma unroll
;             for (int bj = 0; bj < 2; ++bj) {
;                 *(LAS f32x4*)(st + wr_off) = acc[ai][bj][m][0]; *(LAS f32x4*)(st + wr_off + 64) = acc[ai][bj][m][1];
;                 const f32x4 a0 = *(const LAS f32x4*)(st + rd_off), a1 = *(const LAS f32x4*)(st + rd_off + 8 * 144);
;                 { const f32x4 xv = xb[g & 1][bj][0] + gv[bj] * a0; __builtin_nontemporal_store(xv, (f32x4*)((char*)xo + 4u * ERN_EOFF(g, bj, 0)));
;                   sq0 += (xv.x * xv.x + xv.y * xv.y) + (xv.z * xv.z + xv.w * xv.w);
;                   const f32x4 hv = xv * gsn[bj]; hw[bj][0].x = cvt_pk_bf16(hv.x, hv.y); hw[bj][0].y = cvt_pk_bf16(hv.z, hv.w); }
;                 { const f32x4 xv = xb[g & 1][bj][1] + gv[bj] * a1; __builtin_nontemporal_store(xv, (f32x4*)((char*)xo + 4u * ERN_EOFF(g, bj, 1)));
;                   sq1 += (xv.x * xv.x + xv.y * xv.y) + (xv.z * xv.z + xv.w * xv.w);
;                   const f32x4 hv = xv * gsn[bj]; hw[bj][1].x = cvt_pk_bf16(hv.x, hv.y); hw[bj][1].y = cvt_pk_bf16(hv.z, hv.w); }
;             }
;             if (!NOH && !PLAIN) {
; #pragma unroll
;                 for (int rh = 0; rh < 2; ++rh) { u32x2 rv; rv.x = __shfl_xor(hw[1][rh].x, 8); rv.y = __shfl_xor(hw[1][rh].y, 8);
;                     const unsigned e0 = ERN_EOFF(g, 0, rh);
;                     const unsigned ee = odd ? (e0 - DM + 32) : e0, eo2 = odd ? e0 : (e0 + DM + 32);
;                     *(u32x2*)((char*)ho + 2u * ee) = odd ? rv : hw[0][rh];
;                     *(u32x2*)((char*)ho + 2u * eo2) = odd ? hw[0][rh] : rv; }
.LBB0_1638:
	s_or_b64 exec, exec, s[16:17]
	v_lshl_add_u64 v[104:105], s[22:23], 0, v[154:155]
	v_add_u32_e32 v154, 0x120000, v205
	v_add_u32_e32 v100, 0x120080, v205
	v_add_u32_e32 v102, 0x130000, v205
	global_load_dwordx4 v[78:81], v154, s[22:23]
	global_load_dwordx4 v[74:77], v102, s[22:23]
	v_add_u32_e32 v98, 0x130080, v205
	global_load_dwordx4 v[70:73], v100, s[22:23]
	s_waitcnt lgkmcnt(0)
	global_load_dwordx4 v[66:69], v98, s[22:23]
	v_add_u32_e32 v250, 0x160000, v249
	global_load_dword v251, v250, s[22:23]
	ds_write_b128 v200, v[62:65]
	ds_write_b128 v200, v[58:61] offset:64
	ds_read_b128 v[58:61], v201
	ds_read_b128 v[62:65], v201 offset:1152
	v_mov_b32_e32 v115, v155
	s_waitcnt vmcnt(13) lgkmcnt(1)
	v_pk_fma_f32 v[60:61], v[176:177], v[60:61], v[96:97]
	v_add_u32_e32 v96, 0x40000, v202
	v_pk_fma_f32 v[58:59], v[180:181], v[58:59], v[94:95]
	v_lshlrev_b32_e32 v94, 2, v96
	s_waitcnt vmcnt(12) lgkmcnt(0)
	v_pk_fma_f32 v[64:65], v[176:177], v[64:65], v[92:93]
	v_add_u32_e32 v92, 0x44000, v202
	global_store_dwordx4 v94, v[58:61], s[22:23] nt
	v_pk_mul_f32 v[94:95], v[178:179], v[58:59]
	v_pk_fma_f32 v[62:63], v[180:181], v[62:63], v[90:91]
	v_lshlrev_b32_e32 v90, 2, v92
	v_pk_mul_f32 v[106:107], v[174:175], v[60:61]
	v_cvt_pk_bf16_f32 v94, v94, v95
	s_nop 0
	v_cvt_pk_bf16_f32 v95, v106, v107
	global_store_dwordx4 v90, v[62:65], s[22:23] nt
	v_pk_mul_f32 v[90:91], v[178:179], v[62:63]
	v_pk_mul_f32 v[106:107], v[174:175], v[64:65]
	v_cvt_pk_bf16_f32 v90, v90, v91
	s_nop 0
	v_cvt_pk_bf16_f32 v91, v106, v107
	ds_write_b128 v200, v[54:57]
	ds_write_b128 v200, v[50:53] offset:64
	ds_read_b128 v[50:53], v201
	ds_read_b128 v[54:57], v201 offset:1152
	v_lshl_add_u64 v[106:107], s[22:23], 0, v[114:115]
	s_waitcnt vmcnt(13) lgkmcnt(1)
	v_pk_fma_f32 v[50:51], v[168:169], v[50:51], v[86:87]
	v_pk_fma_f32 v[52:53], v[166:167], v[52:53], v[88:89]
	v_pk_mul_f32 v[88:89], v[172:173], v[50:51]
	global_store_dwordx4 v[104:105], v[50:53], off nt
	v_pk_mul_f32 v[86:87], v[170:171], v[52:53]
	v_cvt_pk_bf16_f32 v88, v88, v89
	s_waitcnt vmcnt(13) lgkmcnt(0)
	v_pk_fma_f32 v[54:55], v[168:169], v[54:55], v[82:83]
	v_cvt_pk_bf16_f32 v89, v86, v87
	ds_bpermute_b32 v82, v203, v88
	ds_bpermute_b32 v83, v203, v89
	v_pk_fma_f32 v[56:57], v[166:167], v[56:57], v[84:85]
	v_pk_mul_f32 v[84:85], v[172:173], v[54:55]
	v_pk_mul_f32 v[86:87], v[170:171], v[56:57]
	global_store_dwordx4 v[106:107], v[54:57], off nt
	v_cvt_pk_bf16_f32 v84, v84, v85
	v_cvt_pk_bf16_f32 v85, v86, v87
	v_lshlrev_b32_e32 v86, 1, v96
	s_and_saveexec_b64 s[16:17], s[40:41]
	s_xor_b64 s[16:17], exec, s[16:17]
	s_cbranch_execz .LBB0_1640
	v_lshlrev_b32_e32 v86, 1, v96
	v_add_u32_e32 v87, 0xfffff040, v86
	s_waitcnt lgkmcnt(0)
	global_store_dwordx2 v87, v[82:83], s[20:21]

; #define LAS __attribute__((address_space(3)))
;     __device__ __forceinline__ void operator()(const f32x4 (&acc)[2][2][4][2], const Unit& u, int wr, int wc, int fr, int fq) const {
;         const int s = u.pm >> 5, lane = fq * 16 + fr, rr = lane >> 3, pc = lane & 7;
;         const float* __restrict__ xi = xin + (size_t)u.pm * BM * DM; float* __restrict__ xo = xout + (size_t)u.pm * BM * DM; bf16_t* __restrict__ ho = Hn + (size_t)u.pm * BM * DM;
;         LAS unsigned char* st = lds_epi + (wr * 4 + wc) * 2304;
;         LAS float* sst = (LAS float*)(lds_epi + 18432 + (wr * 4 + wc) * 512);
;         const int colr = u.pn * BM + wc * 64 + 4 * pc;
;         const unsigned eb = (unsigned)((wr * 64 + rr) * DM + colr);
;         f32x4 gv[2], gsn[2];
; #pragma unroll
;         for (int bj = 0; bj < 2; ++bj) { gv[bj] = *(const f32x4*)(gate + (size_t)s * MODW + colr + bj * 32) * (0.5f * GS2);
;             if (!PLAIN) gsn[bj] = *(const f32x4*)(gnext + colr + bj * 32) * (*(const f32x4*)(scnext + (size_t)s * MODW + colr + bj * 32) + 1.0f); else gsn[bj] = gv[bj]; }
;         const unsigned wr_off = (unsigned)(fr * 144 + 16 * fq), rd_off = (unsigned)(rr * 144 + pc * 16);
;         const bool odd = (rr & 1) != 0;
;         f32x4 xb[2][2][2];
;     ...
;         ERN_LOADX(0);
; #pragma unroll
;         for (int g = 0; g < 8; ++g) { const int ai = g >> 2, m = g & 3;
;             if (g + 1 < 8) ERN_LOADX(g + 1);
;             float sq0 = 0.f, sq1 = 0.f; u32x2 hw[2][2];
; #pragma unroll
;             for (int bj = 0; bj < 2; ++bj) {
;                 *(LAS f32x4*)(st + wr_off) = acc[ai][bj][m][0]; *(LAS f32x4*)(st + wr_off + 64) = acc[ai][bj][m][1];
;                 const f32x4 a0 = *(const LAS f32x4*)(st + rd_off), a1 = *(const LAS f32x4*)(st + rd_off + 8 * 144);
;                 { const f32x4 xv = xb[g & 1][bj][0] + gv[bj] * a0; __builtin_nontemporal_store(xv, (f32x4*)((char*)xo + 4u * ERN_EOFF(g, bj, 0)));
;                   sq0 += (xv.x * xv.x + xv.y * xv.y) + (xv.z * xv.z + xv.w * xv.w);
;                   const f32x4 hv = xv * gsn[bj]; hw[bj][0].x = cvt_pk_bf16(hv.x, hv.y); hw[bj][0].y = cvt_pk_bf16(hv.z, hv.w); }
;                 { const f32x4 xv = xb[g & 1][bj][1] + gv[bj] * a1; __builtin_nontemporal_store(xv, (f32x4*)((char*)xo + 4u * ERN_EOFF(g, bj, 1)));
;                   sq1 += (xv.x * xv.x + xv.y * xv.y) + (xv.z * xv.z + xv.w * xv.w);
.LBB0_1929:
	s_ashr_i32 s18, s4, 5
	s_ashr_i32 s5, s4, 31
	v_lshl_or_b32 v130, s0, 8, v192
	s_mul_i32 s20, s18, 0x12000
	s_mul_hi_i32 s0, s18, 0x12000
	s_add_u32 s18, s33, s20
	v_ashrrev_i32_e32 v131, 31, v130
	s_addc_u32 s19, s34, s0
	v_lshlrev_b64 v[132:133], 2, v[130:131]
	v_lshl_add_u64 v[134:135], s[18:19], 0, v[132:133]
	s_add_u32 s18, s35, s20
	s_addc_u32 s19, s36, s0
	v_lshl_add_u64 v[136:137], s[10:11], 0, v[132:133]
	v_lshl_add_u64 v[132:133], s[18:19], 0, v[132:133]
	s_lshl_b64 s[18:19], s[4:5], 21
	s_add_u32 s20, s90, s18
	v_add_u32_e32 v202, v130, v193
	s_addc_u32 s21, s91, s19
	v_lshlrev_b32_e32 v205, 2, v202
	global_load_dwordx4 v[170:173], v[136:137], off
	global_load_dwordx4 v[166:169], v[134:135], off
	global_load_dwordx4 v[186:189], v[134:135], off offset:128
	global_load_dwordx4 v[206:209], v[132:133], off
	global_load_dwordx4 v[210:213], v[132:133], off offset:128
	global_load_dwordx4 v[214:217], v205, s[20:21]
	v_add_u32_e32 v130, 0x10000, v205
	global_load_dwordx4 v[218:221], v130, s[20:21]
	global_load_dwordx4 v[222:225], v[136:137], off offset:128
	global_load_dwordx4 v[226:229], v205, s[20:21] offset:128
	v_add_u32_e32 v204, 0x10080, v205
	global_load_dwordx4 v[230:233], v204, s[20:21]
	v_add_u32_e32 v130, 0x20000, v205
	v_add_u32_e32 v154, 0x30000, v205
	v_add_u32_e32 v184, 0x20080, v205
	v_add_u32_e32 v182, 0x30080, v205
	global_load_dwordx4 v[142:145], v130, s[20:21]
	global_load_dwordx4 v[138:141], v154, s[20:21]
	global_load_dwordx4 v[134:137], v184, s[20:21]
	s_nop 0
	global_load_dwordx4 v[130:133], v182, s[20:21]
	ds_write_b128 v200, v[126:129]
	ds_write_b128 v200, v[122:125] offset:64
	v_and_b32_e32 v127, 64, v199
	ds_read_b128 v[122:125], v201
	ds_read_b128 v[234:237], v201 offset:1152
	v_xor_b32_e32 v126, 8, v199
	v_add_u32_e32 v183, 64, v127
	v_cmp_lt_i32_e32 vcc, v126, v183
	v_add_u32_e32 v185, 0x4000, v202
	v_lshlrev_b32_e32 v238, 2, v185
	v_cndmask_b32_e32 v126, v199, v126, vcc
	v_lshlrev_b32_e32 v203, 2, v126
	s_lshl_b64 s[18:19], s[4:5], 20
	s_add_u32 s18, s93, s18
	s_addc_u32 s19, s92, s19
	v_mbcnt_lo_u32_b32 v250, -1, 0
	v_mbcnt_hi_u32_b32 v250, -1, v250
	v_and_b32_e32 v249, 15, v250
	v_lshrrev_b32_e32 v251, 3, v250
	v_sub_u32_e32 v249, v249, v251
	v_lshlrev_b32_e32 v249, 13, v249
	v_bfe_u32 v251, v250, 4, 1
	v_lshl_add_u32 v249, v251, 7, v249
	v_and_b32_e32 v251, 7, v250
	v_lshlrev_b32_e32 v251, 4, v251
	v_sub_u32_e32 v249, v249, v251
	v_add_u32_e32 v249, v249, v205
	v_add_u32_e32 v250, 0x40000, v249
	global_load_dword v251, v250, s[20:21]
	v_add_u32_e32 v250, 0x60000, v249
	global_load_dword v251, v250, s[20:21]
	s_waitcnt vmcnt(2)
	v_pk_mul_f32 v[180:181], v[166:167], 0.5 op_sel_hi:[1,0]
	v_pk_mul_f32 v[176:177], v[168:169], 0.5 op_sel_hi:[1,0]
	v_pk_add_f32 v[126:127], v[208:209], 1.0 op_sel_hi:[1,0]
	v_pk_add_f32 v[128:129], v[206:207], 1.0 op_sel_hi:[1,0]
	v_pk_mul_f32 v[174:175], v[172:173], v[126:127]
	v_pk_mul_f32 v[178:179], v[170:171], v[128:129]
	s_waitcnt lgkmcnt(1)
	v_pk_fma_f32 v[126:127], v[180:181], v[122:123], v[214:215]
	s_waitcnt lgkmcnt(0)
	v_pk_fma_f32 v[122:123], v[180:181], v[234:235], v[218:219]
	v_pk_mul_f32 v[168:169], v[186:187], 0.5 op_sel_hi:[1,0]
	v_pk_fma_f32 v[128:129], v[176:177], v[124:125], v[216:217]
	v_pk_fma_f32 v[124:125], v[176:177], v[236:237], v[220:221]
	v_pk_mul_f32 v[186:187], v[178:179], v[122:123]
	v_pk_mul_f32 v[166:167], v[188:189], 0.5 op_sel_hi:[1,0]
	global_store_dwordx4 v205, v[126:129], s[20:21] nt
	v_pk_mul_f32 v[170:171], v[174:175], v[128:129]
	v_pk_mul_f32 v[172:173], v[178:179], v[126:127]
	v_pk_mul_f32 v[206:207], v[174:175], v[124:125]
	v_cvt_pk_bf16_f32 v188, v172, v173
	v_cvt_pk_bf16_f32 v189, v170, v171
	global_store_dwordx4 v238, v[122:125], s[20:21] nt
	v_cvt_pk_bf16_f32 v186, v186, v187
	v_cvt_pk_bf16_f32 v187, v206, v207
	ds_write_b128 v200, v[118:121]
	ds_write_b128 v200, v[114:117] offset:64
	ds_read_b128 v[114:117], v201
	ds_read_b128 v[206:209], v201 offset:1152
	v_pk_add_f32 v[190:191], v[212:213], 1.0 op_sel_hi:[1,0]
	v_pk_add_f32 v[118:119], v[210:211], 1.0 op_sel_hi:[1,0]
	v_pk_mul_f32 v[170:171], v[224:225], v[190:191]
	v_pk_mul_f32 v[172:173], v[222:223], v[118:119]
	s_waitcnt lgkmcnt(1)
	v_pk_fma_f32 v[120:121], v[166:167], v[116:117], v[228:229]
	v_pk_fma_f32 v[118:119], v[168:169], v[114:115], v[226:227]
	s_waitcnt lgkmcnt(0)
	v_pk_fma_f32 v[114:115], v[168:169], v[206:207], v[230:231]
	v_pk_mul_f32 v[190:191], v[170:171], v[120:121]
	v_pk_mul_f32 v[206:207], v[172:173], v[118:119]
	global_store_dwordx4 v205, v[118:121], s[20:21] offset:128 nt
	v_cvt_pk_bf16_f32 v206, v206, v207
	v_cvt_pk_bf16_f32 v191, v190, v191
	ds_bpermute_b32 v190, v203, v206
	ds_bpermute_b32 v191, v203, v191
	v_pk_fma_f32 v[116:117], v[166:167], v[208:209], v[232:233]
	v_pk_mul_f32 v[206:207], v[172:173], v[114:115]
	global_store_dwordx4 v204, v[114:117], s[20:21] nt
	v_cvt_pk_bf16_f32 v204, v206, v207
	v_lshlrev_b32_e32 v207, 1, v202
	v_pk_mul_f32 v[208:209], v[170:171], v[116:117]
	s_nop 0
	v_cvt_pk_bf16_f32 v206, v208, v209
	s_and_saveexec_b64 s[22:23], s[40:41]
	s_xor_b64 s[22:23], exec, s[22:23]
	s_cbranch_execz .LBB0_1931
	v_lshlrev_b32_e32 v207, 1, v202
	v_add_u32_e32 v208, 0xfffff040, v207
	s_waitcnt lgkmcnt(0)
	global_store_dwordx2 v208, v[190:191], s[18:19]

; #define LAS __attribute__((address_space(3)))
; __device__ __forceinline__ unsigned cvt_pk_bf16(float lo, float hi) { unsigned r; asm volatile("v_cvt_pk_bf16_f32 %0, %1, %2" : "=v"(r) : "v"(lo), "v"(hi)); return r; }
; #define ERN_EOFF(q, m) (eb + (unsigned)((((q) & 1) * HALF + (m) * 16) * DM + ERN_COL((q) >> 1)))
; #define ERN_LOADX(q) do { _Pragma("unroll") for (int m = 0; m < 4; ++m) xb[(q) & 1][m] = *(const f32x4*)((const char*)xi + 4u * ERN_EOFF(q, m)); } while (0)
;     __device__ __forceinline__ void operator()(const f32x4 (&acc)[2][2][4][2], const Unit& u, int wr, int wc, int fr, int fq) const {
;     ...
;         for (int g = 0; g < 8; ++g) { const int ai = g >> 2, m = g & 3;
;             if (g + 1 < 8) ERN_LOADX(g + 1);
;             float sq0 = 0.f, sq1 = 0.f; u32x2 hw[2][2];
; #pragma unroll
;             for (int bj = 0; bj < 2; ++bj) {
;                 *(LAS f32x4*)(st + wr_off) = acc[ai][bj][m][0]; *(LAS f32x4*)(st + wr_off + 64) = acc[ai][bj][m][1];
;                 const f32x4 a0 = *(const LAS f32x4*)(st + rd_off), a1 = *(const LAS f32x4*)(st + rd_off + 8 * 144);
;                 { const f32x4 xv = xb[g & 1][bj][0] + gv[bj] * a0; __builtin_nontemporal_store(xv, (f32x4*)((char*)xo + 4u * ERN_EOFF(g, bj, 0)));
;                   sq0 += (xv.x * xv.x + xv.y * xv.y) + (xv.z * xv.z + xv.w * xv.w);
;                   const f32x4 hv = xv * gsn[bj]; hw[bj][0].x = cvt_pk_bf16(hv.x, hv.y); hw[bj][0].y = cvt_pk_bf16(hv.z, hv.w); }
;                 { const f32x4 xv = xb[g & 1][bj][1] + gv[bj] * a1; __builtin_nontemporal_store(xv, (f32x4*)((char*)xo + 4u * ERN_EOFF(g, bj, 1)));
;                   sq1 += (xv.x * xv.x + xv.y * xv.y) + (xv.z * xv.z + xv.w * xv.w);
;                   const f32x4 hv = xv * gsn[bj]; hw[bj][1].x = cvt_pk_bf16(hv.x, hv.y); hw[bj][1].y = cvt_pk_bf16(hv.z, hv.w); }
;             }
;             if (!NOH && !PLAIN) {
; #pragma unroll
;                 for (int rh = 0; rh < 2; ++rh) { u32x2 rv; rv.x = __shfl_xor(hw[1][rh].x, 8); rv.y = __shfl_xor(hw[1][rh].y, 8);
;                     const unsigned e0 = ERN_EOFF(g, 0, rh);
;                     const unsigned ee = odd ? (e0 - DM + 32) : e0, eo2 = odd ? e0 : (e0 + DM + 32);
;                     *(u32x2*)((char*)ho + 2u * ee) = odd ? rv : hw[0][rh];
;                     *(u32x2*)((char*)ho + 2u * eo2) = odd ? hw[0][rh] : rv; }
.LBB0_1939:
	s_or_b64 exec, exec, s[22:23]
	v_lshl_add_u64 v[206:207], s[20:21], 0, v[154:155]
	v_add_u32_e32 v114, 0x40000, v205
	v_add_u32_e32 v154, 0x50000, v205
	v_add_u32_e32 v186, 0x40080, v205
	global_load_dwordx4 v[122:125], v154, s[20:21]
	global_load_dwordx4 v[118:121], v186, s[20:21]
	v_add_u32_e32 v188, 0x50080, v205
	global_load_dwordx4 v[126:129], v114, s[20:21]
	s_waitcnt lgkmcnt(0)
	global_load_dwordx4 v[114:117], v188, s[20:21]
	v_add_u32_e32 v250, 0x100000, v249
	global_load_dword v251, v250, s[20:21]
	ds_write_b128 v200, v[110:113]
	ds_write_b128 v200, v[106:109] offset:64
	ds_read_b128 v[106:109], v201
	ds_read_b128 v[110:113], v201 offset:1152
	v_mov_b32_e32 v185, v155
	v_mov_b32_e32 v183, v155
	v_lshl_add_u64 v[182:183], s[20:21], 0, v[182:183]
	s_waitcnt lgkmcnt(1)
	v_pk_fma_f32 v[108:109], v[176:177], v[108:109], v[144:145]
	v_add_u32_e32 v144, 0x8000, v202
	v_pk_fma_f32 v[106:107], v[180:181], v[106:107], v[142:143]
	v_lshlrev_b32_e32 v142, 2, v144
	s_waitcnt lgkmcnt(0)
	v_pk_fma_f32 v[110:111], v[180:181], v[110:111], v[138:139]
	global_store_dwordx4 v142, v[106:109], s[20:21] nt
	v_pk_mul_f32 v[142:143], v[178:179], v[106:107]
	v_pk_fma_f32 v[112:113], v[176:177], v[112:113], v[140:141]
	v_pk_mul_f32 v[138:139], v[178:179], v[110:111]
	v_pk_mul_f32 v[208:209], v[174:175], v[108:109]
	v_cvt_pk_bf16_f32 v142, v142, v143
	v_pk_mul_f32 v[140:141], v[174:175], v[112:113]
	v_cvt_pk_bf16_f32 v143, v208, v209
	global_store_dwordx4 v[206:207], v[110:113], off nt
	v_cvt_pk_bf16_f32 v138, v138, v139
	v_cvt_pk_bf16_f32 v139, v140, v141
	ds_write_b128 v200, v[102:105]
	ds_write_b128 v200, v[98:101] offset:64
	ds_read_b128 v[98:101], v201
	ds_read_b128 v[102:105], v201 offset:1152
	v_lshl_add_u64 v[140:141], s[20:21], 0, v[184:185]
	s_waitcnt lgkmcnt(1)
	v_pk_fma_f32 v[98:99], v[168:169], v[98:99], v[134:135]
	v_pk_fma_f32 v[100:101], v[166:167], v[100:101], v[136:137]
	v_pk_mul_f32 v[136:137], v[172:173], v[98:99]
	global_store_dwordx4 v[140:141], v[98:101], off nt
	v_pk_mul_f32 v[134:135], v[170:171], v[100:101]
	v_cvt_pk_bf16_f32 v136, v136, v137
	s_waitcnt lgkmcnt(0)
	v_pk_fma_f32 v[102:103], v[168:169], v[102:103], v[130:131]
	v_cvt_pk_bf16_f32 v137, v134, v135
	ds_bpermute_b32 v130, v203, v136
	ds_bpermute_b32 v131, v203, v137
	v_pk_fma_f32 v[104:105], v[166:167], v[104:105], v[132:133]
	v_pk_mul_f32 v[132:133], v[172:173], v[102:103]
	v_pk_mul_f32 v[134:135], v[170:171], v[104:105]
	global_store_dwordx4 v[182:183], v[102:105], off nt
	v_cvt_pk_bf16_f32 v132, v132, v133
	v_cvt_pk_bf16_f32 v133, v134, v135
	v_lshlrev_b32_e32 v134, 1, v144
	s_and_saveexec_b64 s[22:23], s[40:41]
	s_xor_b64 s[22:23], exec, s[22:23]
	s_cbranch_execz .LBB0_1941
	v_lshlrev_b32_e32 v134, 1, v144
	v_add_u32_e32 v135, 0xfffff040, v134
	s_waitcnt lgkmcnt(0)
	global_store_dwordx2 v135, v[130:131], s[18:19]

; #define LAS __attribute__((address_space(3)))
; __device__ __forceinline__ unsigned cvt_pk_bf16(float lo, float hi) { unsigned r; asm volatile("v_cvt_pk_bf16_f32 %0, %1, %2" : "=v"(r) : "v"(lo), "v"(hi)); return r; }
; #define ERN_EOFF(q, m) (eb + (unsigned)((((q) & 1) * HALF + (m) * 16) * DM + ERN_COL((q) >> 1)))
; #define ERN_LOADX(q) do { _Pragma("unroll") for (int m = 0; m < 4; ++m) xb[(q) & 1][m] = *(const f32x4*)((const char*)xi + 4u * ERN_EOFF(q, m)); } while (0)
;     __device__ __forceinline__ void operator()(const f32x4 (&acc)[2][2][4][2], const Unit& u, int wr, int wc, int fr, int fq) const {
;     ...
;         for (int g = 0; g < 8; ++g) { const int ai = g >> 2, m = g & 3;
;             if (g + 1 < 8) ERN_LOADX(g + 1);
;             float sq0 = 0.f, sq1 = 0.f; u32x2 hw[2][2];
; #pragma unroll
;             for (int bj = 0; bj < 2; ++bj) {
;                 *(LAS f32x4*)(st + wr_off) = acc[ai][bj][m][0]; *(LAS f32x4*)(st + wr_off + 64) = acc[ai][bj][m][1];
;                 const f32x4 a0 = *(const LAS f32x4*)(st + rd_off), a1 = *(const LAS f32x4*)(st + rd_off + 8 * 144);
;                 { const f32x4 xv = xb[g & 1][bj][0] + gv[bj] * a0; __builtin_nontemporal_store(xv, (f32x4*)((char*)xo + 4u * ERN_EOFF(g, bj, 0)));
;                   sq0 += (xv.x * xv.x + xv.y * xv.y) + (xv.z * xv.z + xv.w * xv.w);
;                   const f32x4 hv = xv * gsn[bj]; hw[bj][0].x = cvt_pk_bf16(hv.x, hv.y); hw[bj][0].y = cvt_pk_bf16(hv.z, hv.w); }
;                 { const f32x4 xv = xb[g & 1][bj][1] + gv[bj] * a1; __builtin_nontemporal_store(xv, (f32x4*)((char*)xo + 4u * ERN_EOFF(g, bj, 1)));
;                   sq1 += (xv.x * xv.x + xv.y * xv.y) + (xv.z * xv.z + xv.w * xv.w);
;                   const f32x4 hv = xv * gsn[bj]; hw[bj][1].x = cvt_pk_bf16(hv.x, hv.y); hw[bj][1].y = cvt_pk_bf16(hv.z, hv.w); }
;             }
;             if (!NOH && !PLAIN) {
; #pragma unroll
;                 for (int rh = 0; rh < 2; ++rh) { u32x2 rv; rv.x = __shfl_xor(hw[1][rh].x, 8); rv.y = __shfl_xor(hw[1][rh].y, 8);
;                     const unsigned e0 = ERN_EOFF(g, 0, rh);
;                     const unsigned ee = odd ? (e0 - DM + 32) : e0, eo2 = odd ? e0 : (e0 + DM + 32);
;                     *(u32x2*)((char*)ho + 2u * ee) = odd ? rv : hw[0][rh];
;                     *(u32x2*)((char*)ho + 2u * eo2) = odd ? hw[0][rh] : rv; }
.LBB0_1949:
	s_or_b64 exec, exec, s[22:23]
	v_lshl_add_u64 v[134:135], s[20:21], 0, v[154:155]
	v_add_u32_e32 v98, 0x60000, v205
	v_add_u32_e32 v154, 0x70000, v205
	v_add_u32_e32 v130, 0x60080, v205
	global_load_dwordx4 v[106:109], v154, s[20:21]
	global_load_dwordx4 v[102:105], v130, s[20:21]
	v_add_u32_e32 v132, 0x70080, v205
	global_load_dwordx4 v[110:113], v98, s[20:21]
	s_waitcnt lgkmcnt(0)
	global_load_dwordx4 v[98:101], v132, s[20:21]
	v_add_u32_e32 v250, 0x120000, v249
	global_load_dword v251, v250, s[20:21]
	ds_write_b128 v200, v[94:97]
	ds_write_b128 v200, v[90:93] offset:64
	ds_read_b128 v[90:93], v201
	ds_read_b128 v[94:97], v201 offset:1152
	v_mov_b32_e32 v187, v155
	v_mov_b32_e32 v189, v155
	s_waitcnt vmcnt(11) lgkmcnt(1)
	v_pk_fma_f32 v[92:93], v[176:177], v[92:93], v[128:129]
	v_add_u32_e32 v128, 0x10000, v202
	v_pk_fma_f32 v[90:91], v[180:181], v[90:91], v[126:127]
	v_lshlrev_b32_e32 v126, 2, v128
	s_waitcnt lgkmcnt(0)
	v_pk_fma_f32 v[94:95], v[180:181], v[94:95], v[122:123]
	global_store_dwordx4 v126, v[90:93], s[20:21] nt
	v_pk_mul_f32 v[126:127], v[178:179], v[90:91]
	v_pk_fma_f32 v[96:97], v[176:177], v[96:97], v[124:125]
	v_pk_mul_f32 v[122:123], v[178:179], v[94:95]
	v_pk_mul_f32 v[136:137], v[174:175], v[92:93]
	v_cvt_pk_bf16_f32 v126, v126, v127
	v_pk_mul_f32 v[124:125], v[174:175], v[96:97]
	v_cvt_pk_bf16_f32 v127, v136, v137
	global_store_dwordx4 v[134:135], v[94:97], off nt
	v_cvt_pk_bf16_f32 v122, v122, v123
	v_cvt_pk_bf16_f32 v123, v124, v125
	ds_write_b128 v200, v[86:89]
	ds_write_b128 v200, v[82:85] offset:64
	ds_read_b128 v[82:85], v201
	ds_read_b128 v[86:89], v201 offset:1152
	v_lshl_add_u64 v[124:125], s[20:21], 0, v[186:187]
	v_lshl_add_u64 v[134:135], s[20:21], 0, v[188:189]
	s_waitcnt lgkmcnt(1)
	v_pk_fma_f32 v[82:83], v[168:169], v[82:83], v[118:119]
	v_pk_fma_f32 v[84:85], v[166:167], v[84:85], v[120:121]
	v_pk_mul_f32 v[120:121], v[172:173], v[82:83]
	global_store_dwordx4 v[124:125], v[82:85], off nt
	v_pk_mul_f32 v[118:119], v[170:171], v[84:85]
	v_cvt_pk_bf16_f32 v120, v120, v121
	s_waitcnt vmcnt(13) lgkmcnt(0)
	v_pk_fma_f32 v[86:87], v[168:169], v[86:87], v[114:115]
	v_cvt_pk_bf16_f32 v121, v118, v119
	ds_bpermute_b32 v114, v203, v120
	ds_bpermute_b32 v115, v203, v121
	v_pk_fma_f32 v[88:89], v[166:167], v[88:89], v[116:117]
	v_pk_mul_f32 v[116:117], v[172:173], v[86:87]
	v_pk_mul_f32 v[118:119], v[170:171], v[88:89]
	global_store_dwordx4 v[134:135], v[86:89], off nt
	v_cvt_pk_bf16_f32 v116, v116, v117
	v_cvt_pk_bf16_f32 v117, v118, v119
	v_lshlrev_b32_e32 v118, 1, v128
	s_and_saveexec_b64 s[22:23], s[40:41]
	s_xor_b64 s[22:23], exec, s[22:23]
	s_cbranch_execz .LBB0_1951
	v_lshlrev_b32_e32 v118, 1, v128
	v_add_u32_e32 v119, 0xfffff040, v118
	s_waitcnt lgkmcnt(0)
	global_store_dwordx2 v119, v[114:115], s[18:19]

; #define LAS __attribute__((address_space(3)))
; __device__ __forceinline__ unsigned cvt_pk_bf16(float lo, float hi) { unsigned r; asm volatile("v_cvt_pk_bf16_f32 %0, %1, %2" : "=v"(r) : "v"(lo), "v"(hi)); return r; }
; #define ERN_EOFF(q, m) (eb + (unsigned)((((q) & 1) * HALF + (m) * 16) * DM + ERN_COL((q) >> 1)))
; #define ERN_LOADX(q) do { _Pragma("unroll") for (int m = 0; m < 4; ++m) xb[(q) & 1][m] = *(const f32x4*)((const char*)xi + 4u * ERN_EOFF(q, m)); } while (0)
;     __device__ __forceinline__ void operator()(const f32x4 (&acc)[2][2][4][2], const Unit& u, int wr, int wc, int fr, int fq) const {
;     ...
;         for (int g = 0; g < 8; ++g) { const int ai = g >> 2, m = g & 3;
;             if (g + 1 < 8) ERN_LOADX(g + 1);
;             float sq0 = 0.f, sq1 = 0.f; u32x2 hw[2][2];
; #pragma unroll
;             for (int bj = 0; bj < 2; ++bj) {
;                 *(LAS f32x4*)(st + wr_off) = acc[ai][bj][m][0]; *(LAS f32x4*)(st + wr_off + 64) = acc[ai][bj][m][1];
;                 const f32x4 a0 = *(const LAS f32x4*)(st + rd_off), a1 = *(const LAS f32x4*)(st + rd_off + 8 * 144);
;                 { const f32x4 xv = xb[g & 1][bj][0] + gv[bj] * a0; __builtin_nontemporal_store(xv, (f32x4*)((char*)xo + 4u * ERN_EOFF(g, bj, 0)));
;                   sq0 += (xv.x * xv.x + xv.y * xv.y) + (xv.z * xv.z + xv.w * xv.w);
;                   const f32x4 hv = xv * gsn[bj]; hw[bj][0].x = cvt_pk_bf16(hv.x, hv.y); hw[bj][0].y = cvt_pk_bf16(hv.z, hv.w); }
;                 { const f32x4 xv = xb[g & 1][bj][1] + gv[bj] * a1; __builtin_nontemporal_store(xv, (f32x4*)((char*)xo + 4u * ERN_EOFF(g, bj, 1)));
;                   sq1 += (xv.x * xv.x + xv.y * xv.y) + (xv.z * xv.z + xv.w * xv.w);
;                   const f32x4 hv = xv * gsn[bj]; hw[bj][1].x = cvt_pk_bf16(hv.x, hv.y); hw[bj][1].y = cvt_pk_bf16(hv.z, hv.w); }
;             }
;             if (!NOH && !PLAIN) {
; #pragma unroll
;                 for (int rh = 0; rh < 2; ++rh) { u32x2 rv; rv.x = __shfl_xor(hw[1][rh].x, 8); rv.y = __shfl_xor(hw[1][rh].y, 8);
;                     const unsigned e0 = ERN_EOFF(g, 0, rh);
;                     const unsigned ee = odd ? (e0 - DM + 32) : e0, eo2 = odd ? e0 : (e0 + DM + 32);
;                     *(u32x2*)((char*)ho + 2u * ee) = odd ? rv : hw[0][rh];
;                     *(u32x2*)((char*)ho + 2u * eo2) = odd ? hw[0][rh] : rv; }
.LBB0_1959:
	s_or_b64 exec, exec, s[22:23]
	v_lshl_add_u64 v[116:117], s[20:21], 0, v[154:155]
	v_add_u32_e32 v82, 0x100000, v205
	s_waitcnt lgkmcnt(1)
	v_add_u32_e32 v83, 0x110000, v205
	v_add_u32_e32 v154, 0x100080, v205
	global_load_dwordx4 v[94:97], v82, s[20:21]
	global_load_dwordx4 v[90:93], v83, s[20:21]
	v_add_u32_e32 v114, 0x110080, v205
	global_load_dwordx4 v[86:89], v154, s[20:21]
	s_waitcnt lgkmcnt(0)
	global_load_dwordx4 v[82:85], v114, s[20:21]
	v_add_u32_e32 v250, 0x140000, v249
	global_load_dword v251, v250, s[20:21]
	ds_write_b128 v200, v[78:81]
	ds_write_b128 v200, v[74:77] offset:64
	ds_read_b128 v[74:77], v201
	ds_read_b128 v[78:81], v201 offset:1152
	v_mov_b32_e32 v131, v155
	v_mov_b32_e32 v133, v155
	s_waitcnt vmcnt(11) lgkmcnt(1)
	v_pk_fma_f32 v[76:77], v[176:177], v[76:77], v[112:113]
	v_add_u32_e32 v112, 0x18000, v202
	v_pk_fma_f32 v[74:75], v[180:181], v[74:75], v[110:111]
	v_lshlrev_b32_e32 v110, 2, v112
	s_waitcnt lgkmcnt(0)
	v_pk_fma_f32 v[78:79], v[180:181], v[78:79], v[106:107]
	global_store_dwordx4 v110, v[74:77], s[20:21] nt
	v_pk_mul_f32 v[110:111], v[178:179], v[74:75]
	v_pk_fma_f32 v[80:81], v[176:177], v[80:81], v[108:109]
	v_pk_mul_f32 v[106:107], v[178:179], v[78:79]
	v_pk_mul_f32 v[118:119], v[174:175], v[76:77]
	v_cvt_pk_bf16_f32 v110, v110, v111
	v_pk_mul_f32 v[108:109], v[174:175], v[80:81]
	v_cvt_pk_bf16_f32 v111, v118, v119
	global_store_dwordx4 v[116:117], v[78:81], off nt
	v_cvt_pk_bf16_f32 v106, v106, v107
	v_cvt_pk_bf16_f32 v107, v108, v109
	ds_write_b128 v200, v[70:73]
	ds_write_b128 v200, v[66:69] offset:64
	ds_read_b128 v[66:69], v201
	ds_read_b128 v[70:73], v201 offset:1152
	v_lshl_add_u64 v[108:109], s[20:21], 0, v[130:131]
	v_lshl_add_u64 v[116:117], s[20:21], 0, v[132:133]
	s_waitcnt lgkmcnt(1)
	v_pk_fma_f32 v[66:67], v[168:169], v[66:67], v[102:103]
	v_pk_fma_f32 v[68:69], v[166:167], v[68:69], v[104:105]
	v_pk_mul_f32 v[104:105], v[172:173], v[66:67]
	global_store_dwordx4 v[108:109], v[66:69], off nt
	v_pk_mul_f32 v[102:103], v[170:171], v[68:69]
	v_cvt_pk_bf16_f32 v104, v104, v105
	s_waitcnt vmcnt(13) lgkmcnt(0)
	v_pk_fma_f32 v[70:71], v[168:169], v[70:71], v[98:99]
	v_cvt_pk_bf16_f32 v105, v102, v103
	ds_bpermute_b32 v98, v203, v104
	ds_bpermute_b32 v99, v203, v105
	v_pk_fma_f32 v[72:73], v[166:167], v[72:73], v[100:101]
	v_pk_mul_f32 v[100:101], v[172:173], v[70:71]
	v_pk_mul_f32 v[102:103], v[170:171], v[72:73]
	global_store_dwordx4 v[116:117], v[70:73], off nt
	v_cvt_pk_bf16_f32 v100, v100, v101
	v_cvt_pk_bf16_f32 v101, v102, v103
	v_lshlrev_b32_e32 v102, 1, v112
	s_and_saveexec_b64 s[22:23], s[40:41]
	s_xor_b64 s[22:23], exec, s[22:23]
	s_cbranch_execz .LBB0_1961
	v_lshlrev_b32_e32 v102, 1, v112
	v_add_u32_e32 v103, 0xfffff040, v102
	s_waitcnt lgkmcnt(0)
	global_store_dwordx2 v103, v[98:99], s[18:19]

; #define LAS __attribute__((address_space(3)))
; __device__ __forceinline__ unsigned cvt_pk_bf16(float lo, float hi) { unsigned r; asm volatile("v_cvt_pk_bf16_f32 %0, %1, %2" : "=v"(r) : "v"(lo), "v"(hi)); return r; }
; #define ERN_EOFF(q, m) (eb + (unsigned)((((q) & 1) * HALF + (m) * 16) * DM + ERN_COL((q) >> 1)))
; #define ERN_LOADX(q) do { _Pragma("unroll") for (int m = 0; m < 4; ++m) xb[(q) & 1][m] = *(const f32x4*)((const char*)xi + 4u * ERN_EOFF(q, m)); } while (0)
;     __device__ __forceinline__ void operator()(const f32x4 (&acc)[2][2][4][2], const Unit& u, int wr, int wc, int fr, int fq) const {
;     ...
;         for (int g = 0; g < 8; ++g) { const int ai = g >> 2, m = g & 3;
;             if (g + 1 < 8) ERN_LOADX(g + 1);
;             float sq0 = 0.f, sq1 = 0.f; u32x2 hw[2][2];
; #pragma unroll
;             for (int bj = 0; bj < 2; ++bj) {
;                 *(LAS f32x4*)(st + wr_off) = acc[ai][bj][m][0]; *(LAS f32x4*)(st + wr_off + 64) = acc[ai][bj][m][1];
;                 const f32x4 a0 = *(const LAS f32x4*)(st + rd_off), a1 = *(const LAS f32x4*)(st + rd_off + 8 * 144);
;                 { const f32x4 xv = xb[g & 1][bj][0] + gv[bj] * a0; __builtin_nontemporal_store(xv, (f32x4*)((char*)xo + 4u * ERN_EOFF(g, bj, 0)));
;                   sq0 += (xv.x * xv.x + xv.y * xv.y) + (xv.z * xv.z + xv.w * xv.w);
;                   const f32x4 hv = xv * gsn[bj]; hw[bj][0].x = cvt_pk_bf16(hv.x, hv.y); hw[bj][0].y = cvt_pk_bf16(hv.z, hv.w); }
;                 { const f32x4 xv = xb[g & 1][bj][1] + gv[bj] * a1; __builtin_nontemporal_store(xv, (f32x4*)((char*)xo + 4u * ERN_EOFF(g, bj, 1)));
;                   sq1 += (xv.x * xv.x + xv.y * xv.y) + (xv.z * xv.z + xv.w * xv.w);
;                   const f32x4 hv = xv * gsn[bj]; hw[bj][1].x = cvt_pk_bf16(hv.x, hv.y); hw[bj][1].y = cvt_pk_bf16(hv.z, hv.w); }
;             }
;             if (!NOH && !PLAIN) {
; #pragma unroll
;                 for (int rh = 0; rh < 2; ++rh) { u32x2 rv; rv.x = __shfl_xor(hw[1][rh].x, 8); rv.y = __shfl_xor(hw[1][rh].y, 8);
;                     const unsigned e0 = ERN_EOFF(g, 0, rh);
;                     const unsigned ee = odd ? (e0 - DM + 32) : e0, eo2 = odd ? e0 : (e0 + DM + 32);
;                     *(u32x2*)((char*)ho + 2u * ee) = odd ? rv : hw[0][rh];
;                     *(u32x2*)((char*)ho + 2u * eo2) = odd ? hw[0][rh] : rv; }
.LBB0_1969:
	s_or_b64 exec, exec, s[22:23]
	v_lshl_add_u64 v[104:105], s[20:21], 0, v[154:155]
	v_add_u32_e32 v154, 0x120000, v205
	v_add_u32_e32 v100, 0x120080, v205
	v_add_u32_e32 v102, 0x130000, v205
	global_load_dwordx4 v[78:81], v154, s[20:21]
	global_load_dwordx4 v[74:77], v102, s[20:21]
	v_add_u32_e32 v98, 0x130080, v205
	global_load_dwordx4 v[70:73], v100, s[20:21]
	s_waitcnt lgkmcnt(0)
	global_load_dwordx4 v[66:69], v98, s[20:21]
	v_add_u32_e32 v250, 0x160000, v249
	global_load_dword v251, v250, s[20:21]
	ds_write_b128 v200, v[62:65]
	ds_write_b128 v200, v[58:61] offset:64
	ds_read_b128 v[58:61], v201
	ds_read_b128 v[62:65], v201 offset:1152
	v_mov_b32_e32 v115, v155
	s_waitcnt vmcnt(13) lgkmcnt(1)
	v_pk_fma_f32 v[60:61], v[176:177], v[60:61], v[96:97]
	v_add_u32_e32 v96, 0x40000, v202
	v_pk_fma_f32 v[58:59], v[180:181], v[58:59], v[94:95]
	v_lshlrev_b32_e32 v94, 2, v96
	s_waitcnt vmcnt(12) lgkmcnt(0)
	v_pk_fma_f32 v[64:65], v[176:177], v[64:65], v[92:93]
	v_add_u32_e32 v92, 0x44000, v202
	global_store_dwordx4 v94, v[58:61], s[20:21] nt
	v_pk_mul_f32 v[94:95], v[178:179], v[58:59]
	v_pk_fma_f32 v[62:63], v[180:181], v[62:63], v[90:91]
	v_lshlrev_b32_e32 v90, 2, v92
	v_pk_mul_f32 v[106:107], v[174:175], v[60:61]
	v_cvt_pk_bf16_f32 v94, v94, v95
	s_nop 0
	v_cvt_pk_bf16_f32 v95, v106, v107
	global_store_dwordx4 v90, v[62:65], s[20:21] nt
	v_pk_mul_f32 v[90:91], v[178:179], v[62:63]
	v_pk_mul_f32 v[106:107], v[174:175], v[64:65]
	v_cvt_pk_bf16_f32 v90, v90, v91
	s_nop 0
	v_cvt_pk_bf16_f32 v91, v106, v107
	ds_write_b128 v200, v[54:57]
	ds_write_b128 v200, v[50:53] offset:64
	ds_read_b128 v[50:53], v201
	ds_read_b128 v[54:57], v201 offset:1152
	v_lshl_add_u64 v[106:107], s[20:21], 0, v[114:115]
	s_waitcnt vmcnt(13) lgkmcnt(1)
	v_pk_fma_f32 v[50:51], v[168:169], v[50:51], v[86:87]
	v_pk_fma_f32 v[52:53], v[166:167], v[52:53], v[88:89]
	v_pk_mul_f32 v[88:89], v[172:173], v[50:51]
	global_store_dwordx4 v[104:105], v[50:53], off nt
	v_pk_mul_f32 v[86:87], v[170:171], v[52:53]
	v_cvt_pk_bf16_f32 v88, v88, v89
	s_waitcnt vmcnt(13) lgkmcnt(0)
	v_pk_fma_f32 v[54:55], v[168:169], v[54:55], v[82:83]
	v_cvt_pk_bf16_f32 v89, v86, v87
	ds_bpermute_b32 v82, v203, v88
	ds_bpermute_b32 v83, v203, v89
	v_pk_fma_f32 v[56:57], v[166:167], v[56:57], v[84:85]
	v_pk_mul_f32 v[84:85], v[172:173], v[54:55]
	v_pk_mul_f32 v[86:87], v[170:171], v[56:57]
	global_store_dwordx4 v[106:107], v[54:57], off nt
	v_cvt_pk_bf16_f32 v84, v84, v85
	v_cvt_pk_bf16_f32 v85, v86, v87
	v_lshlrev_b32_e32 v86, 1, v96
	s_and_saveexec_b64 s[22:23], s[40:41]
	s_xor_b64 s[22:23], exec, s[22:23]
	s_cbranch_execz .LBB0_1971
	v_lshlrev_b32_e32 v86, 1, v96
	v_add_u32_e32 v87, 0xfffff040, v86
	s_waitcnt lgkmcnt(0)
	global_store_dwordx2 v87, v[82:83], s[18:19]

; #define LAS __attribute__((address_space(3)))
;     __device__ __forceinline__ void operator()(const f32x4 (&acc)[2][2][4][2], const Unit& u, int wr, int wc, int fr, int fq) const {
;         const int s = u.pm >> 5, lane = fq * 16 + fr, rr = lane >> 3, pc = lane & 7;
;         const float* __restrict__ xi = xin + (size_t)u.pm * BM * DM; float* __restrict__ xo = xout + (size_t)u.pm * BM * DM; bf16_t* __restrict__ ho = Hn + (size_t)u.pm * BM * DM;
;         LAS unsigned char* st = lds_epi + (wr * 4 + wc) * 2304;
;         LAS float* sst = (LAS float*)(lds_epi + 18432 + (wr * 4 + wc) * 512);
;         const int colr = u.pn * BM + wc * 64 + 4 * pc;
;         const unsigned eb = (unsigned)((wr * 64 + rr) * DM + colr);
;         f32x4 gv[2], gsn[2];
; #pragma unroll
;         for (int bj = 0; bj < 2; ++bj) { gv[bj] = *(const f32x4*)(gate + (size_t)s * MODW + colr + bj * 32) * (0.5f * GS2);
;             if (!PLAIN) gsn[bj] = *(const f32x4*)(gnext + colr + bj * 32) * (*(const f32x4*)(scnext + (size_t)s * MODW + colr + bj * 32) + 1.0f); else gsn[bj] = gv[bj]; }
;         const unsigned wr_off = (unsigned)(fr * 144 + 16 * fq), rd_off = (unsigned)(rr * 144 + pc * 16);
;         const bool odd = (rr & 1) != 0;
;         f32x4 xb[2][2][2];
;     ...
;         ERN_LOADX(0);
; #pragma unroll
;         for (int g = 0; g < 8; ++g) { const int ai = g >> 2, m = g & 3;
;             if (g + 1 < 8) ERN_LOADX(g + 1);
;             float sq0 = 0.f, sq1 = 0.f; u32x2 hw[2][2];
; #pragma unroll
;             for (int bj = 0; bj < 2; ++bj) {
;                 *(LAS f32x4*)(st + wr_off) = acc[ai][bj][m][0]; *(LAS f32x4*)(st + wr_off + 64) = acc[ai][bj][m][1];
;                 const f32x4 a0 = *(const LAS f32x4*)(st + rd_off), a1 = *(const LAS f32x4*)(st + rd_off + 8 * 144);
;                 { const f32x4 xv = xb[g & 1][bj][0] + gv[bj] * a0; __builtin_nontemporal_store(xv, (f32x4*)((char*)xo + 4u * ERN_EOFF(g, bj, 0)));
;                   sq0 += (xv.x * xv.x + xv.y * xv.y) + (xv.z * xv.z + xv.w * xv.w);
;                   const f32x4 hv = xv * gsn[bj]; hw[bj][0].x = cvt_pk_bf16(hv.x, hv.y); hw[bj][0].y = cvt_pk_bf16(hv.z, hv.w); }
;                 { const f32x4 xv = xb[g & 1][bj][1] + gv[bj] * a1; __builtin_nontemporal_store(xv, (f32x4*)((char*)xo + 4u * ERN_EOFF(g, bj, 1)));
;                   sq1 += (xv.x * xv.x + xv.y * xv.y) + (xv.z * xv.z + xv.w * xv.w);
.LBB0_2769:
	s_ashr_i32 s13, s2, 5
	s_ashr_i32 s3, s2, 31
	v_lshl_or_b32 v50, s20, 8, v192
	s_mul_hi_i32 s15, s13, 0x12000
	s_mul_i32 s13, s13, 0x12000
	s_add_u32 s20, s44, s13
	v_ashrrev_i32_e32 v51, 31, v50
	s_addc_u32 s21, s45, s15
	v_lshlrev_b64 v[52:53], 2, v[50:51]
	v_lshl_add_u64 v[138:139], s[20:21], 0, v[52:53]
	s_add_u32 s20, s46, s13
	s_addc_u32 s21, s47, s15
	v_lshl_add_u64 v[140:141], s[6:7], 0, v[52:53]
	v_lshl_add_u64 v[52:53], s[20:21], 0, v[52:53]
	s_lshl_b64 s[20:21], s[2:3], 21
	s_add_u32 s22, s90, s20
	v_add_u32_e32 v202, v50, v193
	s_addc_u32 s23, s91, s21
	v_lshlrev_b32_e32 v205, 2, v202
	global_load_dwordx4 v[54:57], v[138:139], off
	global_load_dwordx4 v[174:177], v[140:141], off
	global_load_dwordx4 v[178:181], v[52:53], off
	global_load_dwordx4 v[206:209], v[52:53], off offset:128
	global_load_dwordx4 v[186:189], v205, s[22:23]
	v_add_u32_e32 v50, 0x10000, v205
	global_load_dwordx4 v[210:213], v50, s[22:23]
	global_load_dwordx4 v[214:217], v[140:141], off offset:128
	s_nop 0
	global_load_dwordx4 v[50:53], v[138:139], off offset:128
	global_load_dwordx4 v[218:221], v205, s[22:23] offset:128
	v_add_u32_e32 v204, 0x10080, v205
	global_load_dwordx4 v[222:225], v204, s[22:23]
	v_add_u32_e32 v138, 0x20000, v205
	v_add_u32_e32 v162, 0x30000, v205
	v_add_u32_e32 v184, 0x20080, v205
	v_add_u32_e32 v182, 0x30080, v205
	global_load_dwordx4 v[150:153], v138, s[22:23]
	global_load_dwordx4 v[146:149], v162, s[22:23]
	global_load_dwordx4 v[142:145], v184, s[22:23]
	s_nop 0
	global_load_dwordx4 v[138:141], v182, s[22:23]
	ds_write_b128 v200, v[134:137]
	ds_write_b128 v200, v[130:133] offset:64
	v_and_b32_e32 v135, 64, v199
	ds_read_b128 v[130:133], v201
	ds_read_b128 v[226:229], v201 offset:1152
	v_xor_b32_e32 v134, 8, v199
	v_add_u32_e32 v183, 64, v135
	v_cmp_lt_i32_e32 vcc, v134, v183
	v_add_u32_e32 v185, 0x4000, v202
	v_lshlrev_b32_e32 v230, 2, v185
	v_cndmask_b32_e32 v134, v199, v134, vcc
	v_lshlrev_b32_e32 v203, 2, v134
	s_lshl_b64 s[20:21], s[2:3], 20
	s_add_u32 s20, s93, s20
	s_addc_u32 s21, s92, s21
	v_mbcnt_lo_u32_b32 v250, -1, 0
	v_mbcnt_hi_u32_b32 v250, -1, v250
	v_and_b32_e32 v249, 15, v250
	v_lshrrev_b32_e32 v251, 3, v250
	v_sub_u32_e32 v249, v249, v251
	v_lshlrev_b32_e32 v249, 13, v249
	v_bfe_u32 v251, v250, 4, 1
	v_lshl_add_u32 v249, v251, 7, v249
	v_and_b32_e32 v251, 7, v250
	v_lshlrev_b32_e32 v251, 4, v251
	v_sub_u32_e32 v249, v249, v251
	v_add_u32_e32 v249, v249, v205
	v_add_u32_e32 v250, 0x40000, v249
	global_load_dword v251, v250, s[22:23]
	v_add_u32_e32 v250, 0x60000, v249
	global_load_dword v251, v250, s[22:23]
	s_waitcnt vmcnt(2)
	v_pk_add_f32 v[134:135], v[180:181], 1.0 op_sel_hi:[1,0]
	v_pk_add_f32 v[136:137], v[178:179], 1.0 op_sel_hi:[1,0]
	v_pk_mul_f32 v[178:179], v[176:177], v[134:135]
	v_pk_mul_f32 v[180:181], v[174:175], v[136:137]
	s_waitcnt lgkmcnt(1)
	v_pk_fma_f32 v[134:135], v[54:55], v[130:131], v[186:187]
	s_waitcnt lgkmcnt(0)
	v_pk_fma_f32 v[130:131], v[54:55], v[226:227], v[210:211]
	v_pk_fma_f32 v[136:137], v[56:57], v[132:133], v[188:189]
	v_pk_fma_f32 v[132:133], v[56:57], v[228:229], v[212:213]
	v_pk_mul_f32 v[186:187], v[180:181], v[130:131]
	v_pk_add_f32 v[190:191], v[208:209], 1.0 op_sel_hi:[1,0]
	global_store_dwordx4 v205, v[134:137], s[22:23] nt
	v_pk_mul_f32 v[174:175], v[178:179], v[136:137]
	v_pk_mul_f32 v[176:177], v[180:181], v[134:135]
	v_pk_mul_f32 v[208:209], v[178:179], v[132:133]
	v_cvt_pk_bf16_f32 v188, v176, v177
	v_cvt_pk_bf16_f32 v189, v174, v175
	global_store_dwordx4 v230, v[130:133], s[22:23] nt
	v_cvt_pk_bf16_f32 v186, v186, v187
	v_cvt_pk_bf16_f32 v187, v208, v209
	ds_write_b128 v200, v[126:129]
	ds_write_b128 v200, v[122:125] offset:64
	ds_read_b128 v[122:125], v201
	v_pk_add_f32 v[126:127], v[206:207], 1.0 op_sel_hi:[1,0]
	ds_read_b128 v[206:209], v201 offset:1152
	v_pk_mul_f32 v[174:175], v[216:217], v[190:191]
	v_pk_mul_f32 v[176:177], v[214:215], v[126:127]
	s_waitcnt lgkmcnt(1)
	v_pk_fma_f32 v[128:129], v[52:53], v[124:125], v[220:221]
	v_pk_fma_f32 v[126:127], v[50:51], v[122:123], v[218:219]
	s_waitcnt lgkmcnt(0)
	v_pk_fma_f32 v[122:123], v[50:51], v[206:207], v[222:223]
	v_pk_mul_f32 v[190:191], v[174:175], v[128:129]
	v_pk_mul_f32 v[206:207], v[176:177], v[126:127]
	global_store_dwordx4 v205, v[126:129], s[22:23] offset:128 nt
	v_cvt_pk_bf16_f32 v206, v206, v207
	v_cvt_pk_bf16_f32 v191, v190, v191
	ds_bpermute_b32 v190, v203, v206
	ds_bpermute_b32 v191, v203, v191
	v_pk_fma_f32 v[124:125], v[52:53], v[208:209], v[224:225]
	v_pk_mul_f32 v[206:207], v[176:177], v[122:123]
	global_store_dwordx4 v204, v[122:125], s[22:23] nt
	v_cvt_pk_bf16_f32 v204, v206, v207
	v_lshlrev_b32_e32 v207, 1, v202
	v_pk_mul_f32 v[208:209], v[174:175], v[124:125]
	s_nop 0
	v_cvt_pk_bf16_f32 v206, v208, v209
	s_and_saveexec_b64 s[24:25], s[38:39]
	s_xor_b64 s[24:25], exec, s[24:25]
	s_cbranch_execz .LBB0_2771
	v_lshlrev_b32_e32 v207, 1, v202
	v_add_u32_e32 v208, 0xfffff040, v207
	s_waitcnt lgkmcnt(0)
	global_store_dwordx2 v208, v[190:191], s[20:21]

; #define LAS __attribute__((address_space(3)))
; __device__ __forceinline__ unsigned cvt_pk_bf16(float lo, float hi) { unsigned r; asm volatile("v_cvt_pk_bf16_f32 %0, %1, %2" : "=v"(r) : "v"(lo), "v"(hi)); return r; }
; #define ERN_EOFF(q, m) (eb + (unsigned)((((q) & 1) * HALF + (m) * 16) * DM + ERN_COL((q) >> 1)))
; #define ERN_LOADX(q) do { _Pragma("unroll") for (int m = 0; m < 4; ++m) xb[(q) & 1][m] = *(const f32x4*)((const char*)xi + 4u * ERN_EOFF(q, m)); } while (0)
;     __device__ __forceinline__ void operator()(const f32x4 (&acc)[2][2][4][2], const Unit& u, int wr, int wc, int fr, int fq) const {
;     ...
;         for (int g = 0; g < 8; ++g) { const int ai = g >> 2, m = g & 3;
;             if (g + 1 < 8) ERN_LOADX(g + 1);
;             float sq0 = 0.f, sq1 = 0.f; u32x2 hw[2][2];
; #pragma unroll
;             for (int bj = 0; bj < 2; ++bj) {
;                 *(LAS f32x4*)(st + wr_off) = acc[ai][bj][m][0]; *(LAS f32x4*)(st + wr_off + 64) = acc[ai][bj][m][1];
;                 const f32x4 a0 = *(const LAS f32x4*)(st + rd_off), a1 = *(const LAS f32x4*)(st + rd_off + 8 * 144);
;                 { const f32x4 xv = xb[g & 1][bj][0] + gv[bj] * a0; __builtin_nontemporal_store(xv, (f32x4*)((char*)xo + 4u * ERN_EOFF(g, bj, 0)));
;                   sq0 += (xv.x * xv.x + xv.y * xv.y) + (xv.z * xv.z + xv.w * xv.w);
;                   const f32x4 hv = xv * gsn[bj]; hw[bj][0].x = cvt_pk_bf16(hv.x, hv.y); hw[bj][0].y = cvt_pk_bf16(hv.z, hv.w); }
;                 { const f32x4 xv = xb[g & 1][bj][1] + gv[bj] * a1; __builtin_nontemporal_store(xv, (f32x4*)((char*)xo + 4u * ERN_EOFF(g, bj, 1)));
;                   sq1 += (xv.x * xv.x + xv.y * xv.y) + (xv.z * xv.z + xv.w * xv.w);
;                   const f32x4 hv = xv * gsn[bj]; hw[bj][1].x = cvt_pk_bf16(hv.x, hv.y); hw[bj][1].y = cvt_pk_bf16(hv.z, hv.w); }
;             }
;             if (!NOH && !PLAIN) {
; #pragma unroll
;                 for (int rh = 0; rh < 2; ++rh) { u32x2 rv; rv.x = __shfl_xor(hw[1][rh].x, 8); rv.y = __shfl_xor(hw[1][rh].y, 8);
;                     const unsigned e0 = ERN_EOFF(g, 0, rh);
;                     const unsigned ee = odd ? (e0 - DM + 32) : e0, eo2 = odd ? e0 : (e0 + DM + 32);
;                     *(u32x2*)((char*)ho + 2u * ee) = odd ? rv : hw[0][rh];
;                     *(u32x2*)((char*)ho + 2u * eo2) = odd ? hw[0][rh] : rv; }
.LBB0_2779:
	s_or_b64 exec, exec, s[24:25]
	v_lshl_add_u64 v[206:207], s[22:23], 0, v[162:163]
	v_add_u32_e32 v122, 0x40000, v205
	v_add_u32_e32 v162, 0x50000, v205
	v_add_u32_e32 v186, 0x40080, v205
	global_load_dwordx4 v[130:133], v162, s[22:23]
	global_load_dwordx4 v[126:129], v186, s[22:23]
	v_add_u32_e32 v188, 0x50080, v205
	global_load_dwordx4 v[134:137], v122, s[22:23]
	s_waitcnt lgkmcnt(0)
	global_load_dwordx4 v[122:125], v188, s[22:23]
	v_add_u32_e32 v250, 0x100000, v249
	global_load_dword v251, v250, s[22:23]
	ds_write_b128 v200, v[118:121]
	ds_write_b128 v200, v[114:117] offset:64
	ds_read_b128 v[114:117], v201
	ds_read_b128 v[118:121], v201 offset:1152
	v_mov_b32_e32 v185, v163
	v_mov_b32_e32 v183, v163
	v_lshl_add_u64 v[182:183], s[22:23], 0, v[182:183]
	s_waitcnt lgkmcnt(1)
	v_pk_fma_f32 v[116:117], v[56:57], v[116:117], v[152:153]
	v_add_u32_e32 v152, 0x8000, v202
	v_pk_fma_f32 v[114:115], v[54:55], v[114:115], v[150:151]
	v_lshlrev_b32_e32 v150, 2, v152
	s_waitcnt lgkmcnt(0)
	v_pk_fma_f32 v[118:119], v[54:55], v[118:119], v[146:147]
	global_store_dwordx4 v150, v[114:117], s[22:23] nt
	v_pk_mul_f32 v[150:151], v[180:181], v[114:115]
	v_pk_fma_f32 v[120:121], v[56:57], v[120:121], v[148:149]
	v_pk_mul_f32 v[146:147], v[180:181], v[118:119]
	v_pk_mul_f32 v[208:209], v[178:179], v[116:117]
	v_cvt_pk_bf16_f32 v150, v150, v151
	v_pk_mul_f32 v[148:149], v[178:179], v[120:121]
	v_cvt_pk_bf16_f32 v151, v208, v209
	global_store_dwordx4 v[206:207], v[118:121], off nt
	v_cvt_pk_bf16_f32 v146, v146, v147
	v_cvt_pk_bf16_f32 v147, v148, v149
	ds_write_b128 v200, v[110:113]
	ds_write_b128 v200, v[106:109] offset:64
	ds_read_b128 v[106:109], v201
	ds_read_b128 v[110:113], v201 offset:1152
	v_lshl_add_u64 v[148:149], s[22:23], 0, v[184:185]
	s_waitcnt lgkmcnt(1)
	v_pk_fma_f32 v[106:107], v[50:51], v[106:107], v[142:143]
	v_pk_fma_f32 v[108:109], v[52:53], v[108:109], v[144:145]
	v_pk_mul_f32 v[144:145], v[176:177], v[106:107]
	global_store_dwordx4 v[148:149], v[106:109], off nt
	v_pk_mul_f32 v[142:143], v[174:175], v[108:109]
	v_cvt_pk_bf16_f32 v144, v144, v145
	s_waitcnt lgkmcnt(0)
	v_pk_fma_f32 v[110:111], v[50:51], v[110:111], v[138:139]
	v_cvt_pk_bf16_f32 v145, v142, v143
	ds_bpermute_b32 v138, v203, v144
	ds_bpermute_b32 v139, v203, v145
	v_pk_fma_f32 v[112:113], v[52:53], v[112:113], v[140:141]
	v_pk_mul_f32 v[140:141], v[176:177], v[110:111]
	v_pk_mul_f32 v[142:143], v[174:175], v[112:113]
	global_store_dwordx4 v[182:183], v[110:113], off nt
	v_cvt_pk_bf16_f32 v140, v140, v141
	v_cvt_pk_bf16_f32 v141, v142, v143
	v_lshlrev_b32_e32 v142, 1, v152
	s_and_saveexec_b64 s[24:25], s[38:39]
	s_xor_b64 s[24:25], exec, s[24:25]
	s_cbranch_execz .LBB0_2781
	v_lshlrev_b32_e32 v142, 1, v152
	v_add_u32_e32 v143, 0xfffff040, v142
	s_waitcnt lgkmcnt(0)
	global_store_dwordx2 v143, v[138:139], s[20:21]

; #define LAS __attribute__((address_space(3)))
; __device__ __forceinline__ unsigned cvt_pk_bf16(float lo, float hi) { unsigned r; asm volatile("v_cvt_pk_bf16_f32 %0, %1, %2" : "=v"(r) : "v"(lo), "v"(hi)); return r; }
; #define ERN_EOFF(q, m) (eb + (unsigned)((((q) & 1) * HALF + (m) * 16) * DM + ERN_COL((q) >> 1)))
; #define ERN_LOADX(q) do { _Pragma("unroll") for (int m = 0; m < 4; ++m) xb[(q) & 1][m] = *(const f32x4*)((const char*)xi + 4u * ERN_EOFF(q, m)); } while (0)
;     __device__ __forceinline__ void operator()(const f32x4 (&acc)[2][2][4][2], const Unit& u, int wr, int wc, int fr, int fq) const {
;     ...
;         for (int g = 0; g < 8; ++g) { const int ai = g >> 2, m = g & 3;
;             if (g + 1 < 8) ERN_LOADX(g + 1);
;             float sq0 = 0.f, sq1 = 0.f; u32x2 hw[2][2];
; #pragma unroll
;             for (int bj = 0; bj < 2; ++bj) {
;                 *(LAS f32x4*)(st + wr_off) = acc[ai][bj][m][0]; *(LAS f32x4*)(st + wr_off + 64) = acc[ai][bj][m][1];
;                 const f32x4 a0 = *(const LAS f32x4*)(st + rd_off), a1 = *(const LAS f32x4*)(st + rd_off + 8 * 144);
;                 { const f32x4 xv = xb[g & 1][bj][0] + gv[bj] * a0; __builtin_nontemporal_store(xv, (f32x4*)((char*)xo + 4u * ERN_EOFF(g, bj, 0)));
;                   sq0 += (xv.x * xv.x + xv.y * xv.y) + (xv.z * xv.z + xv.w * xv.w);
;                   const f32x4 hv = xv * gsn[bj]; hw[bj][0].x = cvt_pk_bf16(hv.x, hv.y); hw[bj][0].y = cvt_pk_bf16(hv.z, hv.w); }
;                 { const f32x4 xv = xb[g & 1][bj][1] + gv[bj] * a1; __builtin_nontemporal_store(xv, (f32x4*)((char*)xo + 4u * ERN_EOFF(g, bj, 1)));
;                   sq1 += (xv.x * xv.x + xv.y * xv.y) + (xv.z * xv.z + xv.w * xv.w);
;                   const f32x4 hv = xv * gsn[bj]; hw[bj][1].x = cvt_pk_bf16(hv.x, hv.y); hw[bj][1].y = cvt_pk_bf16(hv.z, hv.w); }
;             }
;             if (!NOH && !PLAIN) {
; #pragma unroll
;                 for (int rh = 0; rh < 2; ++rh) { u32x2 rv; rv.x = __shfl_xor(hw[1][rh].x, 8); rv.y = __shfl_xor(hw[1][rh].y, 8);
;                     const unsigned e0 = ERN_EOFF(g, 0, rh);
;                     const unsigned ee = odd ? (e0 - DM + 32) : e0, eo2 = odd ? e0 : (e0 + DM + 32);
;                     *(u32x2*)((char*)ho + 2u * ee) = odd ? rv : hw[0][rh];
;                     *(u32x2*)((char*)ho + 2u * eo2) = odd ? hw[0][rh] : rv; }
.LBB0_2789:
	s_or_b64 exec, exec, s[24:25]
	v_lshl_add_u64 v[142:143], s[22:23], 0, v[162:163]
	v_add_u32_e32 v106, 0x60000, v205
	v_add_u32_e32 v162, 0x70000, v205
	v_add_u32_e32 v138, 0x60080, v205
	global_load_dwordx4 v[114:117], v162, s[22:23]
	global_load_dwordx4 v[110:113], v138, s[22:23]
	v_add_u32_e32 v140, 0x70080, v205
	global_load_dwordx4 v[118:121], v106, s[22:23]
	s_waitcnt lgkmcnt(0)
	global_load_dwordx4 v[106:109], v140, s[22:23]
	v_add_u32_e32 v250, 0x120000, v249
	global_load_dword v251, v250, s[22:23]
	ds_write_b128 v200, v[102:105]
	ds_write_b128 v200, v[98:101] offset:64
	ds_read_b128 v[98:101], v201
	ds_read_b128 v[102:105], v201 offset:1152
	v_mov_b32_e32 v187, v163
	v_mov_b32_e32 v189, v163
	s_waitcnt vmcnt(11) lgkmcnt(1)
	v_pk_fma_f32 v[100:101], v[56:57], v[100:101], v[136:137]
	v_add_u32_e32 v136, 0x10000, v202
	v_pk_fma_f32 v[98:99], v[54:55], v[98:99], v[134:135]
	v_lshlrev_b32_e32 v134, 2, v136
	s_waitcnt lgkmcnt(0)
	v_pk_fma_f32 v[102:103], v[54:55], v[102:103], v[130:131]
	global_store_dwordx4 v134, v[98:101], s[22:23] nt
	v_pk_mul_f32 v[134:135], v[180:181], v[98:99]
	v_pk_fma_f32 v[104:105], v[56:57], v[104:105], v[132:133]
	v_pk_mul_f32 v[130:131], v[180:181], v[102:103]
	v_pk_mul_f32 v[144:145], v[178:179], v[100:101]
	v_cvt_pk_bf16_f32 v134, v134, v135
	v_pk_mul_f32 v[132:133], v[178:179], v[104:105]
	v_cvt_pk_bf16_f32 v135, v144, v145
	global_store_dwordx4 v[142:143], v[102:105], off nt
	v_cvt_pk_bf16_f32 v130, v130, v131
	v_cvt_pk_bf16_f32 v131, v132, v133
	ds_write_b128 v200, v[94:97]
	ds_write_b128 v200, v[90:93] offset:64
	ds_read_b128 v[90:93], v201
	ds_read_b128 v[94:97], v201 offset:1152
	v_lshl_add_u64 v[132:133], s[22:23], 0, v[186:187]
	v_lshl_add_u64 v[142:143], s[22:23], 0, v[188:189]
	s_waitcnt lgkmcnt(1)
	v_pk_fma_f32 v[90:91], v[50:51], v[90:91], v[126:127]
	v_pk_fma_f32 v[92:93], v[52:53], v[92:93], v[128:129]
	v_pk_mul_f32 v[128:129], v[176:177], v[90:91]
	global_store_dwordx4 v[132:133], v[90:93], off nt
	v_pk_mul_f32 v[126:127], v[174:175], v[92:93]
	v_cvt_pk_bf16_f32 v128, v128, v129
	s_waitcnt vmcnt(13) lgkmcnt(0)
	v_pk_fma_f32 v[94:95], v[50:51], v[94:95], v[122:123]
	v_cvt_pk_bf16_f32 v129, v126, v127
	ds_bpermute_b32 v122, v203, v128
	ds_bpermute_b32 v123, v203, v129
	v_pk_fma_f32 v[96:97], v[52:53], v[96:97], v[124:125]
	v_pk_mul_f32 v[124:125], v[176:177], v[94:95]
	v_pk_mul_f32 v[126:127], v[174:175], v[96:97]
	global_store_dwordx4 v[142:143], v[94:97], off nt
	v_cvt_pk_bf16_f32 v124, v124, v125
	v_cvt_pk_bf16_f32 v125, v126, v127
	v_lshlrev_b32_e32 v126, 1, v136
	s_and_saveexec_b64 s[24:25], s[38:39]
	s_xor_b64 s[24:25], exec, s[24:25]
	s_cbranch_execz .LBB0_2791
	v_lshlrev_b32_e32 v126, 1, v136
	v_add_u32_e32 v127, 0xfffff040, v126
	s_waitcnt lgkmcnt(0)
	global_store_dwordx2 v127, v[122:123], s[20:21]

; #define LAS __attribute__((address_space(3)))
; __device__ __forceinline__ unsigned cvt_pk_bf16(float lo, float hi) { unsigned r; asm volatile("v_cvt_pk_bf16_f32 %0, %1, %2" : "=v"(r) : "v"(lo), "v"(hi)); return r; }
; #define ERN_EOFF(q, m) (eb + (unsigned)((((q) & 1) * HALF + (m) * 16) * DM + ERN_COL((q) >> 1)))
; #define ERN_LOADX(q) do { _Pragma("unroll") for (int m = 0; m < 4; ++m) xb[(q) & 1][m] = *(const f32x4*)((const char*)xi + 4u * ERN_EOFF(q, m)); } while (0)
;     __device__ __forceinline__ void operator()(const f32x4 (&acc)[2][2][4][2], const Unit& u, int wr, int wc, int fr, int fq) const {
;     ...
;         for (int g = 0; g < 8; ++g) { const int ai = g >> 2, m = g & 3;
;             if (g + 1 < 8) ERN_LOADX(g + 1);
;             float sq0 = 0.f, sq1 = 0.f; u32x2 hw[2][2];
; #pragma unroll
;             for (int bj = 0; bj < 2; ++bj) {
;                 *(LAS f32x4*)(st + wr_off) = acc[ai][bj][m][0]; *(LAS f32x4*)(st + wr_off + 64) = acc[ai][bj][m][1];
;                 const f32x4 a0 = *(const LAS f32x4*)(st + rd_off), a1 = *(const LAS f32x4*)(st + rd_off + 8 * 144);
;                 { const f32x4 xv = xb[g & 1][bj][0] + gv[bj] * a0; __builtin_nontemporal_store(xv, (f32x4*)((char*)xo + 4u * ERN_EOFF(g, bj, 0)));
;                   sq0 += (xv.x * xv.x + xv.y * xv.y) + (xv.z * xv.z + xv.w * xv.w);
;                   const f32x4 hv = xv * gsn[bj]; hw[bj][0].x = cvt_pk_bf16(hv.x, hv.y); hw[bj][0].y = cvt_pk_bf16(hv.z, hv.w); }
;                 { const f32x4 xv = xb[g & 1][bj][1] + gv[bj] * a1; __builtin_nontemporal_store(xv, (f32x4*)((char*)xo + 4u * ERN_EOFF(g, bj, 1)));
;                   sq1 += (xv.x * xv.x + xv.y * xv.y) + (xv.z * xv.z + xv.w * xv.w);
;                   const f32x4 hv = xv * gsn[bj]; hw[bj][1].x = cvt_pk_bf16(hv.x, hv.y); hw[bj][1].y = cvt_pk_bf16(hv.z, hv.w); }
;             }
;             if (!NOH && !PLAIN) {
; #pragma unroll
;                 for (int rh = 0; rh < 2; ++rh) { u32x2 rv; rv.x = __shfl_xor(hw[1][rh].x, 8); rv.y = __shfl_xor(hw[1][rh].y, 8);
;                     const unsigned e0 = ERN_EOFF(g, 0, rh);
;                     const unsigned ee = odd ? (e0 - DM + 32) : e0, eo2 = odd ? e0 : (e0 + DM + 32);
;                     *(u32x2*)((char*)ho + 2u * ee) = odd ? rv : hw[0][rh];
;                     *(u32x2*)((char*)ho + 2u * eo2) = odd ? hw[0][rh] : rv; }
.LBB0_2799:
	s_or_b64 exec, exec, s[24:25]
	v_lshl_add_u64 v[124:125], s[22:23], 0, v[162:163]
	v_add_u32_e32 v90, 0x100000, v205
	s_waitcnt lgkmcnt(1)
	v_add_u32_e32 v91, 0x110000, v205
	v_add_u32_e32 v162, 0x100080, v205
	global_load_dwordx4 v[102:105], v90, s[22:23]
	global_load_dwordx4 v[98:101], v91, s[22:23]
	v_add_u32_e32 v122, 0x110080, v205
	global_load_dwordx4 v[94:97], v162, s[22:23]
	s_waitcnt lgkmcnt(0)
	global_load_dwordx4 v[90:93], v122, s[22:23]
	v_add_u32_e32 v250, 0x140000, v249
	global_load_dword v251, v250, s[22:23]
	ds_write_b128 v200, v[86:89]
	ds_write_b128 v200, v[82:85] offset:64
	ds_read_b128 v[82:85], v201
	ds_read_b128 v[86:89], v201 offset:1152
	v_mov_b32_e32 v139, v163
	v_mov_b32_e32 v141, v163
	s_waitcnt vmcnt(11) lgkmcnt(1)
	v_pk_fma_f32 v[84:85], v[56:57], v[84:85], v[120:121]
	v_add_u32_e32 v120, 0x18000, v202
	v_pk_fma_f32 v[82:83], v[54:55], v[82:83], v[118:119]
	v_lshlrev_b32_e32 v118, 2, v120
	s_waitcnt lgkmcnt(0)
	v_pk_fma_f32 v[86:87], v[54:55], v[86:87], v[114:115]
	global_store_dwordx4 v118, v[82:85], s[22:23] nt
	v_pk_mul_f32 v[118:119], v[180:181], v[82:83]
	v_pk_fma_f32 v[88:89], v[56:57], v[88:89], v[116:117]
	v_pk_mul_f32 v[114:115], v[180:181], v[86:87]
	v_pk_mul_f32 v[126:127], v[178:179], v[84:85]
	v_cvt_pk_bf16_f32 v118, v118, v119
	v_pk_mul_f32 v[116:117], v[178:179], v[88:89]
	v_cvt_pk_bf16_f32 v119, v126, v127
	global_store_dwordx4 v[124:125], v[86:89], off nt
	v_cvt_pk_bf16_f32 v114, v114, v115
	v_cvt_pk_bf16_f32 v115, v116, v117
	ds_write_b128 v200, v[78:81]
	ds_write_b128 v200, v[74:77] offset:64
	ds_read_b128 v[74:77], v201
	ds_read_b128 v[78:81], v201 offset:1152
	v_lshl_add_u64 v[116:117], s[22:23], 0, v[138:139]
	v_lshl_add_u64 v[124:125], s[22:23], 0, v[140:141]
	s_waitcnt lgkmcnt(1)
	v_pk_fma_f32 v[74:75], v[50:51], v[74:75], v[110:111]
	v_pk_fma_f32 v[76:77], v[52:53], v[76:77], v[112:113]
	v_pk_mul_f32 v[112:113], v[176:177], v[74:75]
	global_store_dwordx4 v[116:117], v[74:77], off nt
	v_pk_mul_f32 v[110:111], v[174:175], v[76:77]
	v_cvt_pk_bf16_f32 v112, v112, v113
	s_waitcnt vmcnt(13) lgkmcnt(0)
	v_pk_fma_f32 v[78:79], v[50:51], v[78:79], v[106:107]
	v_cvt_pk_bf16_f32 v113, v110, v111
	ds_bpermute_b32 v106, v203, v112
	ds_bpermute_b32 v107, v203, v113
	v_pk_fma_f32 v[80:81], v[52:53], v[80:81], v[108:109]
	v_pk_mul_f32 v[108:109], v[176:177], v[78:79]
	v_pk_mul_f32 v[110:111], v[174:175], v[80:81]
	global_store_dwordx4 v[124:125], v[78:81], off nt
	v_cvt_pk_bf16_f32 v108, v108, v109
	v_cvt_pk_bf16_f32 v109, v110, v111
	v_lshlrev_b32_e32 v110, 1, v120
	s_and_saveexec_b64 s[24:25], s[38:39]
	s_xor_b64 s[24:25], exec, s[24:25]
	s_cbranch_execz .LBB0_2801
	v_lshlrev_b32_e32 v110, 1, v120
	v_add_u32_e32 v111, 0xfffff040, v110
	s_waitcnt lgkmcnt(0)
	global_store_dwordx2 v111, v[106:107], s[20:21]

; #define LAS __attribute__((address_space(3)))
; __device__ __forceinline__ unsigned cvt_pk_bf16(float lo, float hi) { unsigned r; asm volatile("v_cvt_pk_bf16_f32 %0, %1, %2" : "=v"(r) : "v"(lo), "v"(hi)); return r; }
; #define ERN_EOFF(q, m) (eb + (unsigned)((((q) & 1) * HALF + (m) * 16) * DM + ERN_COL((q) >> 1)))
; #define ERN_LOADX(q) do { _Pragma("unroll") for (int m = 0; m < 4; ++m) xb[(q) & 1][m] = *(const f32x4*)((const char*)xi + 4u * ERN_EOFF(q, m)); } while (0)
;     __device__ __forceinline__ void operator()(const f32x4 (&acc)[2][2][4][2], const Unit& u, int wr, int wc, int fr, int fq) const {
;     ...
;         for (int g = 0; g < 8; ++g) { const int ai = g >> 2, m = g & 3;
;             if (g + 1 < 8) ERN_LOADX(g + 1);
;             float sq0 = 0.f, sq1 = 0.f; u32x2 hw[2][2];
; #pragma unroll
;             for (int bj = 0; bj < 2; ++bj) {
;                 *(LAS f32x4*)(st + wr_off) = acc[ai][bj][m][0]; *(LAS f32x4*)(st + wr_off + 64) = acc[ai][bj][m][1];
;                 const f32x4 a0 = *(const LAS f32x4*)(st + rd_off), a1 = *(const LAS f32x4*)(st + rd_off + 8 * 144);
;                 { const f32x4 xv = xb[g & 1][bj][0] + gv[bj] * a0; __builtin_nontemporal_store(xv, (f32x4*)((char*)xo + 4u * ERN_EOFF(g, bj, 0)));
;                   sq0 += (xv.x * xv.x + xv.y * xv.y) + (xv.z * xv.z + xv.w * xv.w);
;                   const f32x4 hv = xv * gsn[bj]; hw[bj][0].x = cvt_pk_bf16(hv.x, hv.y); hw[bj][0].y = cvt_pk_bf16(hv.z, hv.w); }
;                 { const f32x4 xv = xb[g & 1][bj][1] + gv[bj] * a1; __builtin_nontemporal_store(xv, (f32x4*)((char*)xo + 4u * ERN_EOFF(g, bj, 1)));
;                   sq1 += (xv.x * xv.x + xv.y * xv.y) + (xv.z * xv.z + xv.w * xv.w);
;                   const f32x4 hv = xv * gsn[bj]; hw[bj][1].x = cvt_pk_bf16(hv.x, hv.y); hw[bj][1].y = cvt_pk_bf16(hv.z, hv.w); }
;             }
;             if (!NOH && !PLAIN) {
; #pragma unroll
;                 for (int rh = 0; rh < 2; ++rh) { u32x2 rv; rv.x = __shfl_xor(hw[1][rh].x, 8); rv.y = __shfl_xor(hw[1][rh].y, 8);
;                     const unsigned e0 = ERN_EOFF(g, 0, rh);
;                     const unsigned ee = odd ? (e0 - DM + 32) : e0, eo2 = odd ? e0 : (e0 + DM + 32);
;                     *(u32x2*)((char*)ho + 2u * ee) = odd ? rv : hw[0][rh];
;                     *(u32x2*)((char*)ho + 2u * eo2) = odd ? hw[0][rh] : rv; }
.LBB0_2809:
	s_or_b64 exec, exec, s[24:25]
	v_lshl_add_u64 v[112:113], s[22:23], 0, v[162:163]
	v_add_u32_e32 v162, 0x120000, v205
	v_add_u32_e32 v108, 0x120080, v205
	v_add_u32_e32 v110, 0x130000, v205
	global_load_dwordx4 v[86:89], v162, s[22:23]
	global_load_dwordx4 v[82:85], v110, s[22:23]
	v_add_u32_e32 v106, 0x130080, v205
	global_load_dwordx4 v[78:81], v108, s[22:23]
	s_waitcnt lgkmcnt(0)
	global_load_dwordx4 v[74:77], v106, s[22:23]
	v_add_u32_e32 v250, 0x160000, v249
	global_load_dword v251, v250, s[22:23]
	ds_write_b128 v200, v[70:73]
	ds_write_b128 v200, v[66:69] offset:64
	ds_read_b128 v[66:69], v201
	ds_read_b128 v[70:73], v201 offset:1152
	v_mov_b32_e32 v123, v163
	s_waitcnt vmcnt(13) lgkmcnt(1)
	v_pk_fma_f32 v[68:69], v[56:57], v[68:69], v[104:105]
	v_add_u32_e32 v104, 0x40000, v202
	v_pk_fma_f32 v[66:67], v[54:55], v[66:67], v[102:103]
	v_lshlrev_b32_e32 v102, 2, v104
	s_waitcnt vmcnt(12) lgkmcnt(0)
	v_pk_fma_f32 v[72:73], v[56:57], v[72:73], v[100:101]
	v_add_u32_e32 v100, 0x44000, v202
	global_store_dwordx4 v102, v[66:69], s[22:23] nt
	v_pk_mul_f32 v[102:103], v[180:181], v[66:67]
	v_pk_fma_f32 v[70:71], v[54:55], v[70:71], v[98:99]
	v_lshlrev_b32_e32 v98, 2, v100
	v_pk_mul_f32 v[114:115], v[178:179], v[68:69]
	v_cvt_pk_bf16_f32 v102, v102, v103
	s_nop 0
	v_cvt_pk_bf16_f32 v103, v114, v115
	global_store_dwordx4 v98, v[70:73], s[22:23] nt
	v_pk_mul_f32 v[98:99], v[180:181], v[70:71]
	v_pk_mul_f32 v[114:115], v[178:179], v[72:73]
	v_cvt_pk_bf16_f32 v98, v98, v99
	s_nop 0
	v_cvt_pk_bf16_f32 v99, v114, v115
	ds_write_b128 v200, v[62:65]
	ds_write_b128 v200, v[58:61] offset:64
	ds_read_b128 v[58:61], v201
	ds_read_b128 v[62:65], v201 offset:1152
	v_lshl_add_u64 v[114:115], s[22:23], 0, v[122:123]
	s_waitcnt vmcnt(13) lgkmcnt(1)
	v_pk_fma_f32 v[58:59], v[50:51], v[58:59], v[94:95]
	v_pk_fma_f32 v[60:61], v[52:53], v[60:61], v[96:97]
	v_pk_mul_f32 v[96:97], v[176:177], v[58:59]
	global_store_dwordx4 v[112:113], v[58:61], off nt
	v_pk_mul_f32 v[94:95], v[174:175], v[60:61]
	v_cvt_pk_bf16_f32 v96, v96, v97
	s_waitcnt vmcnt(13) lgkmcnt(0)
	v_pk_fma_f32 v[62:63], v[50:51], v[62:63], v[90:91]
	v_cvt_pk_bf16_f32 v97, v94, v95
	ds_bpermute_b32 v90, v203, v96
	ds_bpermute_b32 v91, v203, v97
	v_pk_fma_f32 v[64:65], v[52:53], v[64:65], v[92:93]
	v_pk_mul_f32 v[92:93], v[176:177], v[62:63]
	v_pk_mul_f32 v[94:95], v[174:175], v[64:65]
	global_store_dwordx4 v[114:115], v[62:65], off nt
	v_cvt_pk_bf16_f32 v92, v92, v93
	v_cvt_pk_bf16_f32 v93, v94, v95
	v_lshlrev_b32_e32 v94, 1, v104
	s_and_saveexec_b64 s[24:25], s[38:39]
	s_xor_b64 s[24:25], exec, s[24:25]
	s_cbranch_execz .LBB0_2811
	v_lshlrev_b32_e32 v94, 1, v104
	v_add_u32_e32 v95, 0xfffff040, v94
	s_waitcnt lgkmcnt(0)
	global_store_dwordx2 v95, v[90:91], s[20:21]
